# GEMM K loops: scalar/address instructions between the last MFMA of a compute segment and its closing barrier moved out (staging set-up behind the barrier, loop-carried updates + exit compare in front
# baseline (speedup 1.0000x reference)
.LBB0_177:
	s_ashr_i32 s45, s44, 31
	v_cmp_lt_i64_e32 vcc, s[46:47], v[144:145]
	s_lshl_b64 s[46:47], s[44:45], 19
	s_add_u32 s46, s68, s46
	s_addc_u32 s47, s69, s47
	s_and_b64 s[48:49], vcc, exec
	s_cselect_b32 s11, s47, s51
	s_cselect_b32 s13, s46, s50
	s_ashr_i32 s43, s42, 31
	s_lshl_b64 s[48:49], s[42:43], 19
	s_add_u32 s48, s26, s48
	s_addc_u32 s49, s27, s49
	s_and_b64 s[54:55], vcc, exec
	s_cselect_b32 s17, s49, s53
	s_cselect_b32 s43, s48, s52
	s_add_u32 s50, s50, 0x40080
	s_addc_u32 s51, s51, 0
	s_add_u32 s45, s52, 0x100
	s_addc_u32 s91, s53, 0
	s_mov_b32 s92, -2
	s_waitcnt lgkmcnt(0)
	ds_read_b128 v[148:151], v159
	ds_read_b128 v[152:155], v159 offset:1024
	ds_read_b128 v[164:167], v159 offset:2048
	ds_read_b128 v[168:171], v159 offset:3072
	s_add_u32 s52, s50, 0xfffc0080
	s_addc_u32 s53, s51, -1
	s_cmp_eq_u32 s92, 12
	s_cselect_b32 s55, s11, s53
	s_cselect_b32 s54, s13, s52
	s_cselect_b32 s53, s17, s91
	s_cselect_b32 s52, s43, s45
	v_lshl_add_u64 v[156:157], s[50:51], 0, v[140:141]
	s_add_i32 m0, s58, 0xc000
	ds_read_b128 v[172:175], v160
	ds_read_b128 v[176:179], v160 offset:1024
	ds_read_b128 v[180:183], v160 offset:2048
	ds_read_b128 v[184:187], v160 offset:3072
	ds_read_b128 v[188:191], v160 offset:4096
	ds_read_b128 v[196:199], v160 offset:5120
	ds_read_b128 v[200:203], v160 offset:6144
	ds_read_b128 v[204:207], v160 offset:7168
	global_load_lds_dwordx4 v[156:157], off
	v_lshl_add_u64 v[156:157], s[50:51], 0, v[142:143]
	s_add_i32 m0, s58, 0xe000
	s_nop 0
	global_load_lds_dwordx4 v[156:157], off
	s_waitcnt lgkmcnt(8)
	s_barrier
	s_waitcnt lgkmcnt(0)
	v_mfma_f32_16x16x32_bf16 v[124:127], v[148:151], v[172:175], 0
	v_mfma_f32_16x16x32_bf16 v[120:123], v[164:167], v[172:175], 0
	v_mfma_f32_16x16x32_bf16 v[108:111], v[148:151], v[180:183], 0
	v_mfma_f32_16x16x32_bf16 v[104:107], v[164:167], v[180:183], 0
	v_mfma_f32_16x16x32_bf16 v[92:95], v[148:151], v[188:191], 0
	v_mfma_f32_16x16x32_bf16 v[88:91], v[164:167], v[188:191], 0
	v_mfma_f32_16x16x32_bf16 v[76:79], v[148:151], v[200:203], 0
	v_mfma_f32_16x16x32_bf16 v[72:75], v[164:167], v[200:203], 0
	v_mfma_f32_16x16x32_bf16 v[124:127], v[152:155], v[176:179], v[124:127]
	v_mfma_f32_16x16x32_bf16 v[120:123], v[168:171], v[176:179], v[120:123]
	v_mfma_f32_16x16x32_bf16 v[108:111], v[152:155], v[184:187], v[108:111]
	v_mfma_f32_16x16x32_bf16 v[104:107], v[168:171], v[184:187], v[104:107]
	v_mfma_f32_16x16x32_bf16 v[92:95], v[152:155], v[196:199], v[92:95]
	v_mfma_f32_16x16x32_bf16 v[88:91], v[168:171], v[196:199], v[88:91]
	v_mfma_f32_16x16x32_bf16 v[76:79], v[152:155], v[204:207], v[76:79]
	v_mfma_f32_16x16x32_bf16 v[72:75], v[168:171], v[204:207], v[72:75]
	s_barrier
	s_add_i32 s93, s89, s57
	v_lshl_add_u64 v[156:157], s[52:53], 0, v[130:131]
	s_mov_b32 m0, s93
	ds_read_b128 v[208:211], v161
	ds_read_b128 v[212:215], v161 offset:1024
	ds_read_b128 v[216:219], v161 offset:2048
	ds_read_b128 v[220:223], v161 offset:3072
	global_load_lds_dwordx4 v[156:157], off
	v_lshl_add_u64 v[224:225], s[52:53], 0, v[134:135]
	s_add_i32 m0, s93, 0x2000
	s_nop 0
	global_load_lds_dwordx4 v[224:225], off
	s_barrier
	s_waitcnt lgkmcnt(0)
	v_mfma_f32_16x16x32_bf16 v[116:119], v[208:211], v[172:175], 0
	v_mfma_f32_16x16x32_bf16 v[112:115], v[216:219], v[172:175], 0
	v_mfma_f32_16x16x32_bf16 v[100:103], v[208:211], v[180:183], 0
	v_mfma_f32_16x16x32_bf16 v[96:99], v[216:219], v[180:183], 0
	v_mfma_f32_16x16x32_bf16 v[84:87], v[208:211], v[188:191], 0
	v_mfma_f32_16x16x32_bf16 v[80:83], v[216:219], v[188:191], 0
	v_mfma_f32_16x16x32_bf16 v[68:71], v[208:211], v[200:203], 0
	v_mfma_f32_16x16x32_bf16 v[64:67], v[216:219], v[200:203], 0
	v_mfma_f32_16x16x32_bf16 v[116:119], v[212:215], v[176:179], v[116:119]
	v_mfma_f32_16x16x32_bf16 v[112:115], v[220:223], v[176:179], v[112:115]
	v_mfma_f32_16x16x32_bf16 v[100:103], v[212:215], v[184:187], v[100:103]
	v_mfma_f32_16x16x32_bf16 v[96:99], v[220:223], v[184:187], v[96:99]
	v_mfma_f32_16x16x32_bf16 v[84:87], v[212:215], v[196:199], v[84:87]
	v_mfma_f32_16x16x32_bf16 v[80:83], v[220:223], v[196:199], v[80:83]
	v_mfma_f32_16x16x32_bf16 v[68:71], v[212:215], v[204:207], v[68:71]
	v_mfma_f32_16x16x32_bf16 v[64:67], v[220:223], v[204:207], v[64:67]
	s_barrier
	s_mov_b32 m0, s58
	v_lshl_add_u64 v[226:227], s[54:55], 0, v[128:129]
	ds_read_b128 v[172:175], v160 offset:16384
	ds_read_b128 v[176:179], v160 offset:17408
	ds_read_b128 v[180:183], v160 offset:18432
	ds_read_b128 v[184:187], v160 offset:19456
	ds_read_b128 v[188:191], v160 offset:20480
	ds_read_b128 v[196:199], v160 offset:21504
	ds_read_b128 v[200:203], v160 offset:22528
	ds_read_b128 v[204:207], v160 offset:23552
	global_load_lds_dwordx4 v[226:227], off
	v_lshl_add_u64 v[228:229], s[54:55], 0, v[132:133]
	s_mov_b32 m0, s59
	s_nop 0
	global_load_lds_dwordx4 v[228:229], off
	s_barrier
	s_waitcnt lgkmcnt(0)
	v_mfma_f32_16x16x32_bf16 v[60:63], v[148:151], v[172:175], 0
	v_mfma_f32_16x16x32_bf16 v[56:59], v[164:167], v[172:175], 0
	v_mfma_f32_16x16x32_bf16 v[44:47], v[148:151], v[180:183], 0
	v_mfma_f32_16x16x32_bf16 v[40:43], v[164:167], v[180:183], 0
	v_mfma_f32_16x16x32_bf16 v[28:31], v[148:151], v[188:191], 0
	v_mfma_f32_16x16x32_bf16 v[24:27], v[164:167], v[188:191], 0
	v_mfma_f32_16x16x32_bf16 v[12:15], v[148:151], v[200:203], 0
	v_mfma_f32_16x16x32_bf16 v[8:11], v[164:167], v[200:203], 0
	v_mfma_f32_16x16x32_bf16 v[60:63], v[152:155], v[176:179], v[60:63]
	v_mfma_f32_16x16x32_bf16 v[56:59], v[168:171], v[176:179], v[56:59]
	v_mfma_f32_16x16x32_bf16 v[44:47], v[152:155], v[184:187], v[44:47]
	v_mfma_f32_16x16x32_bf16 v[40:43], v[168:171], v[184:187], v[40:43]
	v_mfma_f32_16x16x32_bf16 v[28:31], v[152:155], v[196:199], v[28:31]
	v_mfma_f32_16x16x32_bf16 v[24:27], v[168:171], v[196:199], v[24:27]
	v_mfma_f32_16x16x32_bf16 v[12:15], v[152:155], v[204:207], v[12:15]
	v_mfma_f32_16x16x32_bf16 v[8:11], v[168:171], v[204:207], v[8:11]
	s_barrier
	s_add_u32 s94, s52, 0x10000
	s_addc_u32 s95, s53, 0
	s_add_i32 s93, s90, s57
	v_lshl_add_u64 v[148:149], s[94:95], 0, v[130:131]
	s_mov_b32 m0, s93
	s_nop 0
	global_load_lds_dwordx4 v[148:149], off
	v_lshl_add_u64 v[148:149], s[94:95], 0, v[134:135]
	s_add_i32 m0, s93, 0x2000
	s_nop 0
	global_load_lds_dwordx4 v[148:149], off
	s_cmp_eq_u32 s98, 0
	s_cbranch_scc1 .Lk1_w4n
	s_mov_b32 s98, 0
	s_waitcnt vmcnt(24)
	s_branch .Lk1_w4j

.Lk1_w4j:
	s_barrier
	v_mfma_f32_16x16x32_bf16 v[52:55], v[208:211], v[172:175], 0
	v_mfma_f32_16x16x32_bf16 v[48:51], v[216:219], v[172:175], 0
	v_mfma_f32_16x16x32_bf16 v[36:39], v[208:211], v[180:183], 0
	v_mfma_f32_16x16x32_bf16 v[32:35], v[216:219], v[180:183], 0
	v_mfma_f32_16x16x32_bf16 v[20:23], v[208:211], v[188:191], 0
	v_mfma_f32_16x16x32_bf16 v[16:19], v[216:219], v[188:191], 0
	v_mfma_f32_16x16x32_bf16 v[4:7], v[208:211], v[200:203], 0
	v_mfma_f32_16x16x32_bf16 v[0:3], v[216:219], v[200:203], 0
	v_mfma_f32_16x16x32_bf16 v[52:55], v[212:215], v[176:179], v[52:55]
	v_mfma_f32_16x16x32_bf16 v[48:51], v[220:223], v[176:179], v[48:51]
	v_mfma_f32_16x16x32_bf16 v[36:39], v[212:215], v[184:187], v[36:39]
	v_mfma_f32_16x16x32_bf16 v[32:35], v[220:223], v[184:187], v[32:35]
	v_mfma_f32_16x16x32_bf16 v[20:23], v[212:215], v[196:199], v[20:23]
	v_mfma_f32_16x16x32_bf16 v[16:19], v[220:223], v[196:199], v[16:19]
	v_mfma_f32_16x16x32_bf16 v[4:7], v[212:215], v[204:207], v[4:7]
	v_mfma_f32_16x16x32_bf16 v[0:3], v[220:223], v[204:207], v[0:3]
	s_barrier
	s_add_i32 s93, 0, 0x18000
	v_add_u32_e32 v136, s93, v158
	ds_read_b128 v[148:151], v136
	ds_read_b128 v[152:155], v136 offset:1024
	ds_read_b128 v[164:167], v136 offset:2048
	ds_read_b128 v[168:171], v136 offset:3072
	s_add_u32 s54, s54, 0x40000
	s_addc_u32 s55, s55, 0
	s_mov_b32 m0, s60
	v_lshl_add_u64 v[208:209], s[54:55], 0, v[128:129]
	ds_read_b128 v[172:175], v160 offset:32768
	ds_read_b128 v[176:179], v160 offset:33792
	ds_read_b128 v[180:183], v160 offset:34816
	ds_read_b128 v[184:187], v160 offset:35840
	ds_read_b128 v[188:191], v160 offset:36864
	ds_read_b128 v[196:199], v160 offset:37888
	ds_read_b128 v[200:203], v160 offset:38912
	ds_read_b128 v[204:207], v160 offset:39936
	global_load_lds_dwordx4 v[208:209], off
	v_lshl_add_u64 v[208:209], s[54:55], 0, v[132:133]
	s_mov_b32 m0, s61
	s_nop 0
	global_load_lds_dwordx4 v[208:209], off
	s_waitcnt lgkmcnt(8)
	s_barrier
	s_waitcnt lgkmcnt(0)
	v_mfma_f32_16x16x32_bf16 v[124:127], v[148:151], v[172:175], v[124:127]
	v_mfma_f32_16x16x32_bf16 v[120:123], v[164:167], v[172:175], v[120:123]
	v_mfma_f32_16x16x32_bf16 v[108:111], v[148:151], v[180:183], v[108:111]
	v_mfma_f32_16x16x32_bf16 v[104:107], v[164:167], v[180:183], v[104:107]
	v_mfma_f32_16x16x32_bf16 v[92:95], v[148:151], v[188:191], v[92:95]
	v_mfma_f32_16x16x32_bf16 v[88:91], v[164:167], v[188:191], v[88:91]
	v_mfma_f32_16x16x32_bf16 v[76:79], v[148:151], v[200:203], v[76:79]
	v_mfma_f32_16x16x32_bf16 v[72:75], v[164:167], v[200:203], v[72:75]
	v_mfma_f32_16x16x32_bf16 v[124:127], v[152:155], v[176:179], v[124:127]
	v_mfma_f32_16x16x32_bf16 v[120:123], v[168:171], v[176:179], v[120:123]
	v_mfma_f32_16x16x32_bf16 v[108:111], v[152:155], v[184:187], v[108:111]
	v_mfma_f32_16x16x32_bf16 v[104:107], v[168:171], v[184:187], v[104:107]
	v_mfma_f32_16x16x32_bf16 v[92:95], v[152:155], v[196:199], v[92:95]
	v_mfma_f32_16x16x32_bf16 v[88:91], v[168:171], v[196:199], v[88:91]
	v_mfma_f32_16x16x32_bf16 v[76:79], v[152:155], v[204:207], v[76:79]
	v_mfma_f32_16x16x32_bf16 v[72:75], v[168:171], v[204:207], v[72:75]
	s_barrier
	s_add_i32 s54, 0, 0x1c000
	s_add_i32 s55, s93, s57
	v_add_u32_e32 v136, s54, v158
	v_lshl_add_u64 v[156:157], v[156:157], 0, s[0:1]
	s_mov_b32 m0, s55
	ds_read_b128 v[208:211], v136
	ds_read_b128 v[212:215], v136 offset:1024
	ds_read_b128 v[216:219], v136 offset:2048
	ds_read_b128 v[220:223], v136 offset:3072
	global_load_lds_dwordx4 v[156:157], off
	v_lshl_add_u64 v[156:157], v[224:225], 0, s[0:1]
	s_add_i32 m0, s55, 0x2000
	s_nop 0
	global_load_lds_dwordx4 v[156:157], off
	s_barrier
	s_waitcnt lgkmcnt(0)
	v_mfma_f32_16x16x32_bf16 v[116:119], v[208:211], v[172:175], v[116:119]
	v_mfma_f32_16x16x32_bf16 v[112:115], v[216:219], v[172:175], v[112:115]
	v_mfma_f32_16x16x32_bf16 v[100:103], v[208:211], v[180:183], v[100:103]
	v_mfma_f32_16x16x32_bf16 v[96:99], v[216:219], v[180:183], v[96:99]
	v_mfma_f32_16x16x32_bf16 v[84:87], v[208:211], v[188:191], v[84:87]
	v_mfma_f32_16x16x32_bf16 v[80:83], v[216:219], v[188:191], v[80:83]
	v_mfma_f32_16x16x32_bf16 v[68:71], v[208:211], v[200:203], v[68:71]
	v_mfma_f32_16x16x32_bf16 v[64:67], v[216:219], v[200:203], v[64:67]
	v_mfma_f32_16x16x32_bf16 v[116:119], v[212:215], v[176:179], v[116:119]
	v_mfma_f32_16x16x32_bf16 v[112:115], v[220:223], v[176:179], v[112:115]
	v_mfma_f32_16x16x32_bf16 v[100:103], v[212:215], v[184:187], v[100:103]
	v_mfma_f32_16x16x32_bf16 v[96:99], v[220:223], v[184:187], v[96:99]
	v_mfma_f32_16x16x32_bf16 v[84:87], v[212:215], v[196:199], v[84:87]
	v_mfma_f32_16x16x32_bf16 v[80:83], v[220:223], v[196:199], v[80:83]
	v_mfma_f32_16x16x32_bf16 v[68:71], v[212:215], v[204:207], v[68:71]
	v_mfma_f32_16x16x32_bf16 v[64:67], v[220:223], v[204:207], v[64:67]
	s_mov_b32 m0, s65
	v_lshl_add_u64 v[156:157], v[226:227], 0, s[0:1]
	s_waitcnt vmcnt(10)
	s_barrier
	ds_read_b128 v[172:175], v160 offset:49152
	ds_read_b128 v[176:179], v160 offset:50176
	ds_read_b128 v[180:183], v160 offset:51200
	ds_read_b128 v[184:187], v160 offset:52224
	ds_read_b128 v[188:191], v160 offset:53248
	ds_read_b128 v[196:199], v160 offset:54272
	ds_read_b128 v[200:203], v160 offset:55296
	ds_read_b128 v[204:207], v160 offset:56320
	global_load_lds_dwordx4 v[156:157], off
	v_lshl_add_u64 v[156:157], v[228:229], 0, s[0:1]
	s_mov_b32 m0, s66
	s_nop 0
	global_load_lds_dwordx4 v[156:157], off
	s_barrier
	s_waitcnt lgkmcnt(0)
	v_mfma_f32_16x16x32_bf16 v[60:63], v[148:151], v[172:175], v[60:63]
	v_mfma_f32_16x16x32_bf16 v[56:59], v[164:167], v[172:175], v[56:59]
	v_mfma_f32_16x16x32_bf16 v[44:47], v[148:151], v[180:183], v[44:47]
	v_mfma_f32_16x16x32_bf16 v[40:43], v[164:167], v[180:183], v[40:43]
	v_mfma_f32_16x16x32_bf16 v[28:31], v[148:151], v[188:191], v[28:31]
	v_mfma_f32_16x16x32_bf16 v[24:27], v[164:167], v[188:191], v[24:27]
	v_mfma_f32_16x16x32_bf16 v[12:15], v[148:151], v[200:203], v[12:15]
	v_mfma_f32_16x16x32_bf16 v[8:11], v[164:167], v[200:203], v[8:11]
	v_mfma_f32_16x16x32_bf16 v[60:63], v[152:155], v[176:179], v[60:63]
	v_mfma_f32_16x16x32_bf16 v[56:59], v[168:171], v[176:179], v[56:59]
	v_mfma_f32_16x16x32_bf16 v[44:47], v[152:155], v[184:187], v[44:47]
	v_mfma_f32_16x16x32_bf16 v[40:43], v[168:171], v[184:187], v[40:43]
	v_mfma_f32_16x16x32_bf16 v[28:31], v[152:155], v[196:199], v[28:31]
	v_mfma_f32_16x16x32_bf16 v[24:27], v[168:171], v[196:199], v[24:27]
	v_mfma_f32_16x16x32_bf16 v[12:15], v[152:155], v[204:207], v[12:15]
	v_mfma_f32_16x16x32_bf16 v[8:11], v[168:171], v[204:207], v[8:11]
	s_barrier
	s_add_u32 s52, s52, 0x10080
	s_addc_u32 s53, s53, 0
	s_add_i32 s54, s54, s57
	v_lshl_add_u64 v[148:149], s[52:53], 0, v[130:131]
	s_mov_b32 m0, s54
	s_nop 0
	global_load_lds_dwordx4 v[148:149], off
	v_lshl_add_u64 v[148:149], s[52:53], 0, v[134:135]
	s_add_i32 m0, s54, 0x2000
	s_nop 0
	global_load_lds_dwordx4 v[148:149], off
	s_add_i32 s92, s92, 2
	s_add_u32 s50, s50, 0x100
	s_addc_u32 s51, s51, 0
	s_add_u32 s45, s45, 0x100
	s_addc_u32 s91, s91, 0
	s_cmp_gt_u32 s92, 13
	s_waitcnt vmcnt(6)
	s_barrier
	v_mfma_f32_16x16x32_bf16 v[52:55], v[208:211], v[172:175], v[52:55]
	v_mfma_f32_16x16x32_bf16 v[48:51], v[216:219], v[172:175], v[48:51]
	v_mfma_f32_16x16x32_bf16 v[36:39], v[208:211], v[180:183], v[36:39]
	v_mfma_f32_16x16x32_bf16 v[32:35], v[216:219], v[180:183], v[32:35]
	v_mfma_f32_16x16x32_bf16 v[20:23], v[208:211], v[188:191], v[20:23]
	v_mfma_f32_16x16x32_bf16 v[16:19], v[216:219], v[188:191], v[16:19]
	v_mfma_f32_16x16x32_bf16 v[4:7], v[208:211], v[200:203], v[4:7]
	v_mfma_f32_16x16x32_bf16 v[0:3], v[216:219], v[200:203], v[0:3]
	v_mfma_f32_16x16x32_bf16 v[52:55], v[212:215], v[176:179], v[52:55]
	v_mfma_f32_16x16x32_bf16 v[48:51], v[220:223], v[176:179], v[48:51]
	v_mfma_f32_16x16x32_bf16 v[36:39], v[212:215], v[184:187], v[36:39]
	v_mfma_f32_16x16x32_bf16 v[32:35], v[220:223], v[184:187], v[32:35]
	v_mfma_f32_16x16x32_bf16 v[20:23], v[212:215], v[196:199], v[20:23]
	v_mfma_f32_16x16x32_bf16 v[16:19], v[220:223], v[196:199], v[16:19]
	v_mfma_f32_16x16x32_bf16 v[4:7], v[212:215], v[204:207], v[4:7]
	v_mfma_f32_16x16x32_bf16 v[0:3], v[220:223], v[204:207], v[0:3]
	s_barrier
	s_cbranch_scc0 .LBB0_178
.LBB0_178:
	ds_read_b128 v[148:151], v159
	ds_read_b128 v[152:155], v159 offset:1024
	ds_read_b128 v[164:167], v159 offset:2048
	ds_read_b128 v[168:171], v159 offset:3072
	s_add_u32 s52, s50, 0xfffc0080
	s_addc_u32 s53, s51, -1
	s_cmp_eq_u32 s92, 12
	s_cselect_b32 s55, s11, s53
	s_cselect_b32 s54, s13, s52
	s_cselect_b32 s53, s17, s91
	s_cselect_b32 s52, s43, s45
	v_lshl_add_u64 v[156:157], s[50:51], 0, v[140:141]
	s_add_i32 m0, s58, 0xc000
	ds_read_b128 v[172:175], v160
	ds_read_b128 v[176:179], v160 offset:1024
	ds_read_b128 v[180:183], v160 offset:2048
	ds_read_b128 v[184:187], v160 offset:3072
	ds_read_b128 v[188:191], v160 offset:4096
	ds_read_b128 v[196:199], v160 offset:5120
	ds_read_b128 v[200:203], v160 offset:6144
	ds_read_b128 v[204:207], v160 offset:7168
	global_load_lds_dwordx4 v[156:157], off
	v_lshl_add_u64 v[156:157], s[50:51], 0, v[142:143]
	s_add_i32 m0, s58, 0xe000
	s_nop 0
	global_load_lds_dwordx4 v[156:157], off
	s_waitcnt lgkmcnt(8)
	s_barrier
	s_waitcnt lgkmcnt(0)
	v_mfma_f32_16x16x32_bf16 v[124:127], v[148:151], v[172:175], v[124:127]
	v_mfma_f32_16x16x32_bf16 v[120:123], v[164:167], v[172:175], v[120:123]
	v_mfma_f32_16x16x32_bf16 v[108:111], v[148:151], v[180:183], v[108:111]
	v_mfma_f32_16x16x32_bf16 v[104:107], v[164:167], v[180:183], v[104:107]
	v_mfma_f32_16x16x32_bf16 v[92:95], v[148:151], v[188:191], v[92:95]
	v_mfma_f32_16x16x32_bf16 v[88:91], v[164:167], v[188:191], v[88:91]
	v_mfma_f32_16x16x32_bf16 v[76:79], v[148:151], v[200:203], v[76:79]
	v_mfma_f32_16x16x32_bf16 v[72:75], v[164:167], v[200:203], v[72:75]
	v_mfma_f32_16x16x32_bf16 v[124:127], v[152:155], v[176:179], v[124:127]
	v_mfma_f32_16x16x32_bf16 v[120:123], v[168:171], v[176:179], v[120:123]
	v_mfma_f32_16x16x32_bf16 v[108:111], v[152:155], v[184:187], v[108:111]
	v_mfma_f32_16x16x32_bf16 v[104:107], v[168:171], v[184:187], v[104:107]
	v_mfma_f32_16x16x32_bf16 v[92:95], v[152:155], v[196:199], v[92:95]
	v_mfma_f32_16x16x32_bf16 v[88:91], v[168:171], v[196:199], v[88:91]
	v_mfma_f32_16x16x32_bf16 v[76:79], v[152:155], v[204:207], v[76:79]
	v_mfma_f32_16x16x32_bf16 v[72:75], v[168:171], v[204:207], v[72:75]
	s_barrier
	s_add_i32 s93, s89, s57
	v_lshl_add_u64 v[156:157], s[52:53], 0, v[130:131]
	s_mov_b32 m0, s93
	ds_read_b128 v[208:211], v161
	ds_read_b128 v[212:215], v161 offset:1024
	ds_read_b128 v[216:219], v161 offset:2048
	ds_read_b128 v[220:223], v161 offset:3072
	global_load_lds_dwordx4 v[156:157], off
	v_lshl_add_u64 v[224:225], s[52:53], 0, v[134:135]
	s_add_i32 m0, s93, 0x2000
	s_nop 0
	global_load_lds_dwordx4 v[224:225], off
	s_barrier
	s_waitcnt lgkmcnt(0)
	v_mfma_f32_16x16x32_bf16 v[116:119], v[208:211], v[172:175], v[116:119]
	v_mfma_f32_16x16x32_bf16 v[112:115], v[216:219], v[172:175], v[112:115]
	v_mfma_f32_16x16x32_bf16 v[100:103], v[208:211], v[180:183], v[100:103]
	v_mfma_f32_16x16x32_bf16 v[96:99], v[216:219], v[180:183], v[96:99]
	v_mfma_f32_16x16x32_bf16 v[84:87], v[208:211], v[188:191], v[84:87]
	v_mfma_f32_16x16x32_bf16 v[80:83], v[216:219], v[188:191], v[80:83]
	v_mfma_f32_16x16x32_bf16 v[68:71], v[208:211], v[200:203], v[68:71]
	v_mfma_f32_16x16x32_bf16 v[64:67], v[216:219], v[200:203], v[64:67]
	v_mfma_f32_16x16x32_bf16 v[116:119], v[212:215], v[176:179], v[116:119]
	v_mfma_f32_16x16x32_bf16 v[112:115], v[220:223], v[176:179], v[112:115]
	v_mfma_f32_16x16x32_bf16 v[100:103], v[212:215], v[184:187], v[100:103]
	v_mfma_f32_16x16x32_bf16 v[96:99], v[220:223], v[184:187], v[96:99]
	v_mfma_f32_16x16x32_bf16 v[84:87], v[212:215], v[196:199], v[84:87]
	v_mfma_f32_16x16x32_bf16 v[80:83], v[220:223], v[196:199], v[80:83]
	v_mfma_f32_16x16x32_bf16 v[68:71], v[212:215], v[204:207], v[68:71]
	v_mfma_f32_16x16x32_bf16 v[64:67], v[220:223], v[204:207], v[64:67]
	s_barrier
	s_mov_b32 m0, s58
	v_lshl_add_u64 v[226:227], s[54:55], 0, v[128:129]
	ds_read_b128 v[172:175], v160 offset:16384
	ds_read_b128 v[176:179], v160 offset:17408
	ds_read_b128 v[180:183], v160 offset:18432
	ds_read_b128 v[184:187], v160 offset:19456
	ds_read_b128 v[188:191], v160 offset:20480
	ds_read_b128 v[196:199], v160 offset:21504
	ds_read_b128 v[200:203], v160 offset:22528
	ds_read_b128 v[204:207], v160 offset:23552
	global_load_lds_dwordx4 v[226:227], off
	v_lshl_add_u64 v[228:229], s[54:55], 0, v[132:133]
	s_mov_b32 m0, s59
	s_nop 0
	global_load_lds_dwordx4 v[228:229], off
	s_barrier
	s_waitcnt lgkmcnt(0)
	v_mfma_f32_16x16x32_bf16 v[60:63], v[148:151], v[172:175], v[60:63]
	v_mfma_f32_16x16x32_bf16 v[56:59], v[164:167], v[172:175], v[56:59]
	v_mfma_f32_16x16x32_bf16 v[44:47], v[148:151], v[180:183], v[44:47]
	v_mfma_f32_16x16x32_bf16 v[40:43], v[164:167], v[180:183], v[40:43]
	v_mfma_f32_16x16x32_bf16 v[28:31], v[148:151], v[188:191], v[28:31]
	v_mfma_f32_16x16x32_bf16 v[24:27], v[164:167], v[188:191], v[24:27]
	v_mfma_f32_16x16x32_bf16 v[12:15], v[148:151], v[200:203], v[12:15]
	v_mfma_f32_16x16x32_bf16 v[8:11], v[164:167], v[200:203], v[8:11]
	v_mfma_f32_16x16x32_bf16 v[60:63], v[152:155], v[176:179], v[60:63]
	v_mfma_f32_16x16x32_bf16 v[56:59], v[168:171], v[176:179], v[56:59]
	v_mfma_f32_16x16x32_bf16 v[44:47], v[152:155], v[184:187], v[44:47]
	v_mfma_f32_16x16x32_bf16 v[40:43], v[168:171], v[184:187], v[40:43]
	v_mfma_f32_16x16x32_bf16 v[28:31], v[152:155], v[196:199], v[28:31]
	v_mfma_f32_16x16x32_bf16 v[24:27], v[168:171], v[196:199], v[24:27]
	v_mfma_f32_16x16x32_bf16 v[12:15], v[152:155], v[204:207], v[12:15]
	v_mfma_f32_16x16x32_bf16 v[8:11], v[168:171], v[204:207], v[8:11]
	s_barrier
	s_add_u32 s94, s52, 0x10000
	s_addc_u32 s95, s53, 0
	s_add_i32 s93, s90, s57
	v_lshl_add_u64 v[148:149], s[94:95], 0, v[130:131]
	s_mov_b32 m0, s93
	s_nop 0
	global_load_lds_dwordx4 v[148:149], off
	v_lshl_add_u64 v[148:149], s[94:95], 0, v[134:135]
	s_add_i32 m0, s93, 0x2000
	s_nop 0
	global_load_lds_dwordx4 v[148:149], off
	s_waitcnt vmcnt(6)
	s_barrier
	v_mfma_f32_16x16x32_bf16 v[52:55], v[208:211], v[172:175], v[52:55]
	v_mfma_f32_16x16x32_bf16 v[48:51], v[216:219], v[172:175], v[48:51]
	v_mfma_f32_16x16x32_bf16 v[36:39], v[208:211], v[180:183], v[36:39]
	v_mfma_f32_16x16x32_bf16 v[32:35], v[216:219], v[180:183], v[32:35]
	v_mfma_f32_16x16x32_bf16 v[20:23], v[208:211], v[188:191], v[20:23]
	v_mfma_f32_16x16x32_bf16 v[16:19], v[216:219], v[188:191], v[16:19]
	v_mfma_f32_16x16x32_bf16 v[4:7], v[208:211], v[200:203], v[4:7]
	v_mfma_f32_16x16x32_bf16 v[0:3], v[216:219], v[200:203], v[0:3]
	v_mfma_f32_16x16x32_bf16 v[52:55], v[212:215], v[176:179], v[52:55]
	v_mfma_f32_16x16x32_bf16 v[48:51], v[220:223], v[176:179], v[48:51]
	v_mfma_f32_16x16x32_bf16 v[36:39], v[212:215], v[184:187], v[36:39]
	v_mfma_f32_16x16x32_bf16 v[32:35], v[220:223], v[184:187], v[32:35]
	v_mfma_f32_16x16x32_bf16 v[20:23], v[212:215], v[196:199], v[20:23]
	v_mfma_f32_16x16x32_bf16 v[16:19], v[220:223], v[196:199], v[16:19]
	v_mfma_f32_16x16x32_bf16 v[4:7], v[212:215], v[204:207], v[4:7]
	v_mfma_f32_16x16x32_bf16 v[0:3], v[220:223], v[204:207], v[0:3]
	s_barrier
	s_add_i32 s93, 0, 0x18000
	v_add_u32_e32 v136, s93, v158
	ds_read_b128 v[148:151], v136
	ds_read_b128 v[152:155], v136 offset:1024
	ds_read_b128 v[164:167], v136 offset:2048
	ds_read_b128 v[168:171], v136 offset:3072
	s_add_u32 s54, s54, 0x40000
	s_addc_u32 s55, s55, 0
	s_mov_b32 m0, s60
	v_lshl_add_u64 v[208:209], s[54:55], 0, v[128:129]
	ds_read_b128 v[172:175], v160 offset:32768
	ds_read_b128 v[176:179], v160 offset:33792
	ds_read_b128 v[180:183], v160 offset:34816
	ds_read_b128 v[184:187], v160 offset:35840
	ds_read_b128 v[188:191], v160 offset:36864
	ds_read_b128 v[196:199], v160 offset:37888
	ds_read_b128 v[200:203], v160 offset:38912
	ds_read_b128 v[204:207], v160 offset:39936
	global_load_lds_dwordx4 v[208:209], off
	v_lshl_add_u64 v[208:209], s[54:55], 0, v[132:133]
	s_mov_b32 m0, s61
	s_nop 0
	global_load_lds_dwordx4 v[208:209], off
	s_waitcnt lgkmcnt(8)
	s_barrier
	s_waitcnt lgkmcnt(0)
	v_mfma_f32_16x16x32_bf16 v[124:127], v[148:151], v[172:175], v[124:127]
	v_mfma_f32_16x16x32_bf16 v[120:123], v[164:167], v[172:175], v[120:123]
	v_mfma_f32_16x16x32_bf16 v[108:111], v[148:151], v[180:183], v[108:111]
	v_mfma_f32_16x16x32_bf16 v[104:107], v[164:167], v[180:183], v[104:107]
	v_mfma_f32_16x16x32_bf16 v[92:95], v[148:151], v[188:191], v[92:95]
	v_mfma_f32_16x16x32_bf16 v[88:91], v[164:167], v[188:191], v[88:91]
	v_mfma_f32_16x16x32_bf16 v[76:79], v[148:151], v[200:203], v[76:79]
	v_mfma_f32_16x16x32_bf16 v[72:75], v[164:167], v[200:203], v[72:75]
	v_mfma_f32_16x16x32_bf16 v[124:127], v[152:155], v[176:179], v[124:127]
	v_mfma_f32_16x16x32_bf16 v[120:123], v[168:171], v[176:179], v[120:123]
	v_mfma_f32_16x16x32_bf16 v[108:111], v[152:155], v[184:187], v[108:111]
	v_mfma_f32_16x16x32_bf16 v[104:107], v[168:171], v[184:187], v[104:107]
	v_mfma_f32_16x16x32_bf16 v[92:95], v[152:155], v[196:199], v[92:95]
	v_mfma_f32_16x16x32_bf16 v[88:91], v[168:171], v[196:199], v[88:91]
	v_mfma_f32_16x16x32_bf16 v[76:79], v[152:155], v[204:207], v[76:79]
	v_mfma_f32_16x16x32_bf16 v[72:75], v[168:171], v[204:207], v[72:75]
	s_barrier
	s_add_i32 s54, 0, 0x1c000
	s_add_i32 s55, s93, s57
	v_add_u32_e32 v136, s54, v158
	v_lshl_add_u64 v[156:157], v[156:157], 0, s[0:1]
	s_mov_b32 m0, s55
	ds_read_b128 v[208:211], v136
	ds_read_b128 v[212:215], v136 offset:1024
	ds_read_b128 v[216:219], v136 offset:2048
	ds_read_b128 v[220:223], v136 offset:3072
	global_load_lds_dwordx4 v[156:157], off
	v_lshl_add_u64 v[156:157], v[224:225], 0, s[0:1]
	s_add_i32 m0, s55, 0x2000
	s_nop 0
	global_load_lds_dwordx4 v[156:157], off
	s_barrier
	s_waitcnt lgkmcnt(0)
	v_mfma_f32_16x16x32_bf16 v[116:119], v[208:211], v[172:175], v[116:119]
	v_mfma_f32_16x16x32_bf16 v[112:115], v[216:219], v[172:175], v[112:115]
	v_mfma_f32_16x16x32_bf16 v[100:103], v[208:211], v[180:183], v[100:103]
	v_mfma_f32_16x16x32_bf16 v[96:99], v[216:219], v[180:183], v[96:99]
	v_mfma_f32_16x16x32_bf16 v[84:87], v[208:211], v[188:191], v[84:87]
	v_mfma_f32_16x16x32_bf16 v[80:83], v[216:219], v[188:191], v[80:83]
	v_mfma_f32_16x16x32_bf16 v[68:71], v[208:211], v[200:203], v[68:71]
	v_mfma_f32_16x16x32_bf16 v[64:67], v[216:219], v[200:203], v[64:67]
	v_mfma_f32_16x16x32_bf16 v[116:119], v[212:215], v[176:179], v[116:119]
	v_mfma_f32_16x16x32_bf16 v[112:115], v[220:223], v[176:179], v[112:115]
	v_mfma_f32_16x16x32_bf16 v[100:103], v[212:215], v[184:187], v[100:103]
	v_mfma_f32_16x16x32_bf16 v[96:99], v[220:223], v[184:187], v[96:99]
	v_mfma_f32_16x16x32_bf16 v[84:87], v[212:215], v[196:199], v[84:87]
	v_mfma_f32_16x16x32_bf16 v[80:83], v[220:223], v[196:199], v[80:83]
	v_mfma_f32_16x16x32_bf16 v[68:71], v[212:215], v[204:207], v[68:71]
	v_mfma_f32_16x16x32_bf16 v[64:67], v[220:223], v[204:207], v[64:67]
	s_barrier
	s_mov_b32 m0, s65
	v_lshl_add_u64 v[156:157], v[226:227], 0, s[0:1]
	ds_read_b128 v[172:175], v160 offset:49152
	ds_read_b128 v[176:179], v160 offset:50176
	ds_read_b128 v[180:183], v160 offset:51200
	ds_read_b128 v[184:187], v160 offset:52224
	ds_read_b128 v[188:191], v160 offset:53248
	ds_read_b128 v[196:199], v160 offset:54272
	ds_read_b128 v[200:203], v160 offset:55296
	ds_read_b128 v[204:207], v160 offset:56320
	global_load_lds_dwordx4 v[156:157], off
	v_lshl_add_u64 v[156:157], v[228:229], 0, s[0:1]
	s_mov_b32 m0, s66
	s_nop 0
	global_load_lds_dwordx4 v[156:157], off
	s_barrier
	s_waitcnt lgkmcnt(0)
	v_mfma_f32_16x16x32_bf16 v[60:63], v[148:151], v[172:175], v[60:63]
	v_mfma_f32_16x16x32_bf16 v[56:59], v[164:167], v[172:175], v[56:59]
	v_mfma_f32_16x16x32_bf16 v[44:47], v[148:151], v[180:183], v[44:47]
	v_mfma_f32_16x16x32_bf16 v[40:43], v[164:167], v[180:183], v[40:43]
	v_mfma_f32_16x16x32_bf16 v[28:31], v[148:151], v[188:191], v[28:31]
	v_mfma_f32_16x16x32_bf16 v[24:27], v[164:167], v[188:191], v[24:27]
	v_mfma_f32_16x16x32_bf16 v[12:15], v[148:151], v[200:203], v[12:15]
	v_mfma_f32_16x16x32_bf16 v[8:11], v[164:167], v[200:203], v[8:11]
	v_mfma_f32_16x16x32_bf16 v[60:63], v[152:155], v[176:179], v[60:63]
	v_mfma_f32_16x16x32_bf16 v[56:59], v[168:171], v[176:179], v[56:59]
	v_mfma_f32_16x16x32_bf16 v[44:47], v[152:155], v[184:187], v[44:47]
	v_mfma_f32_16x16x32_bf16 v[40:43], v[168:171], v[184:187], v[40:43]
	v_mfma_f32_16x16x32_bf16 v[28:31], v[152:155], v[196:199], v[28:31]
	v_mfma_f32_16x16x32_bf16 v[24:27], v[168:171], v[196:199], v[24:27]
	v_mfma_f32_16x16x32_bf16 v[12:15], v[152:155], v[204:207], v[12:15]
	v_mfma_f32_16x16x32_bf16 v[8:11], v[168:171], v[204:207], v[8:11]
	s_barrier
	s_add_u32 s52, s52, 0x10080
	s_addc_u32 s53, s53, 0
	s_add_i32 s54, s54, s57
	v_lshl_add_u64 v[148:149], s[52:53], 0, v[130:131]
	s_mov_b32 m0, s54
	s_nop 0
	global_load_lds_dwordx4 v[148:149], off
	v_lshl_add_u64 v[148:149], s[52:53], 0, v[134:135]
	s_add_i32 m0, s54, 0x2000
	s_nop 0
	global_load_lds_dwordx4 v[148:149], off
	s_add_i32 s92, s92, 2
	s_add_u32 s50, s50, 0x100
	s_addc_u32 s51, s51, 0
	s_add_u32 s45, s45, 0x100
	s_addc_u32 s91, s91, 0
	s_cmp_gt_u32 s92, 13
	s_waitcnt vmcnt(6)
	s_barrier
	v_mfma_f32_16x16x32_bf16 v[52:55], v[208:211], v[172:175], v[52:55]
	v_mfma_f32_16x16x32_bf16 v[48:51], v[216:219], v[172:175], v[48:51]
	v_mfma_f32_16x16x32_bf16 v[36:39], v[208:211], v[180:183], v[36:39]
	v_mfma_f32_16x16x32_bf16 v[32:35], v[216:219], v[180:183], v[32:35]
	v_mfma_f32_16x16x32_bf16 v[20:23], v[208:211], v[188:191], v[20:23]
	v_mfma_f32_16x16x32_bf16 v[16:19], v[216:219], v[188:191], v[16:19]
	v_mfma_f32_16x16x32_bf16 v[4:7], v[208:211], v[200:203], v[4:7]
	v_mfma_f32_16x16x32_bf16 v[0:3], v[216:219], v[200:203], v[0:3]
	v_mfma_f32_16x16x32_bf16 v[52:55], v[212:215], v[176:179], v[52:55]
	v_mfma_f32_16x16x32_bf16 v[48:51], v[220:223], v[176:179], v[48:51]
	v_mfma_f32_16x16x32_bf16 v[36:39], v[212:215], v[184:187], v[36:39]
	v_mfma_f32_16x16x32_bf16 v[32:35], v[220:223], v[184:187], v[32:35]
	v_mfma_f32_16x16x32_bf16 v[20:23], v[212:215], v[196:199], v[20:23]
	v_mfma_f32_16x16x32_bf16 v[16:19], v[220:223], v[196:199], v[16:19]
	v_mfma_f32_16x16x32_bf16 v[4:7], v[212:215], v[204:207], v[4:7]
	v_mfma_f32_16x16x32_bf16 v[0:3], v[220:223], v[204:207], v[0:3]
	s_barrier
	s_cbranch_scc0 .LBB0_178
	v_lshl_add_u32 v148, s12, 8, v139
	v_and_b32_e32 v149, 24, v138
	s_lshl_b32 s11, s10, 8
	s_or_b32 s11, s11, s87
	s_cmp_gt_i32 s10, 11
	s_cbranch_scc1 .Le1_gates
	s_lshr_b32 s13, s10, 1
	s_lshl_b32 s50, s13, 25
	s_add_u32 s50, s20, s50
	s_addc_u32 s51, s21, 0
	s_bfe_u32 s17, s11, 0x30006
	v_ashrrev_i32_e32 v150, 8, v148
	v_and_or_b32 v150, v150, -8, s17
	v_mov_b32_e32 v151, 0
	v_lshlrev_b64 v[150:151], 18, v[150:151]
	v_lshlrev_b32_e32 v136, 7, v148
	v_and_b32_e32 v136, 0x3ff80, v136
	v_lshl_add_u32 v136, v149, 1, v136
	v_lshl_add_u64 v[150:151], v[150:151], 0, v[136:137]
	v_lshl_add_u64 v[150:151], v[150:151], 0, s[50:51]
	s_movk_i32 s11, 0x800
	s_movk_i32 s17, 0x2800
	s_branch .Le1_addr

.LBB0_342:
	ds_read_b128 v[146:149], v143
	ds_read_b128 v[150:153], v143 offset:1024
	ds_read_b128 v[154:157], v143 offset:2048
	ds_read_b128 v[158:161], v143 offset:3072
	s_add_u32 s46, s44, 0xfffc0080
	s_addc_u32 s47, s45, -1
	s_cmp_eq_u32 s67, 12
	s_cselect_b32 s49, s9, s47
	s_cselect_b32 s48, s63, s46
	s_cselect_b32 s47, s7, s66
	s_cselect_b32 s46, s64, s65
	v_lshl_add_u64 v[190:191], s[44:45], 0, v[136:137]
	s_add_i32 m0, s43, 0xc000
	ds_read_b128 v[162:165], v144
	ds_read_b128 v[166:169], v144 offset:1024
	ds_read_b128 v[170:173], v144 offset:2048
	ds_read_b128 v[174:177], v144 offset:3072
	ds_read_b128 v[178:181], v144 offset:4096
	ds_read_b128 v[182:185], v144 offset:5120
	ds_read_b128 v[186:189], v144 offset:6144
	ds_read_b128 v[196:199], v144 offset:7168
	global_load_lds_dwordx4 v[190:191], off
	v_lshl_add_u64 v[190:191], s[44:45], 0, v[138:139]
	s_add_i32 m0, s43, 0xe000
	s_nop 0
	global_load_lds_dwordx4 v[190:191], off
	s_waitcnt lgkmcnt(8)
	s_barrier
	s_waitcnt lgkmcnt(0)
	v_mfma_f32_16x16x32_bf16 v[124:127], v[146:149], v[162:165], v[124:127]
	v_mfma_f32_16x16x32_bf16 v[120:123], v[154:157], v[162:165], v[120:123]
	v_mfma_f32_16x16x32_bf16 v[108:111], v[146:149], v[170:173], v[108:111]
	v_mfma_f32_16x16x32_bf16 v[104:107], v[154:157], v[170:173], v[104:107]
	v_mfma_f32_16x16x32_bf16 v[92:95], v[146:149], v[178:181], v[92:95]
	v_mfma_f32_16x16x32_bf16 v[88:91], v[154:157], v[178:181], v[88:91]
	v_mfma_f32_16x16x32_bf16 v[76:79], v[146:149], v[186:189], v[76:79]
	v_mfma_f32_16x16x32_bf16 v[72:75], v[154:157], v[186:189], v[72:75]
	v_mfma_f32_16x16x32_bf16 v[124:127], v[150:153], v[166:169], v[124:127]
	v_mfma_f32_16x16x32_bf16 v[120:123], v[158:161], v[166:169], v[120:123]
	v_mfma_f32_16x16x32_bf16 v[108:111], v[150:153], v[174:177], v[108:111]
	v_mfma_f32_16x16x32_bf16 v[104:107], v[158:161], v[174:177], v[104:107]
	v_mfma_f32_16x16x32_bf16 v[92:95], v[150:153], v[182:185], v[92:95]
	v_mfma_f32_16x16x32_bf16 v[88:91], v[158:161], v[182:185], v[88:91]
	v_mfma_f32_16x16x32_bf16 v[76:79], v[150:153], v[196:199], v[76:79]
	v_mfma_f32_16x16x32_bf16 v[72:75], v[158:161], v[196:199], v[72:75]
	s_barrier
	s_add_i32 s84, s60, s50
	v_lshl_add_u64 v[190:191], s[46:47], 0, v[132:133]
	s_mov_b32 m0, s84
	ds_read_b128 v[200:203], v145
	ds_read_b128 v[204:207], v145 offset:1024
	ds_read_b128 v[208:211], v145 offset:2048
	ds_read_b128 v[212:215], v145 offset:3072
	global_load_lds_dwordx4 v[190:191], off
	v_lshl_add_u64 v[216:217], s[46:47], 0, v[128:129]
	s_add_i32 m0, s84, 0x2000
	s_nop 0
	global_load_lds_dwordx4 v[216:217], off
	s_barrier
	s_waitcnt lgkmcnt(0)
	v_mfma_f32_16x16x32_bf16 v[116:119], v[200:203], v[162:165], v[116:119]
	v_mfma_f32_16x16x32_bf16 v[112:115], v[208:211], v[162:165], v[112:115]
	v_mfma_f32_16x16x32_bf16 v[100:103], v[200:203], v[170:173], v[100:103]
	v_mfma_f32_16x16x32_bf16 v[96:99], v[208:211], v[170:173], v[96:99]
	v_mfma_f32_16x16x32_bf16 v[84:87], v[200:203], v[178:181], v[84:87]
	v_mfma_f32_16x16x32_bf16 v[80:83], v[208:211], v[178:181], v[80:83]
	v_mfma_f32_16x16x32_bf16 v[68:71], v[200:203], v[186:189], v[68:71]
	v_mfma_f32_16x16x32_bf16 v[64:67], v[208:211], v[186:189], v[64:67]
	v_mfma_f32_16x16x32_bf16 v[116:119], v[204:207], v[166:169], v[116:119]
	v_mfma_f32_16x16x32_bf16 v[112:115], v[212:215], v[166:169], v[112:115]
	v_mfma_f32_16x16x32_bf16 v[100:103], v[204:207], v[174:177], v[100:103]
	v_mfma_f32_16x16x32_bf16 v[96:99], v[212:215], v[174:177], v[96:99]
	v_mfma_f32_16x16x32_bf16 v[84:87], v[204:207], v[182:185], v[84:87]
	v_mfma_f32_16x16x32_bf16 v[80:83], v[212:215], v[182:185], v[80:83]
	v_mfma_f32_16x16x32_bf16 v[68:71], v[204:207], v[196:199], v[68:71]
	v_mfma_f32_16x16x32_bf16 v[64:67], v[212:215], v[196:199], v[64:67]
	s_barrier
	s_mov_b32 m0, s43
	v_lshl_add_u64 v[218:219], s[48:49], 0, v[134:135]
	ds_read_b128 v[162:165], v144 offset:16384
	ds_read_b128 v[166:169], v144 offset:17408
	ds_read_b128 v[170:173], v144 offset:18432
	ds_read_b128 v[174:177], v144 offset:19456
	ds_read_b128 v[178:181], v144 offset:20480
	ds_read_b128 v[182:185], v144 offset:21504
	ds_read_b128 v[186:189], v144 offset:22528
	ds_read_b128 v[196:199], v144 offset:23552
	global_load_lds_dwordx4 v[218:219], off
	v_lshl_add_u64 v[220:221], s[48:49], 0, v[130:131]
	s_mov_b32 m0, s52
	s_nop 0
	global_load_lds_dwordx4 v[220:221], off
	s_barrier
	s_waitcnt lgkmcnt(0)
	v_mfma_f32_16x16x32_bf16 v[60:63], v[146:149], v[162:165], v[60:63]
	v_mfma_f32_16x16x32_bf16 v[56:59], v[154:157], v[162:165], v[56:59]
	v_mfma_f32_16x16x32_bf16 v[44:47], v[146:149], v[170:173], v[44:47]
	v_mfma_f32_16x16x32_bf16 v[40:43], v[154:157], v[170:173], v[40:43]
	v_mfma_f32_16x16x32_bf16 v[28:31], v[146:149], v[178:181], v[28:31]
	v_mfma_f32_16x16x32_bf16 v[24:27], v[154:157], v[178:181], v[24:27]
	v_mfma_f32_16x16x32_bf16 v[12:15], v[146:149], v[186:189], v[12:15]
	v_mfma_f32_16x16x32_bf16 v[8:11], v[154:157], v[186:189], v[8:11]
	v_mfma_f32_16x16x32_bf16 v[60:63], v[150:153], v[166:169], v[60:63]
	v_mfma_f32_16x16x32_bf16 v[56:59], v[158:161], v[166:169], v[56:59]
	v_mfma_f32_16x16x32_bf16 v[44:47], v[150:153], v[174:177], v[44:47]
	v_mfma_f32_16x16x32_bf16 v[40:43], v[158:161], v[174:177], v[40:43]
	v_mfma_f32_16x16x32_bf16 v[28:31], v[150:153], v[182:185], v[28:31]
	v_mfma_f32_16x16x32_bf16 v[24:27], v[158:161], v[182:185], v[24:27]
	v_mfma_f32_16x16x32_bf16 v[12:15], v[150:153], v[196:199], v[12:15]
	v_mfma_f32_16x16x32_bf16 v[8:11], v[158:161], v[196:199], v[8:11]
	s_barrier
	s_add_u32 s84, s46, 0x10000
	s_addc_u32 s85, s47, 0
	s_add_i32 s89, s61, s50
	v_lshl_add_u64 v[146:147], s[84:85], 0, v[132:133]
	s_mov_b32 m0, s89
	s_nop 0
	global_load_lds_dwordx4 v[146:147], off
	v_lshl_add_u64 v[146:147], s[84:85], 0, v[128:129]
	s_add_i32 m0, s89, 0x2000
	s_nop 0
	global_load_lds_dwordx4 v[146:147], off
	s_waitcnt vmcnt(6)
	s_barrier
	v_mfma_f32_16x16x32_bf16 v[52:55], v[200:203], v[162:165], v[52:55]
	v_mfma_f32_16x16x32_bf16 v[48:51], v[208:211], v[162:165], v[48:51]
	v_mfma_f32_16x16x32_bf16 v[36:39], v[200:203], v[170:173], v[36:39]
	v_mfma_f32_16x16x32_bf16 v[32:35], v[208:211], v[170:173], v[32:35]
	v_mfma_f32_16x16x32_bf16 v[20:23], v[200:203], v[178:181], v[20:23]
	v_mfma_f32_16x16x32_bf16 v[16:19], v[208:211], v[178:181], v[16:19]
	v_mfma_f32_16x16x32_bf16 v[4:7], v[200:203], v[186:189], v[4:7]
	v_mfma_f32_16x16x32_bf16 v[0:3], v[208:211], v[186:189], v[0:3]
	v_mfma_f32_16x16x32_bf16 v[52:55], v[204:207], v[166:169], v[52:55]
	v_mfma_f32_16x16x32_bf16 v[48:51], v[212:215], v[166:169], v[48:51]
	v_mfma_f32_16x16x32_bf16 v[36:39], v[204:207], v[174:177], v[36:39]
	v_mfma_f32_16x16x32_bf16 v[32:35], v[212:215], v[174:177], v[32:35]
	v_mfma_f32_16x16x32_bf16 v[20:23], v[204:207], v[182:185], v[20:23]
	v_mfma_f32_16x16x32_bf16 v[16:19], v[212:215], v[182:185], v[16:19]
	v_mfma_f32_16x16x32_bf16 v[4:7], v[204:207], v[196:199], v[4:7]
	v_mfma_f32_16x16x32_bf16 v[0:3], v[212:215], v[196:199], v[0:3]
	s_barrier
	s_add_i32 s84, 0, 0x18000
	v_add_u32_e32 v158, s84, v141
	ds_read_b128 v[146:149], v158
	ds_read_b128 v[150:153], v158 offset:1024
	ds_read_b128 v[154:157], v158 offset:2048
	ds_read_b128 v[158:161], v158 offset:3072
	s_add_u32 s48, s48, 0x40000
	s_addc_u32 s49, s49, 0
	s_mov_b32 m0, s53
	v_lshl_add_u64 v[200:201], s[48:49], 0, v[134:135]
	ds_read_b128 v[162:165], v144 offset:32768
	ds_read_b128 v[166:169], v144 offset:33792
	ds_read_b128 v[170:173], v144 offset:34816
	ds_read_b128 v[174:177], v144 offset:35840
	ds_read_b128 v[178:181], v144 offset:36864
	ds_read_b128 v[182:185], v144 offset:37888
	ds_read_b128 v[186:189], v144 offset:38912
	ds_read_b128 v[196:199], v144 offset:39936
	global_load_lds_dwordx4 v[200:201], off
	v_lshl_add_u64 v[200:201], s[48:49], 0, v[130:131]
	s_mov_b32 m0, s54
	s_nop 0
	global_load_lds_dwordx4 v[200:201], off
	s_waitcnt lgkmcnt(8)
	s_barrier
	s_waitcnt lgkmcnt(0)
	v_mfma_f32_16x16x32_bf16 v[124:127], v[146:149], v[162:165], v[124:127]
	v_mfma_f32_16x16x32_bf16 v[120:123], v[154:157], v[162:165], v[120:123]
	v_mfma_f32_16x16x32_bf16 v[108:111], v[146:149], v[170:173], v[108:111]
	v_mfma_f32_16x16x32_bf16 v[104:107], v[154:157], v[170:173], v[104:107]
	v_mfma_f32_16x16x32_bf16 v[92:95], v[146:149], v[178:181], v[92:95]
	v_mfma_f32_16x16x32_bf16 v[88:91], v[154:157], v[178:181], v[88:91]
	v_mfma_f32_16x16x32_bf16 v[76:79], v[146:149], v[186:189], v[76:79]
	v_mfma_f32_16x16x32_bf16 v[72:75], v[154:157], v[186:189], v[72:75]
	v_mfma_f32_16x16x32_bf16 v[124:127], v[150:153], v[166:169], v[124:127]
	v_mfma_f32_16x16x32_bf16 v[120:123], v[158:161], v[166:169], v[120:123]
	v_mfma_f32_16x16x32_bf16 v[108:111], v[150:153], v[174:177], v[108:111]
	v_mfma_f32_16x16x32_bf16 v[104:107], v[158:161], v[174:177], v[104:107]
	v_mfma_f32_16x16x32_bf16 v[92:95], v[150:153], v[182:185], v[92:95]
	v_mfma_f32_16x16x32_bf16 v[88:91], v[158:161], v[182:185], v[88:91]
	v_mfma_f32_16x16x32_bf16 v[76:79], v[150:153], v[196:199], v[76:79]
	v_mfma_f32_16x16x32_bf16 v[72:75], v[158:161], v[196:199], v[72:75]
	s_barrier
	s_add_i32 s48, 0, 0x1c000
	s_add_i32 s49, s84, s50
	v_add_u32_e32 v195, s48, v141
	v_lshl_add_u64 v[190:191], v[190:191], 0, s[0:1]
	s_mov_b32 m0, s49
	ds_read_b128 v[200:203], v195
	ds_read_b128 v[204:207], v195 offset:1024
	ds_read_b128 v[208:211], v195 offset:2048
	ds_read_b128 v[212:215], v195 offset:3072
	global_load_lds_dwordx4 v[190:191], off
	v_lshl_add_u64 v[190:191], v[216:217], 0, s[0:1]
	s_add_i32 m0, s49, 0x2000
	s_nop 0
	global_load_lds_dwordx4 v[190:191], off
	s_barrier
	s_waitcnt lgkmcnt(0)
	v_mfma_f32_16x16x32_bf16 v[116:119], v[200:203], v[162:165], v[116:119]
	v_mfma_f32_16x16x32_bf16 v[112:115], v[208:211], v[162:165], v[112:115]
	v_mfma_f32_16x16x32_bf16 v[100:103], v[200:203], v[170:173], v[100:103]
	v_mfma_f32_16x16x32_bf16 v[96:99], v[208:211], v[170:173], v[96:99]
	v_mfma_f32_16x16x32_bf16 v[84:87], v[200:203], v[178:181], v[84:87]
	v_mfma_f32_16x16x32_bf16 v[80:83], v[208:211], v[178:181], v[80:83]
	v_mfma_f32_16x16x32_bf16 v[68:71], v[200:203], v[186:189], v[68:71]
	v_mfma_f32_16x16x32_bf16 v[64:67], v[208:211], v[186:189], v[64:67]
	v_mfma_f32_16x16x32_bf16 v[116:119], v[204:207], v[166:169], v[116:119]
	v_mfma_f32_16x16x32_bf16 v[112:115], v[212:215], v[166:169], v[112:115]
	v_mfma_f32_16x16x32_bf16 v[100:103], v[204:207], v[174:177], v[100:103]
	v_mfma_f32_16x16x32_bf16 v[96:99], v[212:215], v[174:177], v[96:99]
	v_mfma_f32_16x16x32_bf16 v[84:87], v[204:207], v[182:185], v[84:87]
	v_mfma_f32_16x16x32_bf16 v[80:83], v[212:215], v[182:185], v[80:83]
	v_mfma_f32_16x16x32_bf16 v[68:71], v[204:207], v[196:199], v[68:71]
	v_mfma_f32_16x16x32_bf16 v[64:67], v[212:215], v[196:199], v[64:67]
	s_barrier
	s_mov_b32 m0, s57
	v_lshl_add_u64 v[190:191], v[218:219], 0, s[0:1]
	ds_read_b128 v[162:165], v144 offset:49152
	ds_read_b128 v[166:169], v144 offset:50176
	ds_read_b128 v[170:173], v144 offset:51200
	ds_read_b128 v[174:177], v144 offset:52224
	ds_read_b128 v[178:181], v144 offset:53248
	ds_read_b128 v[182:185], v144 offset:54272
	ds_read_b128 v[186:189], v144 offset:55296
	ds_read_b128 v[196:199], v144 offset:56320
	global_load_lds_dwordx4 v[190:191], off
	v_lshl_add_u64 v[190:191], v[220:221], 0, s[0:1]
	s_mov_b32 m0, s58
	s_nop 0
	global_load_lds_dwordx4 v[190:191], off
	s_barrier
	s_waitcnt lgkmcnt(0)
	v_mfma_f32_16x16x32_bf16 v[60:63], v[146:149], v[162:165], v[60:63]
	v_mfma_f32_16x16x32_bf16 v[56:59], v[154:157], v[162:165], v[56:59]
	v_mfma_f32_16x16x32_bf16 v[44:47], v[146:149], v[170:173], v[44:47]
	v_mfma_f32_16x16x32_bf16 v[40:43], v[154:157], v[170:173], v[40:43]
	v_mfma_f32_16x16x32_bf16 v[28:31], v[146:149], v[178:181], v[28:31]
	v_mfma_f32_16x16x32_bf16 v[24:27], v[154:157], v[178:181], v[24:27]
	v_mfma_f32_16x16x32_bf16 v[12:15], v[146:149], v[186:189], v[12:15]
	v_mfma_f32_16x16x32_bf16 v[8:11], v[154:157], v[186:189], v[8:11]
	v_mfma_f32_16x16x32_bf16 v[60:63], v[150:153], v[166:169], v[60:63]
	v_mfma_f32_16x16x32_bf16 v[56:59], v[158:161], v[166:169], v[56:59]
	v_mfma_f32_16x16x32_bf16 v[44:47], v[150:153], v[174:177], v[44:47]
	v_mfma_f32_16x16x32_bf16 v[40:43], v[158:161], v[174:177], v[40:43]
	v_mfma_f32_16x16x32_bf16 v[28:31], v[150:153], v[182:185], v[28:31]
	v_mfma_f32_16x16x32_bf16 v[24:27], v[158:161], v[182:185], v[24:27]
	v_mfma_f32_16x16x32_bf16 v[12:15], v[150:153], v[196:199], v[12:15]
	v_mfma_f32_16x16x32_bf16 v[8:11], v[158:161], v[196:199], v[8:11]
	s_barrier
	s_add_u32 s46, s46, 0x10080
	s_addc_u32 s47, s47, 0
	s_add_i32 s48, s48, s50
	v_lshl_add_u64 v[146:147], s[46:47], 0, v[132:133]
	s_mov_b32 m0, s48
	s_nop 0
	global_load_lds_dwordx4 v[146:147], off
	v_lshl_add_u64 v[146:147], s[46:47], 0, v[128:129]
	s_add_i32 m0, s48, 0x2000
	s_nop 0
	global_load_lds_dwordx4 v[146:147], off
	s_add_i32 s67, s67, 2
	s_add_u32 s44, s44, 0x100
	s_addc_u32 s45, s45, 0
	s_add_u32 s65, s65, 0x100
	s_addc_u32 s66, s66, 0
	s_cmp_gt_u32 s67, 13
	s_waitcnt vmcnt(6)
	s_barrier
	v_mfma_f32_16x16x32_bf16 v[52:55], v[200:203], v[162:165], v[52:55]
	v_mfma_f32_16x16x32_bf16 v[48:51], v[208:211], v[162:165], v[48:51]
	v_mfma_f32_16x16x32_bf16 v[36:39], v[200:203], v[170:173], v[36:39]
	v_mfma_f32_16x16x32_bf16 v[32:35], v[208:211], v[170:173], v[32:35]
	v_mfma_f32_16x16x32_bf16 v[20:23], v[200:203], v[178:181], v[20:23]
	v_mfma_f32_16x16x32_bf16 v[16:19], v[208:211], v[178:181], v[16:19]
	v_mfma_f32_16x16x32_bf16 v[4:7], v[200:203], v[186:189], v[4:7]
	v_mfma_f32_16x16x32_bf16 v[0:3], v[208:211], v[186:189], v[0:3]
	v_mfma_f32_16x16x32_bf16 v[52:55], v[204:207], v[166:169], v[52:55]
	v_mfma_f32_16x16x32_bf16 v[48:51], v[212:215], v[166:169], v[48:51]
	v_mfma_f32_16x16x32_bf16 v[36:39], v[204:207], v[174:177], v[36:39]
	v_mfma_f32_16x16x32_bf16 v[32:35], v[212:215], v[174:177], v[32:35]
	v_mfma_f32_16x16x32_bf16 v[20:23], v[204:207], v[182:185], v[20:23]
	v_mfma_f32_16x16x32_bf16 v[16:19], v[212:215], v[182:185], v[16:19]
	v_mfma_f32_16x16x32_bf16 v[4:7], v[204:207], v[196:199], v[4:7]
	v_mfma_f32_16x16x32_bf16 v[0:3], v[212:215], v[196:199], v[0:3]
	s_barrier
	s_cbranch_scc0 .LBB0_342
	v_cvt_pk_bf16_f32 v124, v124, v125
	v_cvt_pk_bf16_f32 v120, v120, v121
	v_cvt_pk_bf16_f32 v121, v122, v123
	v_cvt_pk_bf16_f32 v122, v116, v117
	v_cvt_pk_bf16_f32 v112, v112, v113
	v_cvt_pk_bf16_f32 v125, v126, v127
	v_cvt_pk_bf16_f32 v118, v118, v119
	v_cvt_pk_bf16_f32 v113, v114, v115
	v_cndmask_b32_e64 v114, v124, v122, s[2:3]
	v_mov_b32_e32 v123, 0
	v_cndmask_b32_e64 v115, v120, v112, s[2:3]
	v_mov_b32_e32 v126, 0
	v_lshl_add_u32 v148, s42, 8, v140
	v_mov_b32_dpp v123, v114 row_ror:8 row_mask:0xf bank_mask:0xf
	v_cndmask_b32_e64 v114, v125, v118, s[2:3]
	v_mov_b32_e32 v119, 0
	v_mov_b32_dpp v126, v115 row_ror:8 row_mask:0xf bank_mask:0xf
	v_mov_b32_e32 v127, 0
	v_mov_b32_dpp v119, v114 row_ror:8 row_mask:0xf bank_mask:0xf
	v_cndmask_b32_e64 v114, v121, v113, s[2:3]
	v_cndmask_b32_e64 v116, v126, v120, s[2:3]
	v_cndmask_b32_e64 v120, v112, v126, s[2:3]
	v_add_u32_e32 v112, -8, v148
	v_mov_b32_dpp v127, v114 row_ror:8 row_mask:0xf bank_mask:0xf
	v_cndmask_b32_e64 v112, v112, v148, s[2:3]
	v_lshl_or_b32 v146, s62, 8, v142
	v_cndmask_b32_e64 v117, v127, v121, s[2:3]
	v_cndmask_b32_e64 v121, v113, v127, s[2:3]
	v_ashrrev_i32_e32 v113, 31, v112
	v_ashrrev_i32_e32 v147, 31, v146
	v_lshlrev_b64 v[112:113], 11, v[112:113]
	v_cndmask_b32_e64 v115, v119, v125, s[2:3]
	v_cndmask_b32_e64 v114, v123, v124, s[2:3]
	v_cndmask_b32_e64 v119, v118, v119, s[2:3]
	v_cndmask_b32_e64 v118, v122, v123, s[2:3]
	v_lshl_add_u64 v[122:123], s[40:41], 0, v[112:113]
	v_lshlrev_b64 v[112:113], 1, v[146:147]
	v_lshl_add_u64 v[122:123], v[122:123], 0, v[112:113]
	global_store_dwordx4 v[122:123], v[114:117], off
	v_cvt_pk_bf16_f32 v108, v108, v109
	v_cvt_pk_bf16_f32 v100, v100, v101
	v_add_u32_e32 v116, 8, v148
	v_cndmask_b32_e64 v114, v148, v116, s[2:3]
	v_ashrrev_i32_e32 v115, 31, v114
	v_lshlrev_b64 v[114:115], 11, v[114:115]
	v_lshl_add_u64 v[114:115], s[40:41], 0, v[114:115]
	v_cvt_pk_bf16_f32 v109, v110, v111
	v_cvt_pk_bf16_f32 v104, v104, v105
	v_cvt_pk_bf16_f32 v105, v106, v107
	v_cvt_pk_bf16_f32 v101, v102, v103
	v_cvt_pk_bf16_f32 v102, v96, v97
	v_cndmask_b32_e64 v96, v108, v100, s[2:3]
	v_mov_b32_e32 v106, 0
	v_lshl_add_u64 v[114:115], v[114:115], 0, v[112:113]
	v_cvt_pk_bf16_f32 v103, v98, v99
	v_mov_b32_dpp v106, v96 row_ror:8 row_mask:0xf bank_mask:0xf
	v_cndmask_b32_e64 v96, v109, v101, s[2:3]
	v_mov_b32_e32 v107, 0
	v_cndmask_b32_e64 v97, v104, v102, s[2:3]
	v_mov_b32_e32 v110, 0
	global_store_dwordx4 v[114:115], v[118:121], off
	v_or_b32_e32 v114, 16, v148
	v_mov_b32_dpp v107, v96 row_ror:8 row_mask:0xf bank_mask:0xf
	v_cndmask_b32_e64 v96, v105, v103, s[2:3]
	v_mov_b32_dpp v110, v97 row_ror:8 row_mask:0xf bank_mask:0xf
	v_mov_b32_e32 v111, 0
	v_cndmask_b32_e64 v98, v110, v104, s[2:3]
	v_cndmask_b32_e64 v104, v116, v114, s[2:3]
	v_mov_b32_dpp v111, v96 row_ror:8 row_mask:0xf bank_mask:0xf
	v_cndmask_b32_e64 v99, v111, v105, s[2:3]
	v_ashrrev_i32_e32 v105, 31, v104
	v_lshlrev_b64 v[104:105], 11, v[104:105]
	v_lshl_add_u64 v[104:105], s[40:41], 0, v[104:105]
	v_cndmask_b32_e64 v97, v107, v109, s[2:3]
	v_cndmask_b32_e64 v96, v106, v108, s[2:3]
	v_lshl_add_u64 v[104:105], v[104:105], 0, v[112:113]
	global_store_dwordx4 v[104:105], v[96:99], off
	v_cvt_pk_bf16_f32 v92, v92, v93
	v_cvt_pk_bf16_f32 v84, v84, v85
	v_add_u32_e32 v98, 24, v148
	v_cndmask_b32_e64 v96, v114, v98, s[2:3]
	v_ashrrev_i32_e32 v97, 31, v96
	v_lshlrev_b64 v[96:97], 11, v[96:97]
	v_lshl_add_u64 v[96:97], s[40:41], 0, v[96:97]
	v_cvt_pk_bf16_f32 v93, v94, v95
	v_cvt_pk_bf16_f32 v88, v88, v89
	v_cvt_pk_bf16_f32 v89, v90, v91
	v_cvt_pk_bf16_f32 v85, v86, v87
	v_cvt_pk_bf16_f32 v86, v80, v81
	v_cndmask_b32_e64 v80, v92, v84, s[2:3]
	v_mov_b32_e32 v90, 0
	v_cndmask_b32_e64 v103, v103, v111, s[2:3]
	v_cndmask_b32_e64 v102, v102, v110, s[2:3]
	v_cndmask_b32_e64 v101, v101, v107, s[2:3]
	v_cndmask_b32_e64 v100, v100, v106, s[2:3]
	v_lshl_add_u64 v[96:97], v[96:97], 0, v[112:113]
	v_cvt_pk_bf16_f32 v87, v82, v83
	v_mov_b32_dpp v90, v80 row_ror:8 row_mask:0xf bank_mask:0xf
	v_cndmask_b32_e64 v80, v93, v85, s[2:3]
	v_mov_b32_e32 v91, 0
	v_cndmask_b32_e64 v81, v88, v86, s[2:3]
	v_mov_b32_e32 v94, 0
	global_store_dwordx4 v[96:97], v[100:103], off
	v_or_b32_e32 v96, 32, v148
	v_mov_b32_dpp v91, v80 row_ror:8 row_mask:0xf bank_mask:0xf
	v_cndmask_b32_e64 v80, v89, v87, s[2:3]
	v_mov_b32_dpp v94, v81 row_ror:8 row_mask:0xf bank_mask:0xf
	v_mov_b32_e32 v95, 0
	v_cndmask_b32_e64 v82, v94, v88, s[2:3]
	v_cndmask_b32_e64 v88, v98, v96, s[2:3]
	v_mov_b32_dpp v95, v80 row_ror:8 row_mask:0xf bank_mask:0xf
	v_cndmask_b32_e64 v83, v95, v89, s[2:3]
	v_ashrrev_i32_e32 v89, 31, v88
	v_lshlrev_b64 v[88:89], 11, v[88:89]
	v_lshl_add_u64 v[88:89], s[40:41], 0, v[88:89]
	v_cndmask_b32_e64 v81, v91, v93, s[2:3]
	v_cndmask_b32_e64 v80, v90, v92, s[2:3]
	v_lshl_add_u64 v[88:89], v[88:89], 0, v[112:113]
	global_store_dwordx4 v[88:89], v[80:83], off
	v_cvt_pk_bf16_f32 v76, v76, v77
	v_cvt_pk_bf16_f32 v68, v68, v69
	v_add_u32_e32 v82, 40, v148
	v_cndmask_b32_e64 v80, v96, v82, s[2:3]
	v_ashrrev_i32_e32 v81, 31, v80
	v_lshlrev_b64 v[80:81], 11, v[80:81]
	v_lshl_add_u64 v[80:81], s[40:41], 0, v[80:81]
	v_cvt_pk_bf16_f32 v77, v78, v79
	v_cvt_pk_bf16_f32 v72, v72, v73
	v_cvt_pk_bf16_f32 v73, v74, v75
	v_cvt_pk_bf16_f32 v69, v70, v71
	v_cvt_pk_bf16_f32 v70, v64, v65
	v_cndmask_b32_e64 v64, v76, v68, s[2:3]
	v_mov_b32_e32 v74, 0
	v_cndmask_b32_e64 v87, v87, v95, s[2:3]
	v_cndmask_b32_e64 v86, v86, v94, s[2:3]
	v_cndmask_b32_e64 v85, v85, v91, s[2:3]
	v_cndmask_b32_e64 v84, v84, v90, s[2:3]
	v_lshl_add_u64 v[80:81], v[80:81], 0, v[112:113]
	v_cvt_pk_bf16_f32 v71, v66, v67
	v_mov_b32_dpp v74, v64 row_ror:8 row_mask:0xf bank_mask:0xf
	v_cndmask_b32_e64 v64, v77, v69, s[2:3]
	v_mov_b32_e32 v75, 0
	v_cndmask_b32_e64 v65, v72, v70, s[2:3]
	v_mov_b32_e32 v78, 0
	global_store_dwordx4 v[80:81], v[84:87], off
	v_or_b32_e32 v80, 48, v148
	v_mov_b32_dpp v75, v64 row_ror:8 row_mask:0xf bank_mask:0xf
	v_cndmask_b32_e64 v64, v73, v71, s[2:3]
	v_mov_b32_dpp v78, v65 row_ror:8 row_mask:0xf bank_mask:0xf
	v_mov_b32_e32 v79, 0
	v_cndmask_b32_e64 v66, v78, v72, s[2:3]
	v_cndmask_b32_e64 v72, v82, v80, s[2:3]
	v_mov_b32_dpp v79, v64 row_ror:8 row_mask:0xf bank_mask:0xf
	v_cndmask_b32_e64 v67, v79, v73, s[2:3]
	v_ashrrev_i32_e32 v73, 31, v72
	v_lshlrev_b64 v[72:73], 11, v[72:73]
	v_lshl_add_u64 v[72:73], s[40:41], 0, v[72:73]
	v_cndmask_b32_e64 v65, v75, v77, s[2:3]
	v_cndmask_b32_e64 v64, v74, v76, s[2:3]
	v_lshl_add_u64 v[72:73], v[72:73], 0, v[112:113]
	global_store_dwordx4 v[72:73], v[64:67], off
	v_cvt_pk_bf16_f32 v60, v60, v61
	v_cvt_pk_bf16_f32 v56, v56, v57
	v_add_u32_e32 v64, 56, v148
	v_cndmask_b32_e64 v64, v80, v64, s[2:3]
	v_ashrrev_i32_e32 v65, 31, v64
	v_lshlrev_b64 v[64:65], 11, v[64:65]
	v_cvt_pk_bf16_f32 v52, v52, v53
	v_cvt_pk_bf16_f32 v53, v54, v55
	v_cvt_pk_bf16_f32 v54, v48, v49
	v_lshl_add_u64 v[64:65], s[40:41], 0, v[64:65]
	v_cvt_pk_bf16_f32 v61, v62, v63
	v_cvt_pk_bf16_f32 v57, v58, v59
	v_cndmask_b32_e64 v48, v60, v52, s[2:3]
	v_mov_b32_e32 v58, 0
	v_cndmask_b32_e64 v49, v56, v54, s[2:3]
	v_mov_b32_e32 v62, 0
	v_cndmask_b32_e64 v71, v71, v79, s[2:3]
	v_cndmask_b32_e64 v70, v70, v78, s[2:3]
	v_cndmask_b32_e64 v69, v69, v75, s[2:3]
	v_cndmask_b32_e64 v68, v68, v74, s[2:3]
	v_lshl_add_u64 v[64:65], v[64:65], 0, v[112:113]
	v_cvt_pk_bf16_f32 v55, v50, v51
	v_mov_b32_dpp v58, v48 row_ror:8 row_mask:0xf bank_mask:0xf
	v_cndmask_b32_e64 v48, v61, v53, s[2:3]
	v_mov_b32_e32 v59, 0
	v_mov_b32_dpp v62, v49 row_ror:8 row_mask:0xf bank_mask:0xf
	global_store_dwordx4 v[64:65], v[68:71], off
	v_add_u32_e32 v64, 0x80, v148
	v_mov_b32_dpp v59, v48 row_ror:8 row_mask:0xf bank_mask:0xf
	v_cndmask_b32_e64 v48, v57, v55, s[2:3]
	v_mov_b32_e32 v63, 0
	v_cndmask_b32_e64 v50, v62, v56, s[2:3]
	v_add_u32_e32 v56, 0x78, v148
	v_mov_b32_dpp v63, v48 row_ror:8 row_mask:0xf bank_mask:0xf
	v_cndmask_b32_e64 v56, v56, v64, s[2:3]
	v_cndmask_b32_e64 v51, v63, v57, s[2:3]
	v_ashrrev_i32_e32 v57, 31, v56
	v_lshlrev_b64 v[56:57], 11, v[56:57]
	v_lshl_add_u64 v[56:57], s[40:41], 0, v[56:57]
	v_cndmask_b32_e64 v49, v59, v61, s[2:3]
	v_cndmask_b32_e64 v48, v58, v60, s[2:3]
	v_lshl_add_u64 v[56:57], v[56:57], 0, v[112:113]
	global_store_dwordx4 v[56:57], v[48:51], off
	v_cvt_pk_bf16_f32 v44, v44, v45
	v_cvt_pk_bf16_f32 v36, v36, v37
	v_add_u32_e32 v50, 0x88, v148
	v_cndmask_b32_e64 v48, v64, v50, s[2:3]
	v_ashrrev_i32_e32 v49, 31, v48
	v_lshlrev_b64 v[48:49], 11, v[48:49]
	v_lshl_add_u64 v[48:49], s[40:41], 0, v[48:49]
	v_cvt_pk_bf16_f32 v45, v46, v47
	v_cvt_pk_bf16_f32 v40, v40, v41
	v_cvt_pk_bf16_f32 v41, v42, v43
	v_cvt_pk_bf16_f32 v37, v38, v39
	v_cvt_pk_bf16_f32 v38, v32, v33
	v_cndmask_b32_e64 v32, v44, v36, s[2:3]
	v_mov_b32_e32 v42, 0
	v_cndmask_b32_e64 v55, v55, v63, s[2:3]
	v_cndmask_b32_e64 v54, v54, v62, s[2:3]
	v_cndmask_b32_e64 v53, v53, v59, s[2:3]
	v_cndmask_b32_e64 v52, v52, v58, s[2:3]
	v_lshl_add_u64 v[48:49], v[48:49], 0, v[112:113]
	v_cvt_pk_bf16_f32 v39, v34, v35
	v_mov_b32_dpp v42, v32 row_ror:8 row_mask:0xf bank_mask:0xf
	v_cndmask_b32_e64 v32, v45, v37, s[2:3]
	v_mov_b32_e32 v43, 0
	v_cndmask_b32_e64 v33, v40, v38, s[2:3]
	v_mov_b32_e32 v46, 0
	global_store_dwordx4 v[48:49], v[52:55], off
	v_add_u32_e32 v48, 0x90, v148
	v_mov_b32_dpp v43, v32 row_ror:8 row_mask:0xf bank_mask:0xf
	v_cndmask_b32_e64 v32, v41, v39, s[2:3]
	v_mov_b32_dpp v46, v33 row_ror:8 row_mask:0xf bank_mask:0xf
	v_mov_b32_e32 v47, 0
	v_cndmask_b32_e64 v34, v46, v40, s[2:3]
	v_cndmask_b32_e64 v40, v50, v48, s[2:3]
	v_mov_b32_dpp v47, v32 row_ror:8 row_mask:0xf bank_mask:0xf
	v_cndmask_b32_e64 v35, v47, v41, s[2:3]
	v_ashrrev_i32_e32 v41, 31, v40
	v_lshlrev_b64 v[40:41], 11, v[40:41]
	v_lshl_add_u64 v[40:41], s[40:41], 0, v[40:41]
	v_cndmask_b32_e64 v33, v43, v45, s[2:3]
	v_cndmask_b32_e64 v32, v42, v44, s[2:3]
	v_lshl_add_u64 v[40:41], v[40:41], 0, v[112:113]
	global_store_dwordx4 v[40:41], v[32:35], off
	v_cvt_pk_bf16_f32 v28, v28, v29
	v_cvt_pk_bf16_f32 v20, v20, v21
	v_add_u32_e32 v34, 0x98, v148
	v_cndmask_b32_e64 v32, v48, v34, s[2:3]
	v_ashrrev_i32_e32 v33, 31, v32
	v_lshlrev_b64 v[32:33], 11, v[32:33]
	v_lshl_add_u64 v[32:33], s[40:41], 0, v[32:33]
	v_cvt_pk_bf16_f32 v29, v30, v31
	v_cvt_pk_bf16_f32 v24, v24, v25
	v_cvt_pk_bf16_f32 v25, v26, v27
	v_cvt_pk_bf16_f32 v21, v22, v23
	v_cvt_pk_bf16_f32 v22, v16, v17
	v_cndmask_b32_e64 v16, v28, v20, s[2:3]
	v_mov_b32_e32 v26, 0
	v_cndmask_b32_e64 v39, v39, v47, s[2:3]
	v_cndmask_b32_e64 v38, v38, v46, s[2:3]
	v_cndmask_b32_e64 v37, v37, v43, s[2:3]
	v_cndmask_b32_e64 v36, v36, v42, s[2:3]
	v_lshl_add_u64 v[32:33], v[32:33], 0, v[112:113]
	v_cvt_pk_bf16_f32 v23, v18, v19
	v_mov_b32_dpp v26, v16 row_ror:8 row_mask:0xf bank_mask:0xf
	v_cndmask_b32_e64 v16, v29, v21, s[2:3]
	v_mov_b32_e32 v27, 0
	v_cndmask_b32_e64 v17, v24, v22, s[2:3]
	v_mov_b32_e32 v30, 0
	global_store_dwordx4 v[32:33], v[36:39], off
	v_add_u32_e32 v32, 0xa0, v148
	v_mov_b32_dpp v27, v16 row_ror:8 row_mask:0xf bank_mask:0xf
	v_cndmask_b32_e64 v16, v25, v23, s[2:3]
	v_mov_b32_dpp v30, v17 row_ror:8 row_mask:0xf bank_mask:0xf
	v_mov_b32_e32 v31, 0
	v_cndmask_b32_e64 v18, v30, v24, s[2:3]
	v_cndmask_b32_e64 v24, v34, v32, s[2:3]
	v_mov_b32_dpp v31, v16 row_ror:8 row_mask:0xf bank_mask:0xf
	v_cndmask_b32_e64 v19, v31, v25, s[2:3]
	v_ashrrev_i32_e32 v25, 31, v24
	v_lshlrev_b64 v[24:25], 11, v[24:25]
	v_lshl_add_u64 v[24:25], s[40:41], 0, v[24:25]
	v_cndmask_b32_e64 v17, v27, v29, s[2:3]
	v_cndmask_b32_e64 v16, v26, v28, s[2:3]
	v_lshl_add_u64 v[24:25], v[24:25], 0, v[112:113]
	global_store_dwordx4 v[24:25], v[16:19], off
	v_cndmask_b32_e64 v23, v23, v31, s[2:3]
	v_cndmask_b32_e64 v22, v22, v30, s[2:3]
	v_add_u32_e32 v18, 0xa8, v148
	v_cndmask_b32_e64 v16, v32, v18, s[2:3]
	v_ashrrev_i32_e32 v17, 31, v16
	v_lshlrev_b64 v[16:17], 11, v[16:17]
	v_lshl_add_u64 v[16:17], s[40:41], 0, v[16:17]
	v_cndmask_b32_e64 v21, v21, v27, s[2:3]
	v_cndmask_b32_e64 v20, v20, v26, s[2:3]
	v_lshl_add_u64 v[16:17], v[16:17], 0, v[112:113]
	global_store_dwordx4 v[16:17], v[20:23], off
	v_add_u32_e32 v16, 0xb0, v148
	v_cvt_pk_bf16_f32 v12, v12, v13
	v_cvt_pk_bf16_f32 v8, v8, v9
	v_cvt_pk_bf16_f32 v9, v10, v11
	v_cvt_pk_bf16_f32 v10, v4, v5
	v_cvt_pk_bf16_f32 v13, v14, v15
	v_cvt_pk_bf16_f32 v6, v6, v7
	v_cvt_pk_bf16_f32 v7, v0, v1
	v_cndmask_b32_e64 v0, v12, v10, s[2:3]
	v_mov_b32_e32 v14, 0
	v_cndmask_b32_e64 v4, v18, v16, s[2:3]
	v_cvt_pk_bf16_f32 v11, v2, v3
	v_mov_b32_dpp v14, v0 row_ror:8 row_mask:0xf bank_mask:0xf
	v_cndmask_b32_e64 v0, v13, v6, s[2:3]
	v_mov_b32_e32 v15, 0
	v_ashrrev_i32_e32 v5, 31, v4
	v_cndmask_b32_e64 v1, v8, v7, s[2:3]
	v_mov_b32_dpp v15, v0 row_ror:8 row_mask:0xf bank_mask:0xf
	v_cndmask_b32_e64 v0, v9, v11, s[2:3]
	v_mov_b32_e32 v17, 0
	v_mov_b32_e32 v19, 0
	v_lshlrev_b64 v[4:5], 11, v[4:5]
	v_mov_b32_dpp v17, v1 row_ror:8 row_mask:0xf bank_mask:0xf
	v_mov_b32_dpp v19, v0 row_ror:8 row_mask:0xf bank_mask:0xf
	v_lshl_add_u64 v[4:5], s[40:41], 0, v[4:5]
	v_cndmask_b32_e64 v3, v19, v9, s[2:3]
	v_cndmask_b32_e64 v2, v17, v8, s[2:3]
	v_cndmask_b32_e64 v1, v15, v13, s[2:3]
	v_cndmask_b32_e64 v0, v14, v12, s[2:3]
	v_lshl_add_u64 v[4:5], v[4:5], 0, v[112:113]
	global_store_dwordx4 v[4:5], v[0:3], off
	s_and_b64 vcc, exec, s[4:5]
	s_mov_b32 s62, s6
	v_add_u32_e32 v0, 0xb8, v148
	v_cndmask_b32_e64 v0, v16, v0, s[2:3]
	v_ashrrev_i32_e32 v1, 31, v0
	v_lshlrev_b64 v[0:1], 11, v[0:1]
	v_lshl_add_u64 v[0:1], s[40:41], 0, v[0:1]
	v_lshl_add_u64 v[4:5], v[0:1], 0, v[112:113]
	v_cndmask_b32_e64 v3, v11, v19, s[2:3]
	v_cndmask_b32_e64 v2, v7, v17, s[2:3]
	v_cndmask_b32_e64 v1, v6, v15, s[2:3]
	v_cndmask_b32_e64 v0, v10, v14, s[2:3]
	s_mov_b32 s42, s8
	s_mov_b64 s[46:47], s[12:13]
	s_mov_b64 s[44:45], s[10:11]
	global_store_dwordx4 v[4:5], v[0:3], off
	s_cbranch_vccz .LBB0_335
	s_waitcnt vmcnt(0)
	s_cmpk_gt_u32 s17, 0xff
	s_cbranch_scc1 .LBB0_346
	s_barrier

.LBB0_740:
	ds_read_b128 v[64:67], v221
	ds_read_b128 v[68:71], v221 offset:1024
	ds_read_b128 v[84:87], v221 offset:2048
	ds_read_b128 v[92:95], v221 offset:3072
	s_add_u32 s28, s10, 0xfffc0080
	s_addc_u32 s29, s11, -1
	s_cmp_eq_u32 s92, 12
	s_cselect_b32 s65, s9, s29
	s_cselect_b32 s64, s13, s28
	s_cselect_b32 s63, s17, s57
	s_cselect_b32 s62, s44, s55
	v_lshl_add_u64 v[176:177], s[10:11], 0, v[204:205]
	s_add_i32 m0, s78, 0xc000
	ds_read_b128 v[144:147], v222
	ds_read_b128 v[148:151], v222 offset:1024
	ds_read_b128 v[152:155], v222 offset:2048
	ds_read_b128 v[156:159], v222 offset:3072
	ds_read_b128 v[160:163], v222 offset:4096
	ds_read_b128 v[164:167], v222 offset:5120
	ds_read_b128 v[168:171], v222 offset:6144
	ds_read_b128 v[172:175], v222 offset:7168
	global_load_lds_dwordx4 v[176:177], off
	v_lshl_add_u64 v[176:177], s[10:11], 0, v[206:207]
	s_add_i32 m0, s78, 0xe000
	s_nop 0
	global_load_lds_dwordx4 v[176:177], off
	s_waitcnt lgkmcnt(8)
	s_barrier
	s_waitcnt lgkmcnt(0)
	v_mfma_f32_16x16x32_bf16 v[140:143], v[64:67], v[144:147], v[140:143]
	v_mfma_f32_16x16x32_bf16 v[136:139], v[84:87], v[144:147], v[136:139]
	v_mfma_f32_16x16x32_bf16 v[124:127], v[64:67], v[152:155], v[124:127]
	v_mfma_f32_16x16x32_bf16 v[120:123], v[84:87], v[152:155], v[120:123]
	v_mfma_f32_16x16x32_bf16 v[108:111], v[64:67], v[160:163], v[108:111]
	v_mfma_f32_16x16x32_bf16 v[104:107], v[84:87], v[160:163], v[104:107]
	v_mfma_f32_16x16x32_bf16 v[88:91], v[64:67], v[168:171], v[88:91]
	v_mfma_f32_16x16x32_bf16 v[80:83], v[84:87], v[168:171], v[80:83]
	v_mfma_f32_16x16x32_bf16 v[140:143], v[68:71], v[148:151], v[140:143]
	v_mfma_f32_16x16x32_bf16 v[136:139], v[92:95], v[148:151], v[136:139]
	v_mfma_f32_16x16x32_bf16 v[124:127], v[68:71], v[156:159], v[124:127]
	v_mfma_f32_16x16x32_bf16 v[120:123], v[92:95], v[156:159], v[120:123]
	v_mfma_f32_16x16x32_bf16 v[108:111], v[68:71], v[164:167], v[108:111]
	v_mfma_f32_16x16x32_bf16 v[104:107], v[92:95], v[164:167], v[104:107]
	v_mfma_f32_16x16x32_bf16 v[88:91], v[68:71], v[172:175], v[88:91]
	v_mfma_f32_16x16x32_bf16 v[80:83], v[92:95], v[172:175], v[80:83]
	s_barrier
	s_add_i32 s28, s89, s67
	v_lshl_add_u64 v[212:213], s[62:63], 0, v[198:199]
	s_mov_b32 m0, s28
	ds_read_b128 v[176:179], v223
	ds_read_b128 v[180:183], v223 offset:1024
	ds_read_b128 v[184:187], v223 offset:2048
	ds_read_b128 v[188:191], v223 offset:3072
	global_load_lds_dwordx4 v[212:213], off
	v_lshl_add_u64 v[214:215], s[62:63], 0, v[202:203]
	s_add_i32 m0, s28, 0x2000
	s_nop 0
	global_load_lds_dwordx4 v[214:215], off
	s_barrier
	s_waitcnt lgkmcnt(0)
	v_mfma_f32_16x16x32_bf16 v[132:135], v[176:179], v[144:147], v[132:135]
	v_mfma_f32_16x16x32_bf16 v[128:131], v[184:187], v[144:147], v[128:131]
	v_mfma_f32_16x16x32_bf16 v[116:119], v[176:179], v[152:155], v[116:119]
	v_mfma_f32_16x16x32_bf16 v[112:115], v[184:187], v[152:155], v[112:115]
	v_mfma_f32_16x16x32_bf16 v[100:103], v[176:179], v[160:163], v[100:103]
	v_mfma_f32_16x16x32_bf16 v[96:99], v[184:187], v[160:163], v[96:99]
	v_mfma_f32_16x16x32_bf16 v[76:79], v[176:179], v[168:171], v[76:79]
	v_mfma_f32_16x16x32_bf16 v[72:75], v[184:187], v[168:171], v[72:75]
	v_mfma_f32_16x16x32_bf16 v[132:135], v[180:183], v[148:151], v[132:135]
	v_mfma_f32_16x16x32_bf16 v[128:131], v[188:191], v[148:151], v[128:131]
	v_mfma_f32_16x16x32_bf16 v[116:119], v[180:183], v[156:159], v[116:119]
	v_mfma_f32_16x16x32_bf16 v[112:115], v[188:191], v[156:159], v[112:115]
	v_mfma_f32_16x16x32_bf16 v[100:103], v[180:183], v[164:167], v[100:103]
	v_mfma_f32_16x16x32_bf16 v[96:99], v[188:191], v[164:167], v[96:99]
	v_mfma_f32_16x16x32_bf16 v[76:79], v[180:183], v[172:175], v[76:79]
	v_mfma_f32_16x16x32_bf16 v[72:75], v[188:191], v[172:175], v[72:75]
	s_barrier
	s_mov_b32 m0, s78
	v_lshl_add_u64 v[216:217], s[64:65], 0, v[196:197]
	ds_read_b128 v[144:147], v222 offset:16384
	ds_read_b128 v[148:151], v222 offset:17408
	ds_read_b128 v[152:155], v222 offset:18432
	ds_read_b128 v[156:159], v222 offset:19456
	ds_read_b128 v[160:163], v222 offset:20480
	ds_read_b128 v[164:167], v222 offset:21504
	ds_read_b128 v[168:171], v222 offset:22528
	ds_read_b128 v[172:175], v222 offset:23552
	global_load_lds_dwordx4 v[216:217], off
	v_lshl_add_u64 v[226:227], s[64:65], 0, v[200:201]
	s_mov_b32 m0, s79
	s_nop 0
	global_load_lds_dwordx4 v[226:227], off
	s_barrier
	s_waitcnt lgkmcnt(0)
	v_mfma_f32_16x16x32_bf16 v[60:63], v[64:67], v[144:147], v[60:63]
	v_mfma_f32_16x16x32_bf16 v[56:59], v[84:87], v[144:147], v[56:59]
	v_mfma_f32_16x16x32_bf16 v[44:47], v[64:67], v[152:155], v[44:47]
	v_mfma_f32_16x16x32_bf16 v[40:43], v[84:87], v[152:155], v[40:43]
	v_mfma_f32_16x16x32_bf16 v[28:31], v[64:67], v[160:163], v[28:31]
	v_mfma_f32_16x16x32_bf16 v[24:27], v[84:87], v[160:163], v[24:27]
	v_mfma_f32_16x16x32_bf16 v[12:15], v[64:67], v[168:171], v[12:15]
	v_mfma_f32_16x16x32_bf16 v[8:11], v[84:87], v[168:171], v[8:11]
	v_mfma_f32_16x16x32_bf16 v[60:63], v[68:71], v[148:151], v[60:63]
	v_mfma_f32_16x16x32_bf16 v[56:59], v[92:95], v[148:151], v[56:59]
	v_mfma_f32_16x16x32_bf16 v[44:47], v[68:71], v[156:159], v[44:47]
	v_mfma_f32_16x16x32_bf16 v[40:43], v[92:95], v[156:159], v[40:43]
	v_mfma_f32_16x16x32_bf16 v[28:31], v[68:71], v[164:167], v[28:31]
	v_mfma_f32_16x16x32_bf16 v[24:27], v[92:95], v[164:167], v[24:27]
	v_mfma_f32_16x16x32_bf16 v[12:15], v[68:71], v[172:175], v[12:15]
	v_mfma_f32_16x16x32_bf16 v[8:11], v[92:95], v[172:175], v[8:11]
	s_barrier
	s_add_u32 s94, s62, 0x10000
	s_addc_u32 s95, s63, 0
	s_add_i32 s28, s90, s67
	v_lshl_add_u64 v[64:65], s[94:95], 0, v[198:199]
	s_mov_b32 m0, s28
	s_nop 0
	global_load_lds_dwordx4 v[64:65], off
	v_lshl_add_u64 v[64:65], s[94:95], 0, v[202:203]
	s_add_i32 m0, s28, 0x2000
	s_nop 0
	global_load_lds_dwordx4 v[64:65], off
	s_waitcnt vmcnt(6)
	s_barrier
	v_mfma_f32_16x16x32_bf16 v[52:55], v[176:179], v[144:147], v[52:55]
	v_mfma_f32_16x16x32_bf16 v[48:51], v[184:187], v[144:147], v[48:51]
	v_mfma_f32_16x16x32_bf16 v[36:39], v[176:179], v[152:155], v[36:39]
	v_mfma_f32_16x16x32_bf16 v[32:35], v[184:187], v[152:155], v[32:35]
	v_mfma_f32_16x16x32_bf16 v[20:23], v[176:179], v[160:163], v[20:23]
	v_mfma_f32_16x16x32_bf16 v[16:19], v[184:187], v[160:163], v[16:19]
	v_mfma_f32_16x16x32_bf16 v[4:7], v[176:179], v[168:171], v[4:7]
	v_mfma_f32_16x16x32_bf16 v[0:3], v[184:187], v[168:171], v[0:3]
	v_mfma_f32_16x16x32_bf16 v[52:55], v[180:183], v[148:151], v[52:55]
	v_mfma_f32_16x16x32_bf16 v[48:51], v[188:191], v[148:151], v[48:51]
	v_mfma_f32_16x16x32_bf16 v[36:39], v[180:183], v[156:159], v[36:39]
	v_mfma_f32_16x16x32_bf16 v[32:35], v[188:191], v[156:159], v[32:35]
	v_mfma_f32_16x16x32_bf16 v[20:23], v[180:183], v[164:167], v[20:23]
	v_mfma_f32_16x16x32_bf16 v[16:19], v[188:191], v[164:167], v[16:19]
	v_mfma_f32_16x16x32_bf16 v[4:7], v[180:183], v[172:175], v[4:7]
	v_mfma_f32_16x16x32_bf16 v[0:3], v[188:191], v[172:175], v[0:3]
	s_barrier
	s_add_i32 s28, 0, 0x18000
	v_add_u32_e32 v92, s28, v218
	ds_read_b128 v[64:67], v92
	ds_read_b128 v[68:71], v92 offset:1024
	ds_read_b128 v[84:87], v92 offset:2048
	ds_read_b128 v[92:95], v92 offset:3072
	s_add_u32 s64, s64, 0x40000
	s_addc_u32 s65, s65, 0
	s_mov_b32 m0, s80
	v_lshl_add_u64 v[176:177], s[64:65], 0, v[196:197]
	ds_read_b128 v[144:147], v222 offset:32768
	ds_read_b128 v[148:151], v222 offset:33792
	ds_read_b128 v[152:155], v222 offset:34816
	ds_read_b128 v[156:159], v222 offset:35840
	ds_read_b128 v[160:163], v222 offset:36864
	ds_read_b128 v[164:167], v222 offset:37888
	ds_read_b128 v[168:171], v222 offset:38912
	ds_read_b128 v[172:175], v222 offset:39936
	global_load_lds_dwordx4 v[176:177], off
	v_lshl_add_u64 v[176:177], s[64:65], 0, v[200:201]
	s_mov_b32 m0, s81
	s_nop 0
	global_load_lds_dwordx4 v[176:177], off
	s_waitcnt lgkmcnt(8)
	s_barrier
	s_waitcnt lgkmcnt(0)
	v_mfma_f32_16x16x32_bf16 v[140:143], v[64:67], v[144:147], v[140:143]
	v_mfma_f32_16x16x32_bf16 v[136:139], v[84:87], v[144:147], v[136:139]
	v_mfma_f32_16x16x32_bf16 v[124:127], v[64:67], v[152:155], v[124:127]
	v_mfma_f32_16x16x32_bf16 v[120:123], v[84:87], v[152:155], v[120:123]
	v_mfma_f32_16x16x32_bf16 v[108:111], v[64:67], v[160:163], v[108:111]
	v_mfma_f32_16x16x32_bf16 v[104:107], v[84:87], v[160:163], v[104:107]
	v_mfma_f32_16x16x32_bf16 v[88:91], v[64:67], v[168:171], v[88:91]
	v_mfma_f32_16x16x32_bf16 v[80:83], v[84:87], v[168:171], v[80:83]
	v_mfma_f32_16x16x32_bf16 v[140:143], v[68:71], v[148:151], v[140:143]
	v_mfma_f32_16x16x32_bf16 v[136:139], v[92:95], v[148:151], v[136:139]
	v_mfma_f32_16x16x32_bf16 v[124:127], v[68:71], v[156:159], v[124:127]
	v_mfma_f32_16x16x32_bf16 v[120:123], v[92:95], v[156:159], v[120:123]
	v_mfma_f32_16x16x32_bf16 v[108:111], v[68:71], v[164:167], v[108:111]
	v_mfma_f32_16x16x32_bf16 v[104:107], v[92:95], v[164:167], v[104:107]
	v_mfma_f32_16x16x32_bf16 v[88:91], v[68:71], v[172:175], v[88:91]
	v_mfma_f32_16x16x32_bf16 v[80:83], v[92:95], v[172:175], v[80:83]
	s_barrier
	s_add_i32 s29, 0, 0x1c000
	s_add_i32 s28, s28, s67
	v_add_u32_e32 v188, s29, v218
	v_lshl_add_u64 v[212:213], v[212:213], 0, s[52:53]
	s_mov_b32 m0, s28
	ds_read_b128 v[176:179], v188
	ds_read_b128 v[180:183], v188 offset:1024
	ds_read_b128 v[184:187], v188 offset:2048
	ds_read_b128 v[188:191], v188 offset:3072
	global_load_lds_dwordx4 v[212:213], off
	v_lshl_add_u64 v[212:213], v[214:215], 0, s[52:53]
	s_add_i32 m0, s28, 0x2000
	s_nop 0
	global_load_lds_dwordx4 v[212:213], off
	s_barrier
	s_waitcnt lgkmcnt(0)
	v_mfma_f32_16x16x32_bf16 v[132:135], v[176:179], v[144:147], v[132:135]
	v_mfma_f32_16x16x32_bf16 v[128:131], v[184:187], v[144:147], v[128:131]
	v_mfma_f32_16x16x32_bf16 v[116:119], v[176:179], v[152:155], v[116:119]
	v_mfma_f32_16x16x32_bf16 v[112:115], v[184:187], v[152:155], v[112:115]
	v_mfma_f32_16x16x32_bf16 v[100:103], v[176:179], v[160:163], v[100:103]
	v_mfma_f32_16x16x32_bf16 v[96:99], v[184:187], v[160:163], v[96:99]
	v_mfma_f32_16x16x32_bf16 v[76:79], v[176:179], v[168:171], v[76:79]
	v_mfma_f32_16x16x32_bf16 v[72:75], v[184:187], v[168:171], v[72:75]
	v_mfma_f32_16x16x32_bf16 v[132:135], v[180:183], v[148:151], v[132:135]
	v_mfma_f32_16x16x32_bf16 v[128:131], v[188:191], v[148:151], v[128:131]
	v_mfma_f32_16x16x32_bf16 v[116:119], v[180:183], v[156:159], v[116:119]
	v_mfma_f32_16x16x32_bf16 v[112:115], v[188:191], v[156:159], v[112:115]
	v_mfma_f32_16x16x32_bf16 v[100:103], v[180:183], v[164:167], v[100:103]
	v_mfma_f32_16x16x32_bf16 v[96:99], v[188:191], v[164:167], v[96:99]
	v_mfma_f32_16x16x32_bf16 v[76:79], v[180:183], v[172:175], v[76:79]
	v_mfma_f32_16x16x32_bf16 v[72:75], v[188:191], v[172:175], v[72:75]
	s_barrier
	s_mov_b32 m0, s85
	v_lshl_add_u64 v[212:213], v[216:217], 0, s[52:53]
	ds_read_b128 v[144:147], v222 offset:49152
	ds_read_b128 v[148:151], v222 offset:50176
	ds_read_b128 v[152:155], v222 offset:51200
	ds_read_b128 v[156:159], v222 offset:52224
	ds_read_b128 v[160:163], v222 offset:53248
	ds_read_b128 v[164:167], v222 offset:54272
	ds_read_b128 v[168:171], v222 offset:55296
	ds_read_b128 v[172:175], v222 offset:56320
	global_load_lds_dwordx4 v[212:213], off
	v_lshl_add_u64 v[212:213], v[226:227], 0, s[52:53]
	s_mov_b32 m0, s87
	s_nop 0
	global_load_lds_dwordx4 v[212:213], off
	s_barrier
	s_waitcnt lgkmcnt(0)
	v_mfma_f32_16x16x32_bf16 v[60:63], v[64:67], v[144:147], v[60:63]
	v_mfma_f32_16x16x32_bf16 v[56:59], v[84:87], v[144:147], v[56:59]
	v_mfma_f32_16x16x32_bf16 v[44:47], v[64:67], v[152:155], v[44:47]
	v_mfma_f32_16x16x32_bf16 v[40:43], v[84:87], v[152:155], v[40:43]
	v_mfma_f32_16x16x32_bf16 v[28:31], v[64:67], v[160:163], v[28:31]
	v_mfma_f32_16x16x32_bf16 v[24:27], v[84:87], v[160:163], v[24:27]
	v_mfma_f32_16x16x32_bf16 v[12:15], v[64:67], v[168:171], v[12:15]
	v_mfma_f32_16x16x32_bf16 v[8:11], v[84:87], v[168:171], v[8:11]
	v_mfma_f32_16x16x32_bf16 v[60:63], v[68:71], v[148:151], v[60:63]
	v_mfma_f32_16x16x32_bf16 v[56:59], v[92:95], v[148:151], v[56:59]
	v_mfma_f32_16x16x32_bf16 v[44:47], v[68:71], v[156:159], v[44:47]
	v_mfma_f32_16x16x32_bf16 v[40:43], v[92:95], v[156:159], v[40:43]
	v_mfma_f32_16x16x32_bf16 v[28:31], v[68:71], v[164:167], v[28:31]
	v_mfma_f32_16x16x32_bf16 v[24:27], v[92:95], v[164:167], v[24:27]
	v_mfma_f32_16x16x32_bf16 v[12:15], v[68:71], v[172:175], v[12:15]
	v_mfma_f32_16x16x32_bf16 v[8:11], v[92:95], v[172:175], v[8:11]
	s_barrier
	s_add_u32 s62, s62, 0x10080
	s_addc_u32 s63, s63, 0
	s_add_i32 s28, s29, s67
	v_lshl_add_u64 v[64:65], s[62:63], 0, v[198:199]
	s_mov_b32 m0, s28
	s_nop 0
	global_load_lds_dwordx4 v[64:65], off
	v_lshl_add_u64 v[64:65], s[62:63], 0, v[202:203]
	s_add_i32 m0, s28, 0x2000
	s_nop 0
	global_load_lds_dwordx4 v[64:65], off
	s_add_i32 s92, s92, 2
	s_add_u32 s10, s10, 0x100
	s_addc_u32 s11, s11, 0
	s_add_u32 s55, s55, 0x100
	s_addc_u32 s57, s57, 0
	s_cmp_gt_u32 s92, 13
	s_waitcnt vmcnt(6)
	s_barrier
	v_mfma_f32_16x16x32_bf16 v[52:55], v[176:179], v[144:147], v[52:55]
	v_mfma_f32_16x16x32_bf16 v[48:51], v[184:187], v[144:147], v[48:51]
	v_mfma_f32_16x16x32_bf16 v[36:39], v[176:179], v[152:155], v[36:39]
	v_mfma_f32_16x16x32_bf16 v[32:35], v[184:187], v[152:155], v[32:35]
	v_mfma_f32_16x16x32_bf16 v[20:23], v[176:179], v[160:163], v[20:23]
	v_mfma_f32_16x16x32_bf16 v[16:19], v[184:187], v[160:163], v[16:19]
	v_mfma_f32_16x16x32_bf16 v[4:7], v[176:179], v[168:171], v[4:7]
	v_mfma_f32_16x16x32_bf16 v[0:3], v[184:187], v[168:171], v[0:3]
	v_mfma_f32_16x16x32_bf16 v[52:55], v[180:183], v[148:151], v[52:55]
	v_mfma_f32_16x16x32_bf16 v[48:51], v[188:191], v[148:151], v[48:51]
	v_mfma_f32_16x16x32_bf16 v[36:39], v[180:183], v[156:159], v[36:39]
	v_mfma_f32_16x16x32_bf16 v[32:35], v[188:191], v[156:159], v[32:35]
	v_mfma_f32_16x16x32_bf16 v[20:23], v[180:183], v[164:167], v[20:23]
	v_mfma_f32_16x16x32_bf16 v[16:19], v[188:191], v[164:167], v[16:19]
	v_mfma_f32_16x16x32_bf16 v[4:7], v[180:183], v[172:175], v[4:7]
	v_mfma_f32_16x16x32_bf16 v[0:3], v[188:191], v[172:175], v[0:3]
	s_barrier
	s_cbranch_scc0 .LBB0_740
	v_lshl_add_u32 v212, s8, 8, v195
	v_lshl_or_b32 v214, s12, 8, v219
	v_ashrrev_i32_e32 v213, 31, v212
	v_ashrrev_i32_e32 v215, 31, v214
	s_mov_b64 s[8:9], -1
	s_and_b64 vcc, exec, s[48:49]
	s_cbranch_vccz .LBB0_743
	v_lshlrev_b64 v[64:65], 12, v[212:213]
	v_lshl_add_u64 v[64:65], s[36:37], 0, v[64:65]
	v_lshl_add_u64 v[64:65], v[214:215], 2, v[64:65]
	global_load_dwordx4 v[160:163], v[64:65], off offset:16
	global_load_dwordx4 v[164:167], v[64:65], off
	global_load_dwordx4 v[168:171], v[64:65], off offset:144
	global_load_dwordx4 v[172:175], v[64:65], off offset:128
	s_mov_b64 s[8:9], 0

.LBB0_904:
	ds_read_b128 v[146:149], v169
	ds_read_b128 v[150:153], v169 offset:1024
	ds_read_b128 v[154:157], v169 offset:2048
	ds_read_b128 v[174:177], v169 offset:3072
	s_add_u32 s28, s0, 0xfffc0080
	s_addc_u32 s29, s1, -1
	s_cmp_eq_u32 s78, 12
	s_cselect_b32 s53, s7, s29
	s_cselect_b32 s52, s45, s28
	s_cselect_b32 s51, s37, s77
	s_cselect_b32 s50, s67, s76
	v_lshl_add_u64 v[158:159], s[0:1], 0, v[138:139]
	s_add_i32 m0, s54, 0xc000
	ds_read_b128 v[178:181], v171
	ds_read_b128 v[182:185], v171 offset:1024
	ds_read_b128 v[186:189], v171 offset:2048
	ds_read_b128 v[196:199], v171 offset:3072
	ds_read_b128 v[200:203], v171 offset:4096
	ds_read_b128 v[204:207], v171 offset:5120
	ds_read_b128 v[208:211], v171 offset:6144
	ds_read_b128 v[212:215], v171 offset:7168
	global_load_lds_dwordx4 v[158:159], off
	v_lshl_add_u64 v[158:159], s[0:1], 0, v[140:141]
	s_add_i32 m0, s54, 0xe000
	s_nop 0
	global_load_lds_dwordx4 v[158:159], off
	s_waitcnt lgkmcnt(8)
	s_barrier
	s_waitcnt lgkmcnt(0)
	v_mfma_f32_16x16x32_bf16 v[124:127], v[146:149], v[178:181], v[124:127]
	v_mfma_f32_16x16x32_bf16 v[120:123], v[154:157], v[178:181], v[120:123]
	v_mfma_f32_16x16x32_bf16 v[108:111], v[146:149], v[186:189], v[108:111]
	v_mfma_f32_16x16x32_bf16 v[104:107], v[154:157], v[186:189], v[104:107]
	v_mfma_f32_16x16x32_bf16 v[92:95], v[146:149], v[200:203], v[92:95]
	v_mfma_f32_16x16x32_bf16 v[88:91], v[154:157], v[200:203], v[88:91]
	v_mfma_f32_16x16x32_bf16 v[76:79], v[146:149], v[208:211], v[76:79]
	v_mfma_f32_16x16x32_bf16 v[72:75], v[154:157], v[208:211], v[72:75]
	v_mfma_f32_16x16x32_bf16 v[124:127], v[150:153], v[182:185], v[124:127]
	v_mfma_f32_16x16x32_bf16 v[120:123], v[174:177], v[182:185], v[120:123]
	v_mfma_f32_16x16x32_bf16 v[108:111], v[150:153], v[196:199], v[108:111]
	v_mfma_f32_16x16x32_bf16 v[104:107], v[174:177], v[196:199], v[104:107]
	v_mfma_f32_16x16x32_bf16 v[92:95], v[150:153], v[204:207], v[92:95]
	v_mfma_f32_16x16x32_bf16 v[88:91], v[174:177], v[204:207], v[88:91]
	v_mfma_f32_16x16x32_bf16 v[76:79], v[150:153], v[212:215], v[76:79]
	v_mfma_f32_16x16x32_bf16 v[72:75], v[174:177], v[212:215], v[72:75]
	s_barrier
	s_add_i32 s28, s63, s13
	v_lshl_add_u64 v[158:159], s[50:51], 0, v[132:133]
	s_mov_b32 m0, s28
	ds_read_b128 v[216:219], v172
	ds_read_b128 v[220:223], v172 offset:1024
	ds_read_b128 v[224:227], v172 offset:2048
	ds_read_b128 v[228:231], v172 offset:3072
	global_load_lds_dwordx4 v[158:159], off
	v_lshl_add_u64 v[164:165], s[50:51], 0, v[128:129]
	s_add_i32 m0, s28, 0x2000
	s_nop 0
	global_load_lds_dwordx4 v[164:165], off
	s_barrier
	s_waitcnt lgkmcnt(0)
	v_mfma_f32_16x16x32_bf16 v[116:119], v[216:219], v[178:181], v[116:119]
	v_mfma_f32_16x16x32_bf16 v[112:115], v[224:227], v[178:181], v[112:115]
	v_mfma_f32_16x16x32_bf16 v[100:103], v[216:219], v[186:189], v[100:103]
	v_mfma_f32_16x16x32_bf16 v[96:99], v[224:227], v[186:189], v[96:99]
	v_mfma_f32_16x16x32_bf16 v[84:87], v[216:219], v[200:203], v[84:87]
	v_mfma_f32_16x16x32_bf16 v[80:83], v[224:227], v[200:203], v[80:83]
	v_mfma_f32_16x16x32_bf16 v[68:71], v[216:219], v[208:211], v[68:71]
	v_mfma_f32_16x16x32_bf16 v[64:67], v[224:227], v[208:211], v[64:67]
	v_mfma_f32_16x16x32_bf16 v[116:119], v[220:223], v[182:185], v[116:119]
	v_mfma_f32_16x16x32_bf16 v[112:115], v[228:231], v[182:185], v[112:115]
	v_mfma_f32_16x16x32_bf16 v[100:103], v[220:223], v[196:199], v[100:103]
	v_mfma_f32_16x16x32_bf16 v[96:99], v[228:231], v[196:199], v[96:99]
	v_mfma_f32_16x16x32_bf16 v[84:87], v[220:223], v[204:207], v[84:87]
	v_mfma_f32_16x16x32_bf16 v[80:83], v[228:231], v[204:207], v[80:83]
	v_mfma_f32_16x16x32_bf16 v[68:71], v[220:223], v[212:215], v[68:71]
	v_mfma_f32_16x16x32_bf16 v[64:67], v[228:231], v[212:215], v[64:67]
	s_barrier
	s_mov_b32 m0, s54
	v_lshl_add_u64 v[190:191], s[52:53], 0, v[134:135]
	ds_read_b128 v[178:181], v171 offset:16384
	ds_read_b128 v[182:185], v171 offset:17408
	ds_read_b128 v[186:189], v171 offset:18432
	ds_read_b128 v[196:199], v171 offset:19456
	ds_read_b128 v[200:203], v171 offset:20480
	ds_read_b128 v[204:207], v171 offset:21504
	ds_read_b128 v[208:211], v171 offset:22528
	ds_read_b128 v[212:215], v171 offset:23552
	global_load_lds_dwordx4 v[190:191], off
	v_lshl_add_u64 v[232:233], s[52:53], 0, v[130:131]
	s_mov_b32 m0, s55
	s_nop 0
	global_load_lds_dwordx4 v[232:233], off
	s_barrier
	s_waitcnt lgkmcnt(0)
	v_mfma_f32_16x16x32_bf16 v[60:63], v[146:149], v[178:181], v[60:63]
	v_mfma_f32_16x16x32_bf16 v[56:59], v[154:157], v[178:181], v[56:59]
	v_mfma_f32_16x16x32_bf16 v[44:47], v[146:149], v[186:189], v[44:47]
	v_mfma_f32_16x16x32_bf16 v[40:43], v[154:157], v[186:189], v[40:43]
	v_mfma_f32_16x16x32_bf16 v[28:31], v[146:149], v[200:203], v[28:31]
	v_mfma_f32_16x16x32_bf16 v[24:27], v[154:157], v[200:203], v[24:27]
	v_mfma_f32_16x16x32_bf16 v[12:15], v[146:149], v[208:211], v[12:15]
	v_mfma_f32_16x16x32_bf16 v[8:11], v[154:157], v[208:211], v[8:11]
	v_mfma_f32_16x16x32_bf16 v[60:63], v[150:153], v[182:185], v[60:63]
	v_mfma_f32_16x16x32_bf16 v[56:59], v[174:177], v[182:185], v[56:59]
	v_mfma_f32_16x16x32_bf16 v[44:47], v[150:153], v[196:199], v[44:47]
	v_mfma_f32_16x16x32_bf16 v[40:43], v[174:177], v[196:199], v[40:43]
	v_mfma_f32_16x16x32_bf16 v[28:31], v[150:153], v[204:207], v[28:31]
	v_mfma_f32_16x16x32_bf16 v[24:27], v[174:177], v[204:207], v[24:27]
	v_mfma_f32_16x16x32_bf16 v[12:15], v[150:153], v[212:215], v[12:15]
	v_mfma_f32_16x16x32_bf16 v[8:11], v[174:177], v[212:215], v[8:11]
	s_barrier
	s_add_u32 s80, s50, 0x10000
	s_addc_u32 s81, s51, 0
	s_add_i32 s28, s64, s13
	v_lshl_add_u64 v[146:147], s[80:81], 0, v[132:133]
	s_mov_b32 m0, s28
	s_nop 0
	global_load_lds_dwordx4 v[146:147], off
	v_lshl_add_u64 v[146:147], s[80:81], 0, v[128:129]
	s_add_i32 m0, s28, 0x2000
	s_nop 0
	global_load_lds_dwordx4 v[146:147], off
	s_waitcnt vmcnt(6)
	s_barrier
	v_mfma_f32_16x16x32_bf16 v[52:55], v[216:219], v[178:181], v[52:55]
	v_mfma_f32_16x16x32_bf16 v[48:51], v[224:227], v[178:181], v[48:51]
	v_mfma_f32_16x16x32_bf16 v[36:39], v[216:219], v[186:189], v[36:39]
	v_mfma_f32_16x16x32_bf16 v[32:35], v[224:227], v[186:189], v[32:35]
	v_mfma_f32_16x16x32_bf16 v[20:23], v[216:219], v[200:203], v[20:23]
	v_mfma_f32_16x16x32_bf16 v[16:19], v[224:227], v[200:203], v[16:19]
	v_mfma_f32_16x16x32_bf16 v[4:7], v[216:219], v[208:211], v[4:7]
	v_mfma_f32_16x16x32_bf16 v[0:3], v[224:227], v[208:211], v[0:3]
	v_mfma_f32_16x16x32_bf16 v[52:55], v[220:223], v[182:185], v[52:55]
	v_mfma_f32_16x16x32_bf16 v[48:51], v[228:231], v[182:185], v[48:51]
	v_mfma_f32_16x16x32_bf16 v[36:39], v[220:223], v[196:199], v[36:39]
	v_mfma_f32_16x16x32_bf16 v[32:35], v[228:231], v[196:199], v[32:35]
	v_mfma_f32_16x16x32_bf16 v[20:23], v[220:223], v[204:207], v[20:23]
	v_mfma_f32_16x16x32_bf16 v[16:19], v[228:231], v[204:207], v[16:19]
	v_mfma_f32_16x16x32_bf16 v[4:7], v[220:223], v[212:215], v[4:7]
	v_mfma_f32_16x16x32_bf16 v[0:3], v[228:231], v[212:215], v[0:3]
	s_barrier
	s_add_i32 s28, 0, 0x18000
	v_add_u32_e32 v160, s28, v163
	ds_read_b128 v[146:149], v160
	ds_read_b128 v[150:153], v160 offset:1024
	ds_read_b128 v[154:157], v160 offset:2048
	ds_read_b128 v[174:177], v160 offset:3072
	s_add_u32 s52, s52, 0x40000
	s_addc_u32 s53, s53, 0
	s_mov_b32 m0, s56
	v_lshl_add_u64 v[216:217], s[52:53], 0, v[134:135]
	ds_read_b128 v[178:181], v171 offset:32768
	ds_read_b128 v[182:185], v171 offset:33792
	ds_read_b128 v[186:189], v171 offset:34816
	ds_read_b128 v[196:199], v171 offset:35840
	ds_read_b128 v[200:203], v171 offset:36864
	ds_read_b128 v[204:207], v171 offset:37888
	ds_read_b128 v[208:211], v171 offset:38912
	ds_read_b128 v[212:215], v171 offset:39936
	global_load_lds_dwordx4 v[216:217], off
	v_lshl_add_u64 v[216:217], s[52:53], 0, v[130:131]
	s_mov_b32 m0, s57
	s_nop 0
	global_load_lds_dwordx4 v[216:217], off
	s_waitcnt lgkmcnt(8)
	s_barrier
	s_waitcnt lgkmcnt(0)
	v_mfma_f32_16x16x32_bf16 v[124:127], v[146:149], v[178:181], v[124:127]
	v_mfma_f32_16x16x32_bf16 v[120:123], v[154:157], v[178:181], v[120:123]
	v_mfma_f32_16x16x32_bf16 v[108:111], v[146:149], v[186:189], v[108:111]
	v_mfma_f32_16x16x32_bf16 v[104:107], v[154:157], v[186:189], v[104:107]
	v_mfma_f32_16x16x32_bf16 v[92:95], v[146:149], v[200:203], v[92:95]
	v_mfma_f32_16x16x32_bf16 v[88:91], v[154:157], v[200:203], v[88:91]
	v_mfma_f32_16x16x32_bf16 v[76:79], v[146:149], v[208:211], v[76:79]
	v_mfma_f32_16x16x32_bf16 v[72:75], v[154:157], v[208:211], v[72:75]
	v_mfma_f32_16x16x32_bf16 v[124:127], v[150:153], v[182:185], v[124:127]
	v_mfma_f32_16x16x32_bf16 v[120:123], v[174:177], v[182:185], v[120:123]
	v_mfma_f32_16x16x32_bf16 v[108:111], v[150:153], v[196:199], v[108:111]
	v_mfma_f32_16x16x32_bf16 v[104:107], v[174:177], v[196:199], v[104:107]
	v_mfma_f32_16x16x32_bf16 v[92:95], v[150:153], v[204:207], v[92:95]
	v_mfma_f32_16x16x32_bf16 v[88:91], v[174:177], v[204:207], v[88:91]
	v_mfma_f32_16x16x32_bf16 v[76:79], v[150:153], v[212:215], v[76:79]
	v_mfma_f32_16x16x32_bf16 v[72:75], v[174:177], v[212:215], v[72:75]
	s_barrier
	s_add_i32 s29, 0, 0x1c000
	s_add_i32 s28, s28, s13
	v_add_u32_e32 v160, s29, v163
	v_lshl_add_u64 v[158:159], v[158:159], 0, s[8:9]
	s_mov_b32 m0, s28
	ds_read_b128 v[216:219], v160
	ds_read_b128 v[220:223], v160 offset:1024
	ds_read_b128 v[224:227], v160 offset:2048
	ds_read_b128 v[228:231], v160 offset:3072
	global_load_lds_dwordx4 v[158:159], off
	v_lshl_add_u64 v[158:159], v[164:165], 0, s[8:9]
	s_add_i32 m0, s28, 0x2000
	s_nop 0
	global_load_lds_dwordx4 v[158:159], off
	s_barrier
	s_waitcnt lgkmcnt(0)
	v_mfma_f32_16x16x32_bf16 v[116:119], v[216:219], v[178:181], v[116:119]
	v_mfma_f32_16x16x32_bf16 v[112:115], v[224:227], v[178:181], v[112:115]
	v_mfma_f32_16x16x32_bf16 v[100:103], v[216:219], v[186:189], v[100:103]
	v_mfma_f32_16x16x32_bf16 v[96:99], v[224:227], v[186:189], v[96:99]
	v_mfma_f32_16x16x32_bf16 v[84:87], v[216:219], v[200:203], v[84:87]
	v_mfma_f32_16x16x32_bf16 v[80:83], v[224:227], v[200:203], v[80:83]
	v_mfma_f32_16x16x32_bf16 v[68:71], v[216:219], v[208:211], v[68:71]
	v_mfma_f32_16x16x32_bf16 v[64:67], v[224:227], v[208:211], v[64:67]
	v_mfma_f32_16x16x32_bf16 v[116:119], v[220:223], v[182:185], v[116:119]
	v_mfma_f32_16x16x32_bf16 v[112:115], v[228:231], v[182:185], v[112:115]
	v_mfma_f32_16x16x32_bf16 v[100:103], v[220:223], v[196:199], v[100:103]
	v_mfma_f32_16x16x32_bf16 v[96:99], v[228:231], v[196:199], v[96:99]
	v_mfma_f32_16x16x32_bf16 v[84:87], v[220:223], v[204:207], v[84:87]
	v_mfma_f32_16x16x32_bf16 v[80:83], v[228:231], v[204:207], v[80:83]
	v_mfma_f32_16x16x32_bf16 v[68:71], v[220:223], v[212:215], v[68:71]
	v_mfma_f32_16x16x32_bf16 v[64:67], v[228:231], v[212:215], v[64:67]
	s_barrier
	s_mov_b32 m0, s60
	v_lshl_add_u64 v[158:159], v[190:191], 0, s[8:9]
	ds_read_b128 v[178:181], v171 offset:49152
	ds_read_b128 v[182:185], v171 offset:50176
	ds_read_b128 v[186:189], v171 offset:51200
	ds_read_b128 v[196:199], v171 offset:52224
	ds_read_b128 v[200:203], v171 offset:53248
	ds_read_b128 v[204:207], v171 offset:54272
	ds_read_b128 v[208:211], v171 offset:55296
	ds_read_b128 v[212:215], v171 offset:56320
	global_load_lds_dwordx4 v[158:159], off
	v_lshl_add_u64 v[158:159], v[232:233], 0, s[8:9]
	s_mov_b32 m0, s61
	s_nop 0
	global_load_lds_dwordx4 v[158:159], off
	s_barrier
	s_waitcnt lgkmcnt(0)
	v_mfma_f32_16x16x32_bf16 v[60:63], v[146:149], v[178:181], v[60:63]
	v_mfma_f32_16x16x32_bf16 v[56:59], v[154:157], v[178:181], v[56:59]
	v_mfma_f32_16x16x32_bf16 v[44:47], v[146:149], v[186:189], v[44:47]
	v_mfma_f32_16x16x32_bf16 v[40:43], v[154:157], v[186:189], v[40:43]
	v_mfma_f32_16x16x32_bf16 v[28:31], v[146:149], v[200:203], v[28:31]
	v_mfma_f32_16x16x32_bf16 v[24:27], v[154:157], v[200:203], v[24:27]
	v_mfma_f32_16x16x32_bf16 v[12:15], v[146:149], v[208:211], v[12:15]
	v_mfma_f32_16x16x32_bf16 v[8:11], v[154:157], v[208:211], v[8:11]
	v_mfma_f32_16x16x32_bf16 v[60:63], v[150:153], v[182:185], v[60:63]
	v_mfma_f32_16x16x32_bf16 v[56:59], v[174:177], v[182:185], v[56:59]
	v_mfma_f32_16x16x32_bf16 v[44:47], v[150:153], v[196:199], v[44:47]
	v_mfma_f32_16x16x32_bf16 v[40:43], v[174:177], v[196:199], v[40:43]
	v_mfma_f32_16x16x32_bf16 v[28:31], v[150:153], v[204:207], v[28:31]
	v_mfma_f32_16x16x32_bf16 v[24:27], v[174:177], v[204:207], v[24:27]
	v_mfma_f32_16x16x32_bf16 v[12:15], v[150:153], v[212:215], v[12:15]
	v_mfma_f32_16x16x32_bf16 v[8:11], v[174:177], v[212:215], v[8:11]
	s_barrier
	s_add_u32 s50, s50, 0x10080
	s_addc_u32 s51, s51, 0
	s_add_i32 s28, s29, s13
	v_lshl_add_u64 v[146:147], s[50:51], 0, v[132:133]
	s_mov_b32 m0, s28
	s_nop 0
	global_load_lds_dwordx4 v[146:147], off
	v_lshl_add_u64 v[146:147], s[50:51], 0, v[128:129]
	s_add_i32 m0, s28, 0x2000
	s_nop 0
	global_load_lds_dwordx4 v[146:147], off
	s_add_i32 s78, s78, 2
	s_add_u32 s0, s0, 0x100
	s_addc_u32 s1, s1, 0
	s_add_u32 s76, s76, 0x100
	s_addc_u32 s77, s77, 0
	s_cmp_gt_u32 s78, 13
	s_waitcnt vmcnt(6)
	s_barrier
	v_mfma_f32_16x16x32_bf16 v[52:55], v[216:219], v[178:181], v[52:55]
	v_mfma_f32_16x16x32_bf16 v[48:51], v[224:227], v[178:181], v[48:51]
	v_mfma_f32_16x16x32_bf16 v[36:39], v[216:219], v[186:189], v[36:39]
	v_mfma_f32_16x16x32_bf16 v[32:35], v[224:227], v[186:189], v[32:35]
	v_mfma_f32_16x16x32_bf16 v[20:23], v[216:219], v[200:203], v[20:23]
	v_mfma_f32_16x16x32_bf16 v[16:19], v[224:227], v[200:203], v[16:19]
	v_mfma_f32_16x16x32_bf16 v[4:7], v[216:219], v[208:211], v[4:7]
	v_mfma_f32_16x16x32_bf16 v[0:3], v[224:227], v[208:211], v[0:3]
	v_mfma_f32_16x16x32_bf16 v[52:55], v[220:223], v[182:185], v[52:55]
	v_mfma_f32_16x16x32_bf16 v[48:51], v[228:231], v[182:185], v[48:51]
	v_mfma_f32_16x16x32_bf16 v[36:39], v[220:223], v[196:199], v[36:39]
	v_mfma_f32_16x16x32_bf16 v[32:35], v[228:231], v[196:199], v[32:35]
	v_mfma_f32_16x16x32_bf16 v[20:23], v[220:223], v[204:207], v[20:23]
	v_mfma_f32_16x16x32_bf16 v[16:19], v[228:231], v[204:207], v[16:19]
	v_mfma_f32_16x16x32_bf16 v[4:7], v[220:223], v[212:215], v[4:7]
	v_mfma_f32_16x16x32_bf16 v[0:3], v[228:231], v[212:215], v[0:3]
	s_barrier
	s_cbranch_scc0 .LBB0_904
	v_lshl_add_u32 v146, s6, 8, v161
	v_or_b32_e32 v164, 16, v146
	v_ashrrev_i32_e32 v165, 31, v164
	v_lshlrev_b64 v[148:149], 6, v[164:165]
	v_or_b32_e32 v158, 32, v146
	v_lshl_add_u64 v[148:149], v[136:137], 0, v[148:149]
	v_ashrrev_i32_e32 v159, 31, v158
	v_or_b32_e32 v156, 48, v146
	global_load_dwordx4 v[174:177], v[148:149], off
	v_lshlrev_b64 v[148:149], 6, v[158:159]
	v_ashrrev_i32_e32 v157, 31, v156
	v_add_u32_e32 v154, 0x80, v146
	v_lshl_add_u64 v[148:149], v[136:137], 0, v[148:149]
	v_lshlrev_b64 v[150:151], 6, v[156:157]
	v_ashrrev_i32_e32 v155, 31, v154
	v_lshl_add_u64 v[150:151], v[136:137], 0, v[150:151]
	global_load_dwordx4 v[178:181], v[148:149], off
	global_load_dwordx4 v[182:185], v[150:151], off
	v_lshlrev_b64 v[148:149], 6, v[154:155]
	v_lshl_add_u64 v[148:149], v[136:137], 0, v[148:149]
	global_load_dwordx4 v[186:189], v[148:149], off
	v_ashrrev_i32_e32 v147, 31, v146
	v_lshlrev_b64 v[148:149], 6, v[146:147]
	v_add_u32_e32 v152, 0x90, v146
	v_lshl_add_u64 v[148:149], v[136:137], 0, v[148:149]
	v_ashrrev_i32_e32 v153, 31, v152
	global_load_dwordx4 v[196:199], v[148:149], off
	v_lshlrev_b64 v[148:149], 6, v[152:153]
	v_lshl_add_u64 v[148:149], v[136:137], 0, v[148:149]
	global_load_dwordx4 v[200:203], v[148:149], off
	v_add_u32_e32 v148, 0xa0, v146
	v_ashrrev_i32_e32 v149, 31, v148
	v_lshlrev_b64 v[150:151], 6, v[148:149]
	v_lshl_add_u64 v[150:151], v[136:137], 0, v[150:151]
	global_load_dwordx4 v[204:207], v[150:151], off
	v_add_u32_e32 v150, 0xb0, v146
	v_ashrrev_i32_e32 v151, 31, v150
	v_lshlrev_b64 v[208:209], 6, v[150:151]
	v_lshl_add_u64 v[208:209], v[136:137], 0, v[208:209]
	global_load_dwordx4 v[208:211], v[208:209], off
	v_and_b32_e32 v149, 64, v173
	v_xor_b32_e32 v147, 16, v173
	v_add_u32_e32 v149, 64, v149
	v_cmp_lt_i32_e32 vcc, v147, v149
	v_xor_b32_e32 v153, 32, v173
	v_mov_b64_e32 v[190:191], s[12:13]
	v_cndmask_b32_e32 v147, v173, v147, vcc
	v_lshlrev_b32_e32 v147, 2, v147
	v_cmp_lt_i32_e32 vcc, v153, v149
	s_waitcnt vmcnt(0)
	v_mov_b32_e32 v212, v175
	v_mov_b32_e32 v213, v176
	v_mov_b32_e32 v175, v177
	v_pk_add_f32 v[174:175], v[212:213], v[174:175]
	v_cndmask_b32_e32 v149, v173, v153, vcc
	v_lshlrev_b32_e32 v149, 2, v149
	v_mov_b32_e32 v176, v179
	v_mov_b32_e32 v177, v180
	v_mov_b32_e32 v179, v181
	v_mov_b32_e32 v180, v183
	v_mov_b32_e32 v181, v184
	v_mov_b32_e32 v183, v185
	v_mov_b32_e32 v184, v187
	v_mov_b32_e32 v185, v188
	v_mov_b32_e32 v187, v189
	v_pk_add_f32 v[176:177], v[176:177], v[178:179]
	v_pk_add_f32 v[178:179], v[180:181], v[182:183]
	v_pk_add_f32 v[180:181], v[184:185], v[186:187]
	v_mov_b32_e32 v182, v176
	v_mov_b32_e32 v183, v174
	v_mov_b32_e32 v174, v177
	v_mov_b32_e32 v176, v180
	v_mov_b32_e32 v177, v178
	v_mov_b32_e32 v178, v181
	v_pk_add_f32 v[174:175], v[182:183], v[174:175]
	v_pk_add_f32 v[176:177], v[176:177], v[178:179]
	ds_bpermute_b32 v179, v147, v175
	ds_bpermute_b32 v178, v147, v174
	ds_bpermute_b32 v181, v147, v177
	ds_bpermute_b32 v180, v147, v176
	v_mov_b32_e32 v184, v201
	v_mov_b32_e32 v185, v202
	s_waitcnt lgkmcnt(0)
	v_pk_add_f32 v[174:175], v[174:175], v[178:179]
	ds_bpermute_b32 v179, v149, v175
	v_pk_add_f32 v[176:177], v[176:177], v[180:181]
	ds_bpermute_b32 v178, v149, v174
	ds_bpermute_b32 v181, v149, v177
	ds_bpermute_b32 v180, v149, v176
	v_mov_b32_e32 v201, v203
	v_mov_b32_e32 v182, v197
	s_waitcnt lgkmcnt(2)
	v_pk_add_f32 v[174:175], v[174:175], v[178:179]
	v_pk_add_f32 v[178:179], v[184:185], v[200:201]
	s_waitcnt lgkmcnt(0)
	v_pk_add_f32 v[176:177], v[176:177], v[180:181]
	v_pk_fma_f32 v[174:175], v[174:175], s[10:11], v[190:191] op_sel_hi:[1,0,0]
	v_mov_b32_e32 v180, v205
	v_mov_b32_e32 v181, v206
	v_mov_b32_e32 v205, v207
	v_mul_f32_e32 v151, 0x4b800000, v175
	v_cmp_gt_f32_e32 vcc, s65, v175
	v_pk_add_f32 v[180:181], v[180:181], v[204:205]
	v_mov_b32_e32 v185, v178
	v_cndmask_b32_e32 v151, v175, v151, vcc
	v_mov_b32_e32 v184, v180
	v_mov_b32_e32 v178, v181
	v_rsq_f32_e32 v151, v151
	v_pk_add_f32 v[178:179], v[184:185], v[178:179]
	ds_bpermute_b32 v181, v147, v179
	ds_bpermute_b32 v180, v147, v178
	v_pk_fma_f32 v[176:177], v[176:177], s[10:11], v[190:191] op_sel_hi:[1,0,0]
	v_mul_f32_e32 v153, 0x4b800000, v174
	v_cmp_gt_f32_e64 s[0:1], s65, v174
	v_mul_f32_e32 v157, 0x45800000, v151
	v_mul_f32_e32 v155, 0x4b800000, v177
	v_cndmask_b32_e64 v153, v174, v153, s[0:1]
	v_cmp_gt_f32_e64 s[6:7], s65, v177
	v_cndmask_b32_e32 v174, v151, v157, vcc
	v_mul_f32_e32 v151, 0x4b800000, v176
	v_cmp_gt_f32_e32 vcc, s65, v176
	v_cndmask_b32_e64 v155, v177, v155, s[6:7]
	v_rsq_f32_e32 v153, v153
	v_cndmask_b32_e32 v151, v176, v151, vcc
	s_waitcnt lgkmcnt(0)
	v_pk_add_f32 v[176:177], v[178:179], v[180:181]
	ds_bpermute_b32 v179, v149, v177
	ds_bpermute_b32 v178, v149, v176
	v_rsq_f32_e32 v155, v155
	v_mul_f32_e32 v159, 0x45800000, v153
	v_cndmask_b32_e64 v180, v153, v159, s[0:1]
	v_rsq_f32_e32 v151, v151
	s_waitcnt lgkmcnt(0)
	v_pk_add_f32 v[176:177], v[176:177], v[178:179]
	v_mul_f32_e32 v153, 0x45800000, v155
	v_pk_fma_f32 v[176:177], v[176:177], s[10:11], v[190:191] op_sel_hi:[1,0,0]
	v_cndmask_b32_e64 v170, v155, v153, s[6:7]
	v_mul_f32_e32 v155, 0x4b800000, v177
	v_cmp_gt_f32_e64 s[0:1], s65, v177
	v_mul_f32_e32 v157, 0x4b800000, v176
	v_cmp_gt_f32_e64 s[6:7], s65, v176
	v_cndmask_b32_e64 v155, v177, v155, s[0:1]
	v_rsq_f32_e32 v155, v155
	v_cndmask_b32_e64 v157, v176, v157, s[6:7]
	v_rsq_f32_e32 v157, v157
	v_mul_f32_e32 v153, 0x45800000, v151
	v_cndmask_b32_e32 v168, v151, v153, vcc
	v_mul_f32_e32 v151, 0x45800000, v155
	v_mov_b32_e32 v183, v198
	v_mov_b32_e32 v197, v199
	v_cndmask_b32_e64 v166, v155, v151, s[0:1]
	v_mul_f32_e32 v151, 0x45800000, v157
	v_mov_b32_e32 v176, v209
	v_mov_b32_e32 v177, v210
	v_mov_b32_e32 v209, v211
	v_pk_add_f32 v[182:183], v[182:183], v[196:197]
	v_cndmask_b32_e64 v162, v157, v151, s[6:7]
	v_pk_add_f32 v[176:177], v[176:177], v[208:209]
	v_mov_b32_e32 v178, v182
	v_mov_b32_e32 v179, v176
	v_mov_b32_e32 v176, v183
	v_pk_add_f32 v[176:177], v[178:179], v[176:177]
	ds_bpermute_b32 v178, v147, v176
	ds_bpermute_b32 v179, v147, v177
	v_lshl_or_b32 v182, s66, 8, v167
	v_pk_mul_f32 v[100:101], v[100:101], v[174:175] op_sel_hi:[1,0]
	v_pk_mul_f32 v[108:109], v[108:109], v[174:175] op_sel_hi:[1,0]
	v_ashrrev_i32_e32 v183, 31, v182
	s_waitcnt lgkmcnt(0)
	v_pk_add_f32 v[176:177], v[176:177], v[178:179]
	ds_bpermute_b32 v178, v149, v176
	ds_bpermute_b32 v179, v149, v177
	v_pk_mul_f32 v[96:97], v[96:97], v[174:175] op_sel_hi:[1,0]
	v_pk_mul_f32 v[102:103], v[102:103], v[174:175] op_sel_hi:[1,0]
	v_pk_mul_f32 v[110:111], v[110:111], v[174:175] op_sel_hi:[1,0]
	v_cvt_pk_bf16_f32 v108, v108, v109
	s_waitcnt lgkmcnt(0)
	v_pk_add_f32 v[176:177], v[176:177], v[178:179]
	v_pk_mul_f32 v[106:107], v[106:107], v[174:175] op_sel_hi:[1,0]
	v_pk_fma_f32 v[176:177], v[176:177], s[10:11], v[190:191] op_sel_hi:[1,0,0]
	v_pk_mul_f32 v[104:105], v[104:105], v[174:175] op_sel_hi:[1,0]
	v_mul_f32_e32 v147, 0x4b800000, v177
	v_cmp_gt_f32_e32 vcc, s65, v177
	v_mul_f32_e32 v149, 0x4b800000, v176
	v_cmp_gt_f32_e64 s[0:1], s65, v176
	v_cndmask_b32_e32 v147, v177, v147, vcc
	v_rsq_f32_e32 v147, v147
	v_cndmask_b32_e64 v149, v176, v149, s[0:1]
	v_rsq_f32_e32 v149, v149
	v_cvt_pk_bf16_f32 v100, v100, v101
	v_mul_f32_e32 v151, 0x45800000, v147
	v_cndmask_b32_e32 v160, v147, v151, vcc
	v_mul_f32_e32 v147, 0x45800000, v149
	v_cndmask_b32_e64 v176, v149, v147, s[0:1]
	v_pk_mul_f32 v[112:113], v[112:113], v[176:177] op_sel_hi:[1,0]
	v_pk_mul_f32 v[116:117], v[116:117], v[176:177] op_sel_hi:[1,0]
	v_pk_mul_f32 v[124:125], v[124:125], v[176:177] op_sel_hi:[1,0]
	v_pk_mul_f32 v[122:123], v[122:123], v[176:177] op_sel_hi:[1,0]
	v_pk_mul_f32 v[120:121], v[120:121], v[176:177] op_sel_hi:[1,0]
	v_pk_mul_f32 v[114:115], v[114:115], v[176:177] op_sel_hi:[1,0]
	v_pk_mul_f32 v[118:119], v[118:119], v[176:177] op_sel_hi:[1,0]
	v_pk_mul_f32 v[126:127], v[126:127], v[176:177] op_sel_hi:[1,0]
	v_cvt_pk_bf16_f32 v124, v124, v125
	v_cvt_pk_bf16_f32 v120, v120, v121
	v_cvt_pk_bf16_f32 v121, v122, v123
	v_cvt_pk_bf16_f32 v122, v116, v117
	v_cvt_pk_bf16_f32 v112, v112, v113
	v_cvt_pk_bf16_f32 v125, v126, v127
	v_cvt_pk_bf16_f32 v118, v118, v119
	v_cvt_pk_bf16_f32 v113, v114, v115
	v_cndmask_b32_e64 v114, v124, v122, s[2:3]
	v_mov_b32_e32 v123, 0
	v_cndmask_b32_e64 v115, v120, v112, s[2:3]
	v_mov_b32_e32 v126, 0
	v_mov_b32_dpp v123, v114 row_ror:8 row_mask:0xf bank_mask:0xf
	v_cndmask_b32_e64 v114, v125, v118, s[2:3]
	v_mov_b32_e32 v119, 0
	v_mov_b32_dpp v126, v115 row_ror:8 row_mask:0xf bank_mask:0xf
	v_mov_b32_e32 v127, 0
	v_mov_b32_dpp v119, v114 row_ror:8 row_mask:0xf bank_mask:0xf
	v_cndmask_b32_e64 v114, v121, v113, s[2:3]
	v_cndmask_b32_e64 v116, v126, v120, s[2:3]
	v_cndmask_b32_e64 v120, v112, v126, s[2:3]
	v_add_u32_e32 v112, -8, v146
	v_mov_b32_dpp v127, v114 row_ror:8 row_mask:0xf bank_mask:0xf
	v_cndmask_b32_e64 v112, v112, v146, s[2:3]
	v_cndmask_b32_e64 v117, v127, v121, s[2:3]
	v_cndmask_b32_e64 v121, v113, v127, s[2:3]
	v_ashrrev_i32_e32 v113, 31, v112
	v_lshlrev_b64 v[112:113], 10, v[112:113]
	v_cndmask_b32_e64 v115, v119, v125, s[2:3]
	v_cndmask_b32_e64 v114, v123, v124, s[2:3]
	v_cndmask_b32_e64 v119, v118, v119, s[2:3]
	v_cndmask_b32_e64 v118, v122, v123, s[2:3]
	v_lshl_add_u64 v[122:123], s[38:39], 0, v[112:113]
	v_lshlrev_b64 v[112:113], 1, v[182:183]
	v_pk_mul_f32 v[98:99], v[98:99], v[174:175] op_sel_hi:[1,0]
	v_cvt_pk_bf16_f32 v109, v110, v111
	v_cvt_pk_bf16_f32 v104, v104, v105
	v_cvt_pk_bf16_f32 v105, v106, v107
	v_cvt_pk_bf16_f32 v101, v102, v103
	v_cvt_pk_bf16_f32 v102, v96, v97
	v_cndmask_b32_e64 v96, v108, v100, s[2:3]
	v_mov_b32_e32 v106, 0
	v_lshl_add_u64 v[122:123], v[122:123], 0, v[112:113]
	v_cvt_pk_bf16_f32 v103, v98, v99
	v_mov_b32_dpp v106, v96 row_ror:8 row_mask:0xf bank_mask:0xf
	v_cndmask_b32_e64 v96, v109, v101, s[2:3]
	v_mov_b32_e32 v107, 0
	v_cndmask_b32_e64 v97, v104, v102, s[2:3]
	v_mov_b32_e32 v110, 0
	global_store_dwordx4 v[122:123], v[114:117], off
	v_mov_b32_dpp v107, v96 row_ror:8 row_mask:0xf bank_mask:0xf
	v_cndmask_b32_e64 v96, v105, v103, s[2:3]
	v_add_u32_e32 v116, 8, v146
	v_mov_b32_dpp v110, v97 row_ror:8 row_mask:0xf bank_mask:0xf
	v_mov_b32_e32 v111, 0
	v_cndmask_b32_e64 v114, v146, v116, s[2:3]
	v_cndmask_b32_e64 v98, v110, v104, s[2:3]
	v_mov_b32_dpp v111, v96 row_ror:8 row_mask:0xf bank_mask:0xf
	v_cndmask_b32_e64 v104, v116, v164, s[2:3]
	v_ashrrev_i32_e32 v115, 31, v114
	v_cndmask_b32_e64 v99, v111, v105, s[2:3]
	v_ashrrev_i32_e32 v105, 31, v104
	v_pk_mul_f32 v[84:85], v[84:85], v[180:181] op_sel_hi:[1,0]
	v_pk_mul_f32 v[92:93], v[92:93], v[180:181] op_sel_hi:[1,0]
	v_lshlrev_b64 v[114:115], 10, v[114:115]
	v_lshlrev_b64 v[104:105], 10, v[104:105]
	v_pk_mul_f32 v[80:81], v[80:81], v[180:181] op_sel_hi:[1,0]
	v_pk_mul_f32 v[86:87], v[86:87], v[180:181] op_sel_hi:[1,0]
	v_pk_mul_f32 v[94:95], v[94:95], v[180:181] op_sel_hi:[1,0]
	v_cvt_pk_bf16_f32 v92, v92, v93
	v_pk_mul_f32 v[90:91], v[90:91], v[180:181] op_sel_hi:[1,0]
	v_pk_mul_f32 v[88:89], v[88:89], v[180:181] op_sel_hi:[1,0]
	v_cvt_pk_bf16_f32 v84, v84, v85
	v_lshl_add_u64 v[114:115], s[38:39], 0, v[114:115]
	v_lshl_add_u64 v[104:105], s[38:39], 0, v[104:105]
	v_pk_mul_f32 v[82:83], v[82:83], v[180:181] op_sel_hi:[1,0]
	v_cvt_pk_bf16_f32 v93, v94, v95
	v_cvt_pk_bf16_f32 v88, v88, v89
	v_cvt_pk_bf16_f32 v89, v90, v91
	v_cvt_pk_bf16_f32 v85, v86, v87
	v_cvt_pk_bf16_f32 v86, v80, v81
	v_cndmask_b32_e64 v80, v92, v84, s[2:3]
	v_mov_b32_e32 v90, 0
	v_lshl_add_u64 v[114:115], v[114:115], 0, v[112:113]
	v_cndmask_b32_e64 v97, v107, v109, s[2:3]
	v_cndmask_b32_e64 v96, v106, v108, s[2:3]
	v_lshl_add_u64 v[104:105], v[104:105], 0, v[112:113]
	v_cvt_pk_bf16_f32 v87, v82, v83
	v_mov_b32_dpp v90, v80 row_ror:8 row_mask:0xf bank_mask:0xf
	v_cndmask_b32_e64 v80, v93, v85, s[2:3]
	v_mov_b32_e32 v91, 0
	v_cndmask_b32_e64 v81, v88, v86, s[2:3]
	v_mov_b32_e32 v94, 0
	global_store_dwordx4 v[114:115], v[118:121], off
	global_store_dwordx4 v[104:105], v[96:99], off
	v_mov_b32_dpp v91, v80 row_ror:8 row_mask:0xf bank_mask:0xf
	v_cndmask_b32_e64 v80, v89, v87, s[2:3]
	v_add_u32_e32 v98, 24, v146
	v_mov_b32_dpp v94, v81 row_ror:8 row_mask:0xf bank_mask:0xf
	v_mov_b32_e32 v95, 0
	v_cndmask_b32_e64 v96, v164, v98, s[2:3]
	v_cndmask_b32_e64 v82, v94, v88, s[2:3]
	v_mov_b32_dpp v95, v80 row_ror:8 row_mask:0xf bank_mask:0xf
	v_cndmask_b32_e64 v88, v98, v158, s[2:3]
	v_ashrrev_i32_e32 v97, 31, v96
	v_cndmask_b32_e64 v83, v95, v89, s[2:3]
	v_ashrrev_i32_e32 v89, 31, v88
	v_pk_mul_f32 v[68:69], v[68:69], v[170:171] op_sel_hi:[1,0]
	v_pk_mul_f32 v[76:77], v[76:77], v[170:171] op_sel_hi:[1,0]
	v_lshlrev_b64 v[96:97], 10, v[96:97]
	v_lshlrev_b64 v[88:89], 10, v[88:89]
	v_pk_mul_f32 v[64:65], v[64:65], v[170:171] op_sel_hi:[1,0]
	v_pk_mul_f32 v[70:71], v[70:71], v[170:171] op_sel_hi:[1,0]
	v_pk_mul_f32 v[78:79], v[78:79], v[170:171] op_sel_hi:[1,0]
	v_cvt_pk_bf16_f32 v76, v76, v77
	v_pk_mul_f32 v[74:75], v[74:75], v[170:171] op_sel_hi:[1,0]
	v_pk_mul_f32 v[72:73], v[72:73], v[170:171] op_sel_hi:[1,0]
	v_cvt_pk_bf16_f32 v68, v68, v69
	v_lshl_add_u64 v[96:97], s[38:39], 0, v[96:97]
	v_lshl_add_u64 v[88:89], s[38:39], 0, v[88:89]
	v_pk_mul_f32 v[66:67], v[66:67], v[170:171] op_sel_hi:[1,0]
	v_cvt_pk_bf16_f32 v77, v78, v79
	v_cvt_pk_bf16_f32 v72, v72, v73
	v_cvt_pk_bf16_f32 v73, v74, v75
	v_cvt_pk_bf16_f32 v69, v70, v71
	v_cvt_pk_bf16_f32 v70, v64, v65
	v_cndmask_b32_e64 v64, v76, v68, s[2:3]
	v_mov_b32_e32 v74, 0
	v_cndmask_b32_e64 v103, v103, v111, s[2:3]
	v_cndmask_b32_e64 v102, v102, v110, s[2:3]
	v_cndmask_b32_e64 v101, v101, v107, s[2:3]
	v_cndmask_b32_e64 v100, v100, v106, s[2:3]
	v_lshl_add_u64 v[96:97], v[96:97], 0, v[112:113]
	v_cndmask_b32_e64 v81, v91, v93, s[2:3]
	v_cndmask_b32_e64 v80, v90, v92, s[2:3]
	v_lshl_add_u64 v[88:89], v[88:89], 0, v[112:113]
	v_cvt_pk_bf16_f32 v71, v66, v67
	v_mov_b32_dpp v74, v64 row_ror:8 row_mask:0xf bank_mask:0xf
	v_cndmask_b32_e64 v64, v77, v69, s[2:3]
	v_mov_b32_e32 v75, 0
	v_cndmask_b32_e64 v65, v72, v70, s[2:3]
	v_mov_b32_e32 v78, 0
	global_store_dwordx4 v[96:97], v[100:103], off
	global_store_dwordx4 v[88:89], v[80:83], off
	v_mov_b32_dpp v75, v64 row_ror:8 row_mask:0xf bank_mask:0xf
	v_cndmask_b32_e64 v64, v73, v71, s[2:3]
	v_add_u32_e32 v82, 40, v146
	v_mov_b32_dpp v78, v65 row_ror:8 row_mask:0xf bank_mask:0xf
	v_mov_b32_e32 v79, 0
	v_cndmask_b32_e64 v80, v158, v82, s[2:3]
	v_cndmask_b32_e64 v66, v78, v72, s[2:3]
	v_mov_b32_dpp v79, v64 row_ror:8 row_mask:0xf bank_mask:0xf
	v_cndmask_b32_e64 v72, v82, v156, s[2:3]
	v_ashrrev_i32_e32 v81, 31, v80
	v_cndmask_b32_e64 v67, v79, v73, s[2:3]
	v_ashrrev_i32_e32 v73, 31, v72
	v_pk_mul_f32 v[48:49], v[48:49], v[168:169] op_sel_hi:[1,0]
	v_pk_mul_f32 v[54:55], v[54:55], v[168:169] op_sel_hi:[1,0]
	v_pk_mul_f32 v[52:53], v[52:53], v[168:169] op_sel_hi:[1,0]
	v_pk_mul_f32 v[60:61], v[60:61], v[168:169] op_sel_hi:[1,0]
	v_pk_mul_f32 v[56:57], v[56:57], v[168:169] op_sel_hi:[1,0]
	v_lshlrev_b64 v[80:81], 10, v[80:81]
	v_lshlrev_b64 v[72:73], 10, v[72:73]
	v_pk_mul_f32 v[62:63], v[62:63], v[168:169] op_sel_hi:[1,0]
	v_cvt_pk_bf16_f32 v60, v60, v61
	v_pk_mul_f32 v[58:59], v[58:59], v[168:169] op_sel_hi:[1,0]
	v_cvt_pk_bf16_f32 v56, v56, v57
	v_cvt_pk_bf16_f32 v52, v52, v53
	v_cvt_pk_bf16_f32 v53, v54, v55
	v_cvt_pk_bf16_f32 v54, v48, v49
	v_lshl_add_u64 v[80:81], s[38:39], 0, v[80:81]
	v_lshl_add_u64 v[72:73], s[38:39], 0, v[72:73]
	v_pk_mul_f32 v[50:51], v[50:51], v[168:169] op_sel_hi:[1,0]
	v_cvt_pk_bf16_f32 v61, v62, v63
	v_cvt_pk_bf16_f32 v57, v58, v59
	v_cndmask_b32_e64 v48, v60, v52, s[2:3]
	v_mov_b32_e32 v58, 0
	v_cndmask_b32_e64 v49, v56, v54, s[2:3]
	v_mov_b32_e32 v62, 0
	v_cndmask_b32_e64 v87, v87, v95, s[2:3]
	v_cndmask_b32_e64 v86, v86, v94, s[2:3]
	v_cndmask_b32_e64 v85, v85, v91, s[2:3]
	v_cndmask_b32_e64 v84, v84, v90, s[2:3]
	v_lshl_add_u64 v[80:81], v[80:81], 0, v[112:113]
	v_cndmask_b32_e64 v65, v75, v77, s[2:3]
	v_cndmask_b32_e64 v64, v74, v76, s[2:3]
	v_lshl_add_u64 v[72:73], v[72:73], 0, v[112:113]
	v_cvt_pk_bf16_f32 v55, v50, v51
	v_mov_b32_dpp v58, v48 row_ror:8 row_mask:0xf bank_mask:0xf
	v_cndmask_b32_e64 v48, v61, v53, s[2:3]
	v_mov_b32_e32 v59, 0
	v_mov_b32_dpp v62, v49 row_ror:8 row_mask:0xf bank_mask:0xf
	global_store_dwordx4 v[80:81], v[84:87], off
	global_store_dwordx4 v[72:73], v[64:67], off
	v_mov_b32_dpp v59, v48 row_ror:8 row_mask:0xf bank_mask:0xf
	v_cndmask_b32_e64 v48, v57, v55, s[2:3]
	v_add_u32_e32 v64, 56, v146
	v_mov_b32_e32 v63, 0
	v_cndmask_b32_e64 v50, v62, v56, s[2:3]
	v_add_u32_e32 v56, 0x78, v146
	v_cndmask_b32_e64 v64, v156, v64, s[2:3]
	v_mov_b32_dpp v63, v48 row_ror:8 row_mask:0xf bank_mask:0xf
	v_cndmask_b32_e64 v56, v56, v154, s[2:3]
	v_ashrrev_i32_e32 v65, 31, v64
	v_cndmask_b32_e64 v51, v63, v57, s[2:3]
	v_ashrrev_i32_e32 v57, 31, v56
	v_pk_mul_f32 v[36:37], v[36:37], v[166:167] op_sel_hi:[1,0]
	v_pk_mul_f32 v[44:45], v[44:45], v[166:167] op_sel_hi:[1,0]
	v_lshlrev_b64 v[64:65], 10, v[64:65]
	v_lshlrev_b64 v[56:57], 10, v[56:57]
	v_pk_mul_f32 v[32:33], v[32:33], v[166:167] op_sel_hi:[1,0]
	v_pk_mul_f32 v[38:39], v[38:39], v[166:167] op_sel_hi:[1,0]
	v_pk_mul_f32 v[46:47], v[46:47], v[166:167] op_sel_hi:[1,0]
	v_cvt_pk_bf16_f32 v44, v44, v45
	v_pk_mul_f32 v[42:43], v[42:43], v[166:167] op_sel_hi:[1,0]
	v_pk_mul_f32 v[40:41], v[40:41], v[166:167] op_sel_hi:[1,0]
	v_cvt_pk_bf16_f32 v36, v36, v37
	v_lshl_add_u64 v[64:65], s[38:39], 0, v[64:65]
	v_lshl_add_u64 v[56:57], s[38:39], 0, v[56:57]
	v_pk_mul_f32 v[34:35], v[34:35], v[166:167] op_sel_hi:[1,0]
	v_cvt_pk_bf16_f32 v45, v46, v47
	v_cvt_pk_bf16_f32 v40, v40, v41
	v_cvt_pk_bf16_f32 v41, v42, v43
	v_cvt_pk_bf16_f32 v37, v38, v39
	v_cvt_pk_bf16_f32 v38, v32, v33
	v_cndmask_b32_e64 v32, v44, v36, s[2:3]
	v_mov_b32_e32 v42, 0
	v_cndmask_b32_e64 v71, v71, v79, s[2:3]
	v_cndmask_b32_e64 v70, v70, v78, s[2:3]
	v_cndmask_b32_e64 v69, v69, v75, s[2:3]
	v_cndmask_b32_e64 v68, v68, v74, s[2:3]
	v_lshl_add_u64 v[64:65], v[64:65], 0, v[112:113]
	v_cndmask_b32_e64 v49, v59, v61, s[2:3]
	v_cndmask_b32_e64 v48, v58, v60, s[2:3]
	v_lshl_add_u64 v[56:57], v[56:57], 0, v[112:113]
	v_cvt_pk_bf16_f32 v39, v34, v35
	v_mov_b32_dpp v42, v32 row_ror:8 row_mask:0xf bank_mask:0xf
	v_cndmask_b32_e64 v32, v45, v37, s[2:3]
	v_mov_b32_e32 v43, 0
	v_cndmask_b32_e64 v33, v40, v38, s[2:3]
	v_mov_b32_e32 v46, 0
	global_store_dwordx4 v[64:65], v[68:71], off
	global_store_dwordx4 v[56:57], v[48:51], off
	v_mov_b32_dpp v43, v32 row_ror:8 row_mask:0xf bank_mask:0xf
	v_cndmask_b32_e64 v32, v41, v39, s[2:3]
	v_add_u32_e32 v50, 0x88, v146
	v_mov_b32_dpp v46, v33 row_ror:8 row_mask:0xf bank_mask:0xf
	v_mov_b32_e32 v47, 0
	v_cndmask_b32_e64 v34, v46, v40, s[2:3]
	v_cndmask_b32_e64 v40, v50, v152, s[2:3]
	v_mov_b32_dpp v47, v32 row_ror:8 row_mask:0xf bank_mask:0xf
	v_cndmask_b32_e64 v35, v47, v41, s[2:3]
	v_ashrrev_i32_e32 v41, 31, v40
	v_pk_mul_f32 v[20:21], v[20:21], v[162:163] op_sel_hi:[1,0]
	v_pk_mul_f32 v[28:29], v[28:29], v[162:163] op_sel_hi:[1,0]
	v_lshlrev_b64 v[40:41], 10, v[40:41]
	v_pk_mul_f32 v[16:17], v[16:17], v[162:163] op_sel_hi:[1,0]
	v_pk_mul_f32 v[22:23], v[22:23], v[162:163] op_sel_hi:[1,0]
	v_pk_mul_f32 v[30:31], v[30:31], v[162:163] op_sel_hi:[1,0]
	v_cvt_pk_bf16_f32 v28, v28, v29
	v_pk_mul_f32 v[26:27], v[26:27], v[162:163] op_sel_hi:[1,0]
	v_pk_mul_f32 v[24:25], v[24:25], v[162:163] op_sel_hi:[1,0]
	v_cvt_pk_bf16_f32 v20, v20, v21
	v_lshl_add_u64 v[40:41], s[38:39], 0, v[40:41]
	v_pk_mul_f32 v[18:19], v[18:19], v[162:163] op_sel_hi:[1,0]
	v_cvt_pk_bf16_f32 v29, v30, v31
	v_cvt_pk_bf16_f32 v24, v24, v25
	v_cvt_pk_bf16_f32 v25, v26, v27
	v_cvt_pk_bf16_f32 v21, v22, v23
	v_cvt_pk_bf16_f32 v22, v16, v17
	v_cndmask_b32_e64 v16, v28, v20, s[2:3]
	v_mov_b32_e32 v26, 0
	v_cndmask_b32_e64 v33, v43, v45, s[2:3]
	v_cndmask_b32_e64 v32, v42, v44, s[2:3]
	v_lshl_add_u64 v[40:41], v[40:41], 0, v[112:113]
	v_cvt_pk_bf16_f32 v23, v18, v19
	v_mov_b32_dpp v26, v16 row_ror:8 row_mask:0xf bank_mask:0xf
	v_cndmask_b32_e64 v16, v29, v21, s[2:3]
	v_mov_b32_e32 v27, 0
	v_cndmask_b32_e64 v17, v24, v22, s[2:3]
	v_mov_b32_e32 v30, 0
	global_store_dwordx4 v[40:41], v[32:35], off
	v_mov_b32_dpp v27, v16 row_ror:8 row_mask:0xf bank_mask:0xf
	v_cndmask_b32_e64 v16, v25, v23, s[2:3]
	v_add_u32_e32 v34, 0x98, v146
	v_mov_b32_dpp v30, v17 row_ror:8 row_mask:0xf bank_mask:0xf
	v_mov_b32_e32 v31, 0
	v_cndmask_b32_e64 v18, v30, v24, s[2:3]
	v_cndmask_b32_e64 v24, v34, v148, s[2:3]
	v_mov_b32_dpp v31, v16 row_ror:8 row_mask:0xf bank_mask:0xf
	v_cndmask_b32_e64 v19, v31, v25, s[2:3]
	v_ashrrev_i32_e32 v25, 31, v24
	v_lshlrev_b64 v[24:25], 10, v[24:25]
	v_lshl_add_u64 v[24:25], s[38:39], 0, v[24:25]
	v_cndmask_b32_e64 v17, v27, v29, s[2:3]
	v_cndmask_b32_e64 v16, v26, v28, s[2:3]
	v_lshl_add_u64 v[24:25], v[24:25], 0, v[112:113]
	global_store_dwordx4 v[24:25], v[16:19], off
	v_pk_mul_f32 v[4:5], v[4:5], v[160:161] op_sel_hi:[1,0]
	v_pk_mul_f32 v[12:13], v[12:13], v[160:161] op_sel_hi:[1,0]
	v_add_u32_e32 v18, 0xa8, v146
	v_cndmask_b32_e64 v16, v148, v18, s[2:3]
	v_ashrrev_i32_e32 v17, 31, v16
	v_pk_mul_f32 v[10:11], v[10:11], v[160:161] op_sel_hi:[1,0]
	v_pk_mul_f32 v[8:9], v[8:9], v[160:161] op_sel_hi:[1,0]
	v_lshlrev_b64 v[16:17], 10, v[16:17]
	v_pk_mul_f32 v[0:1], v[0:1], v[160:161] op_sel_hi:[1,0]
	v_pk_mul_f32 v[6:7], v[6:7], v[160:161] op_sel_hi:[1,0]
	v_pk_mul_f32 v[14:15], v[14:15], v[160:161] op_sel_hi:[1,0]
	v_cvt_pk_bf16_f32 v12, v12, v13
	v_cvt_pk_bf16_f32 v8, v8, v9
	v_cvt_pk_bf16_f32 v9, v10, v11
	v_cvt_pk_bf16_f32 v10, v4, v5
	v_lshl_add_u64 v[16:17], s[38:39], 0, v[16:17]
	v_pk_mul_f32 v[2:3], v[2:3], v[160:161] op_sel_hi:[1,0]
	v_cvt_pk_bf16_f32 v13, v14, v15
	v_cvt_pk_bf16_f32 v6, v6, v7
	v_cvt_pk_bf16_f32 v7, v0, v1
	v_cndmask_b32_e64 v0, v12, v10, s[2:3]
	v_mov_b32_e32 v14, 0
	v_cndmask_b32_e64 v4, v18, v150, s[2:3]
	v_cndmask_b32_e64 v23, v23, v31, s[2:3]
	v_cndmask_b32_e64 v22, v22, v30, s[2:3]
	v_cndmask_b32_e64 v21, v21, v27, s[2:3]
	v_cndmask_b32_e64 v20, v20, v26, s[2:3]
	v_lshl_add_u64 v[16:17], v[16:17], 0, v[112:113]
	v_cvt_pk_bf16_f32 v11, v2, v3
	v_mov_b32_dpp v14, v0 row_ror:8 row_mask:0xf bank_mask:0xf
	v_cndmask_b32_e64 v0, v13, v6, s[2:3]
	v_mov_b32_e32 v15, 0
	v_ashrrev_i32_e32 v5, 31, v4
	global_store_dwordx4 v[16:17], v[20:23], off
	v_mov_b32_dpp v15, v0 row_ror:8 row_mask:0xf bank_mask:0xf
	v_cndmask_b32_e64 v0, v9, v11, s[2:3]
	v_cndmask_b32_e64 v1, v8, v7, s[2:3]
	v_mov_b32_e32 v16, 0
	v_mov_b32_e32 v17, 0
	v_lshlrev_b64 v[4:5], 10, v[4:5]
	v_mov_b32_dpp v16, v1 row_ror:8 row_mask:0xf bank_mask:0xf
	v_mov_b32_dpp v17, v0 row_ror:8 row_mask:0xf bank_mask:0xf
	v_lshl_add_u64 v[4:5], s[38:39], 0, v[4:5]
	v_cndmask_b32_e64 v3, v17, v9, s[2:3]
	v_cndmask_b32_e64 v2, v16, v8, s[2:3]
	v_cndmask_b32_e64 v1, v15, v13, s[2:3]
	v_cndmask_b32_e64 v0, v14, v12, s[2:3]
	v_lshl_add_u64 v[4:5], v[4:5], 0, v[112:113]
	global_store_dwordx4 v[4:5], v[0:3], off
	v_cndmask_b32_e64 v48, v154, v50, s[2:3]
	v_cndmask_b32_e64 v32, v152, v34, s[2:3]
	v_add_u32_e32 v0, 0xb8, v146
	v_cndmask_b32_e64 v0, v150, v0, s[2:3]
	v_ashrrev_i32_e32 v49, 31, v48
	v_ashrrev_i32_e32 v33, 31, v32
	v_ashrrev_i32_e32 v1, 31, v0
	v_lshlrev_b64 v[48:49], 10, v[48:49]
	v_lshlrev_b64 v[32:33], 10, v[32:33]
	v_lshlrev_b64 v[0:1], 10, v[0:1]
	v_lshl_add_u64 v[48:49], s[38:39], 0, v[48:49]
	v_lshl_add_u64 v[32:33], s[38:39], 0, v[32:33]
	v_lshl_add_u64 v[0:1], s[38:39], 0, v[0:1]
	v_cndmask_b32_e64 v55, v55, v63, s[2:3]
	v_cndmask_b32_e64 v54, v54, v62, s[2:3]
	v_cndmask_b32_e64 v53, v53, v59, s[2:3]
	v_cndmask_b32_e64 v52, v52, v58, s[2:3]
	v_lshl_add_u64 v[48:49], v[48:49], 0, v[112:113]
	v_cndmask_b32_e64 v39, v39, v47, s[2:3]
	v_cndmask_b32_e64 v38, v38, v46, s[2:3]
	v_cndmask_b32_e64 v37, v37, v43, s[2:3]
	v_cndmask_b32_e64 v36, v36, v42, s[2:3]
	v_lshl_add_u64 v[32:33], v[32:33], 0, v[112:113]
	v_lshl_add_u64 v[4:5], v[0:1], 0, v[112:113]
	v_cndmask_b32_e64 v3, v11, v17, s[2:3]
	v_cndmask_b32_e64 v2, v7, v16, s[2:3]
	v_cndmask_b32_e64 v1, v6, v15, s[2:3]
	v_cndmask_b32_e64 v0, v10, v14, s[2:3]
	s_and_b64 vcc, exec, s[4:5]
	s_mov_b32 s66, s36
	s_mov_b32 s6, s44
	s_mov_b64 s[50:51], s[48:49]
	s_mov_b64 s[52:53], s[46:47]
	global_store_dwordx4 v[48:49], v[52:55], off
	global_store_dwordx4 v[32:33], v[36:39], off
	global_store_dwordx4 v[4:5], v[0:3], off
	s_cbranch_vccz .LBB0_897
	s_waitcnt vmcnt(0)
	s_cmpk_gt_u32 s11, 0xff
	s_cbranch_scc1 .LBB0_908
	s_barrier

.LBB0_997:
	ds_read_b128 v[128:131], v164
	ds_read_b128 v[132:135], v164 offset:1024
	ds_read_b128 v[152:155], v164 offset:2048
	ds_read_b128 v[156:159], v164 offset:3072
	s_add_u32 s28, s48, 0xfffe0080
	s_addc_u32 s29, s49, -1
	s_cmp_eq_u32 s79, 4
	s_cselect_b32 s53, s9, s29
	s_cselect_b32 s52, s41, s28
	s_cselect_b32 s51, s39, s78
	s_cselect_b32 s50, s76, s77
	v_lshl_add_u64 v[204:205], s[48:49], 0, v[144:145]
	s_add_i32 m0, s55, 0xc000
	ds_read_b128 v[168:171], v165
	ds_read_b128 v[172:175], v165 offset:1024
	ds_read_b128 v[176:179], v165 offset:2048
	ds_read_b128 v[180:183], v165 offset:3072
	ds_read_b128 v[184:187], v165 offset:4096
	ds_read_b128 v[188:191], v165 offset:5120
	ds_read_b128 v[196:199], v165 offset:6144
	ds_read_b128 v[200:203], v165 offset:7168
	global_load_lds_dwordx4 v[204:205], off
	v_lshl_add_u64 v[204:205], s[48:49], 0, v[146:147]
	s_add_i32 m0, s55, 0xe000
	s_nop 0
	global_load_lds_dwordx4 v[204:205], off
	s_waitcnt lgkmcnt(8)
	s_barrier
	s_waitcnt lgkmcnt(0)
	v_mfma_f32_16x16x32_bf16 v[124:127], v[128:131], v[168:171], v[124:127]
	v_mfma_f32_16x16x32_bf16 v[120:123], v[152:155], v[168:171], v[120:123]
	v_mfma_f32_16x16x32_bf16 v[108:111], v[128:131], v[176:179], v[108:111]
	v_mfma_f32_16x16x32_bf16 v[104:107], v[152:155], v[176:179], v[104:107]
	v_mfma_f32_16x16x32_bf16 v[92:95], v[128:131], v[184:187], v[92:95]
	v_mfma_f32_16x16x32_bf16 v[88:91], v[152:155], v[184:187], v[88:91]
	v_mfma_f32_16x16x32_bf16 v[76:79], v[128:131], v[196:199], v[76:79]
	v_mfma_f32_16x16x32_bf16 v[72:75], v[152:155], v[196:199], v[72:75]
	v_mfma_f32_16x16x32_bf16 v[124:127], v[132:135], v[172:175], v[124:127]
	v_mfma_f32_16x16x32_bf16 v[120:123], v[156:159], v[172:175], v[120:123]
	v_mfma_f32_16x16x32_bf16 v[108:111], v[132:135], v[180:183], v[108:111]
	v_mfma_f32_16x16x32_bf16 v[104:107], v[156:159], v[180:183], v[104:107]
	v_mfma_f32_16x16x32_bf16 v[92:95], v[132:135], v[188:191], v[92:95]
	v_mfma_f32_16x16x32_bf16 v[88:91], v[156:159], v[188:191], v[88:91]
	v_mfma_f32_16x16x32_bf16 v[76:79], v[132:135], v[200:203], v[76:79]
	v_mfma_f32_16x16x32_bf16 v[72:75], v[156:159], v[200:203], v[72:75]
	s_barrier
	s_add_i32 s28, s65, s54
	v_lshl_add_u64 v[220:221], s[50:51], 0, v[138:139]
	s_mov_b32 m0, s28
	ds_read_b128 v[204:207], v166
	ds_read_b128 v[208:211], v166 offset:1024
	ds_read_b128 v[212:215], v166 offset:2048
	ds_read_b128 v[216:219], v166 offset:3072
	global_load_lds_dwordx4 v[220:221], off
	v_lshl_add_u64 v[222:223], s[50:51], 0, v[142:143]
	s_add_i32 m0, s28, 0x2000
	s_nop 0
	global_load_lds_dwordx4 v[222:223], off
	s_barrier
	s_waitcnt lgkmcnt(0)
	v_mfma_f32_16x16x32_bf16 v[116:119], v[204:207], v[168:171], v[116:119]
	v_mfma_f32_16x16x32_bf16 v[112:115], v[212:215], v[168:171], v[112:115]
	v_mfma_f32_16x16x32_bf16 v[100:103], v[204:207], v[176:179], v[100:103]
	v_mfma_f32_16x16x32_bf16 v[96:99], v[212:215], v[176:179], v[96:99]
	v_mfma_f32_16x16x32_bf16 v[84:87], v[204:207], v[184:187], v[84:87]
	v_mfma_f32_16x16x32_bf16 v[80:83], v[212:215], v[184:187], v[80:83]
	v_mfma_f32_16x16x32_bf16 v[68:71], v[204:207], v[196:199], v[68:71]
	v_mfma_f32_16x16x32_bf16 v[64:67], v[212:215], v[196:199], v[64:67]
	v_mfma_f32_16x16x32_bf16 v[116:119], v[208:211], v[172:175], v[116:119]
	v_mfma_f32_16x16x32_bf16 v[112:115], v[216:219], v[172:175], v[112:115]
	v_mfma_f32_16x16x32_bf16 v[100:103], v[208:211], v[180:183], v[100:103]
	v_mfma_f32_16x16x32_bf16 v[96:99], v[216:219], v[180:183], v[96:99]
	v_mfma_f32_16x16x32_bf16 v[84:87], v[208:211], v[188:191], v[84:87]
	v_mfma_f32_16x16x32_bf16 v[80:83], v[216:219], v[188:191], v[80:83]
	v_mfma_f32_16x16x32_bf16 v[68:71], v[208:211], v[200:203], v[68:71]
	v_mfma_f32_16x16x32_bf16 v[64:67], v[216:219], v[200:203], v[64:67]
	s_barrier
	s_mov_b32 m0, s55
	v_lshl_add_u64 v[224:225], s[52:53], 0, v[136:137]
	ds_read_b128 v[168:171], v165 offset:16384
	ds_read_b128 v[172:175], v165 offset:17408
	ds_read_b128 v[176:179], v165 offset:18432
	ds_read_b128 v[180:183], v165 offset:19456
	ds_read_b128 v[184:187], v165 offset:20480
	ds_read_b128 v[188:191], v165 offset:21504
	ds_read_b128 v[196:199], v165 offset:22528
	ds_read_b128 v[200:203], v165 offset:23552
	global_load_lds_dwordx4 v[224:225], off
	v_lshl_add_u64 v[226:227], s[52:53], 0, v[140:141]
	s_mov_b32 m0, s56
	s_nop 0
	global_load_lds_dwordx4 v[226:227], off
	s_barrier
	s_waitcnt lgkmcnt(0)
	v_mfma_f32_16x16x32_bf16 v[60:63], v[128:131], v[168:171], v[60:63]
	v_mfma_f32_16x16x32_bf16 v[56:59], v[152:155], v[168:171], v[56:59]
	v_mfma_f32_16x16x32_bf16 v[44:47], v[128:131], v[176:179], v[44:47]
	v_mfma_f32_16x16x32_bf16 v[40:43], v[152:155], v[176:179], v[40:43]
	v_mfma_f32_16x16x32_bf16 v[28:31], v[128:131], v[184:187], v[28:31]
	v_mfma_f32_16x16x32_bf16 v[24:27], v[152:155], v[184:187], v[24:27]
	v_mfma_f32_16x16x32_bf16 v[12:15], v[128:131], v[196:199], v[12:15]
	v_mfma_f32_16x16x32_bf16 v[8:11], v[152:155], v[196:199], v[8:11]
	v_mfma_f32_16x16x32_bf16 v[60:63], v[132:135], v[172:175], v[60:63]
	v_mfma_f32_16x16x32_bf16 v[56:59], v[156:159], v[172:175], v[56:59]
	v_mfma_f32_16x16x32_bf16 v[44:47], v[132:135], v[180:183], v[44:47]
	v_mfma_f32_16x16x32_bf16 v[40:43], v[156:159], v[180:183], v[40:43]
	v_mfma_f32_16x16x32_bf16 v[28:31], v[132:135], v[188:191], v[28:31]
	v_mfma_f32_16x16x32_bf16 v[24:27], v[156:159], v[188:191], v[24:27]
	v_mfma_f32_16x16x32_bf16 v[12:15], v[132:135], v[200:203], v[12:15]
	v_mfma_f32_16x16x32_bf16 v[8:11], v[156:159], v[200:203], v[8:11]
	s_barrier
	s_add_u32 s80, s50, 0x8000
	s_addc_u32 s81, s51, 0
	s_add_i32 s28, s66, s54
	v_lshl_add_u64 v[128:129], s[80:81], 0, v[138:139]
	s_mov_b32 m0, s28
	s_nop 0
	global_load_lds_dwordx4 v[128:129], off
	v_lshl_add_u64 v[128:129], s[80:81], 0, v[142:143]
	s_add_i32 m0, s28, 0x2000
	s_nop 0
	global_load_lds_dwordx4 v[128:129], off
	s_waitcnt vmcnt(6)
	s_barrier
	v_mfma_f32_16x16x32_bf16 v[52:55], v[204:207], v[168:171], v[52:55]
	v_mfma_f32_16x16x32_bf16 v[48:51], v[212:215], v[168:171], v[48:51]
	v_mfma_f32_16x16x32_bf16 v[36:39], v[204:207], v[176:179], v[36:39]
	v_mfma_f32_16x16x32_bf16 v[32:35], v[212:215], v[176:179], v[32:35]
	v_mfma_f32_16x16x32_bf16 v[20:23], v[204:207], v[184:187], v[20:23]
	v_mfma_f32_16x16x32_bf16 v[16:19], v[212:215], v[184:187], v[16:19]
	v_mfma_f32_16x16x32_bf16 v[4:7], v[204:207], v[196:199], v[4:7]
	v_mfma_f32_16x16x32_bf16 v[0:3], v[212:215], v[196:199], v[0:3]
	v_mfma_f32_16x16x32_bf16 v[52:55], v[208:211], v[172:175], v[52:55]
	v_mfma_f32_16x16x32_bf16 v[48:51], v[216:219], v[172:175], v[48:51]
	v_mfma_f32_16x16x32_bf16 v[36:39], v[208:211], v[180:183], v[36:39]
	v_mfma_f32_16x16x32_bf16 v[32:35], v[216:219], v[180:183], v[32:35]
	v_mfma_f32_16x16x32_bf16 v[20:23], v[208:211], v[188:191], v[20:23]
	v_mfma_f32_16x16x32_bf16 v[16:19], v[216:219], v[188:191], v[16:19]
	v_mfma_f32_16x16x32_bf16 v[4:7], v[208:211], v[200:203], v[4:7]
	v_mfma_f32_16x16x32_bf16 v[0:3], v[216:219], v[200:203], v[0:3]
	s_barrier
	s_add_i32 s28, 0, 0x18000
	v_add_u32_e32 v156, s28, v161
	ds_read_b128 v[128:131], v156
	ds_read_b128 v[132:135], v156 offset:1024
	ds_read_b128 v[152:155], v156 offset:2048
	ds_read_b128 v[156:159], v156 offset:3072
	s_add_u32 s52, s52, 0x20000
	s_addc_u32 s53, s53, 0
	s_mov_b32 m0, s57
	v_lshl_add_u64 v[204:205], s[52:53], 0, v[136:137]
	ds_read_b128 v[168:171], v165 offset:32768
	ds_read_b128 v[172:175], v165 offset:33792
	ds_read_b128 v[176:179], v165 offset:34816
	ds_read_b128 v[180:183], v165 offset:35840
	ds_read_b128 v[184:187], v165 offset:36864
	ds_read_b128 v[188:191], v165 offset:37888
	ds_read_b128 v[196:199], v165 offset:38912
	ds_read_b128 v[200:203], v165 offset:39936
	global_load_lds_dwordx4 v[204:205], off
	v_lshl_add_u64 v[204:205], s[52:53], 0, v[140:141]
	s_mov_b32 m0, s58
	s_nop 0
	global_load_lds_dwordx4 v[204:205], off
	s_waitcnt lgkmcnt(8)
	s_barrier
	s_waitcnt lgkmcnt(0)
	v_mfma_f32_16x16x32_bf16 v[124:127], v[128:131], v[168:171], v[124:127]
	v_mfma_f32_16x16x32_bf16 v[120:123], v[152:155], v[168:171], v[120:123]
	v_mfma_f32_16x16x32_bf16 v[108:111], v[128:131], v[176:179], v[108:111]
	v_mfma_f32_16x16x32_bf16 v[104:107], v[152:155], v[176:179], v[104:107]
	v_mfma_f32_16x16x32_bf16 v[92:95], v[128:131], v[184:187], v[92:95]
	v_mfma_f32_16x16x32_bf16 v[88:91], v[152:155], v[184:187], v[88:91]
	v_mfma_f32_16x16x32_bf16 v[76:79], v[128:131], v[196:199], v[76:79]
	v_mfma_f32_16x16x32_bf16 v[72:75], v[152:155], v[196:199], v[72:75]
	v_mfma_f32_16x16x32_bf16 v[124:127], v[132:135], v[172:175], v[124:127]
	v_mfma_f32_16x16x32_bf16 v[120:123], v[156:159], v[172:175], v[120:123]
	v_mfma_f32_16x16x32_bf16 v[108:111], v[132:135], v[180:183], v[108:111]
	v_mfma_f32_16x16x32_bf16 v[104:107], v[156:159], v[180:183], v[104:107]
	v_mfma_f32_16x16x32_bf16 v[92:95], v[132:135], v[188:191], v[92:95]
	v_mfma_f32_16x16x32_bf16 v[88:91], v[156:159], v[188:191], v[88:91]
	v_mfma_f32_16x16x32_bf16 v[76:79], v[132:135], v[200:203], v[76:79]
	v_mfma_f32_16x16x32_bf16 v[72:75], v[156:159], v[200:203], v[72:75]
	s_barrier
	s_add_i32 s29, 0, 0x1c000
	s_add_i32 s28, s28, s54
	v_add_u32_e32 v195, s29, v161
	v_lshl_add_u64 v[220:221], v[220:221], 0, s[36:37]
	s_mov_b32 m0, s28
	ds_read_b128 v[204:207], v195
	ds_read_b128 v[208:211], v195 offset:1024
	ds_read_b128 v[212:215], v195 offset:2048
	ds_read_b128 v[216:219], v195 offset:3072
	global_load_lds_dwordx4 v[220:221], off
	v_lshl_add_u64 v[220:221], v[222:223], 0, s[36:37]
	s_add_i32 m0, s28, 0x2000
	s_nop 0
	global_load_lds_dwordx4 v[220:221], off
	s_barrier
	s_waitcnt lgkmcnt(0)
	v_mfma_f32_16x16x32_bf16 v[116:119], v[204:207], v[168:171], v[116:119]
	v_mfma_f32_16x16x32_bf16 v[112:115], v[212:215], v[168:171], v[112:115]
	v_mfma_f32_16x16x32_bf16 v[100:103], v[204:207], v[176:179], v[100:103]
	v_mfma_f32_16x16x32_bf16 v[96:99], v[212:215], v[176:179], v[96:99]
	v_mfma_f32_16x16x32_bf16 v[84:87], v[204:207], v[184:187], v[84:87]
	v_mfma_f32_16x16x32_bf16 v[80:83], v[212:215], v[184:187], v[80:83]
	v_mfma_f32_16x16x32_bf16 v[68:71], v[204:207], v[196:199], v[68:71]
	v_mfma_f32_16x16x32_bf16 v[64:67], v[212:215], v[196:199], v[64:67]
	v_mfma_f32_16x16x32_bf16 v[116:119], v[208:211], v[172:175], v[116:119]
	v_mfma_f32_16x16x32_bf16 v[112:115], v[216:219], v[172:175], v[112:115]
	v_mfma_f32_16x16x32_bf16 v[100:103], v[208:211], v[180:183], v[100:103]
	v_mfma_f32_16x16x32_bf16 v[96:99], v[216:219], v[180:183], v[96:99]
	v_mfma_f32_16x16x32_bf16 v[84:87], v[208:211], v[188:191], v[84:87]
	v_mfma_f32_16x16x32_bf16 v[80:83], v[216:219], v[188:191], v[80:83]
	v_mfma_f32_16x16x32_bf16 v[68:71], v[208:211], v[200:203], v[68:71]
	v_mfma_f32_16x16x32_bf16 v[64:67], v[216:219], v[200:203], v[64:67]
	s_barrier
	s_mov_b32 m0, s62
	v_lshl_add_u64 v[220:221], v[224:225], 0, s[36:37]
	ds_read_b128 v[168:171], v165 offset:49152
	ds_read_b128 v[172:175], v165 offset:50176
	ds_read_b128 v[176:179], v165 offset:51200
	ds_read_b128 v[180:183], v165 offset:52224
	ds_read_b128 v[184:187], v165 offset:53248
	ds_read_b128 v[188:191], v165 offset:54272
	ds_read_b128 v[196:199], v165 offset:55296
	ds_read_b128 v[200:203], v165 offset:56320
	global_load_lds_dwordx4 v[220:221], off
	v_lshl_add_u64 v[220:221], v[226:227], 0, s[36:37]
	s_mov_b32 m0, s63
	s_nop 0
	global_load_lds_dwordx4 v[220:221], off
	s_barrier
	s_waitcnt lgkmcnt(0)
	v_mfma_f32_16x16x32_bf16 v[60:63], v[128:131], v[168:171], v[60:63]
	v_mfma_f32_16x16x32_bf16 v[56:59], v[152:155], v[168:171], v[56:59]
	v_mfma_f32_16x16x32_bf16 v[44:47], v[128:131], v[176:179], v[44:47]
	v_mfma_f32_16x16x32_bf16 v[40:43], v[152:155], v[176:179], v[40:43]
	v_mfma_f32_16x16x32_bf16 v[28:31], v[128:131], v[184:187], v[28:31]
	v_mfma_f32_16x16x32_bf16 v[24:27], v[152:155], v[184:187], v[24:27]
	v_mfma_f32_16x16x32_bf16 v[12:15], v[128:131], v[196:199], v[12:15]
	v_mfma_f32_16x16x32_bf16 v[8:11], v[152:155], v[196:199], v[8:11]
	v_mfma_f32_16x16x32_bf16 v[60:63], v[132:135], v[172:175], v[60:63]
	v_mfma_f32_16x16x32_bf16 v[56:59], v[156:159], v[172:175], v[56:59]
	v_mfma_f32_16x16x32_bf16 v[44:47], v[132:135], v[180:183], v[44:47]
	v_mfma_f32_16x16x32_bf16 v[40:43], v[156:159], v[180:183], v[40:43]
	v_mfma_f32_16x16x32_bf16 v[28:31], v[132:135], v[188:191], v[28:31]
	v_mfma_f32_16x16x32_bf16 v[24:27], v[156:159], v[188:191], v[24:27]
	v_mfma_f32_16x16x32_bf16 v[12:15], v[132:135], v[200:203], v[12:15]
	v_mfma_f32_16x16x32_bf16 v[8:11], v[156:159], v[200:203], v[8:11]
	s_barrier
	s_add_u32 s50, s50, 0x8080
	s_addc_u32 s51, s51, 0
	s_add_i32 s28, s29, s54
	v_lshl_add_u64 v[128:129], s[50:51], 0, v[138:139]
	s_mov_b32 m0, s28
	s_nop 0
	global_load_lds_dwordx4 v[128:129], off
	v_lshl_add_u64 v[128:129], s[50:51], 0, v[142:143]
	s_add_i32 m0, s28, 0x2000
	s_nop 0
	global_load_lds_dwordx4 v[128:129], off
	s_add_i32 s79, s79, 2
	s_add_u32 s48, s48, 0x100
	s_addc_u32 s49, s49, 0
	s_add_u32 s77, s77, 0x100
	s_addc_u32 s78, s78, 0
	s_cmp_gt_u32 s79, 5
	s_waitcnt vmcnt(6)
	s_barrier
	v_mfma_f32_16x16x32_bf16 v[52:55], v[204:207], v[168:171], v[52:55]
	v_mfma_f32_16x16x32_bf16 v[48:51], v[212:215], v[168:171], v[48:51]
	v_mfma_f32_16x16x32_bf16 v[36:39], v[204:207], v[176:179], v[36:39]
	v_mfma_f32_16x16x32_bf16 v[32:35], v[212:215], v[176:179], v[32:35]
	v_mfma_f32_16x16x32_bf16 v[20:23], v[204:207], v[184:187], v[20:23]
	v_mfma_f32_16x16x32_bf16 v[16:19], v[212:215], v[184:187], v[16:19]
	v_mfma_f32_16x16x32_bf16 v[4:7], v[204:207], v[196:199], v[4:7]
	v_mfma_f32_16x16x32_bf16 v[0:3], v[212:215], v[196:199], v[0:3]
	v_mfma_f32_16x16x32_bf16 v[52:55], v[208:211], v[172:175], v[52:55]
	v_mfma_f32_16x16x32_bf16 v[48:51], v[216:219], v[172:175], v[48:51]
	v_mfma_f32_16x16x32_bf16 v[36:39], v[208:211], v[180:183], v[36:39]
	v_mfma_f32_16x16x32_bf16 v[32:35], v[216:219], v[180:183], v[32:35]
	v_mfma_f32_16x16x32_bf16 v[20:23], v[208:211], v[188:191], v[20:23]
	v_mfma_f32_16x16x32_bf16 v[16:19], v[216:219], v[188:191], v[16:19]
	v_mfma_f32_16x16x32_bf16 v[4:7], v[208:211], v[200:203], v[4:7]
	v_mfma_f32_16x16x32_bf16 v[0:3], v[216:219], v[200:203], v[0:3]
	s_barrier
	s_cbranch_scc0 .LBB0_997
	v_lshl_add_u32 v152, s8, 8, v160
	v_lshl_or_b32 v156, s10, 8, v162
	v_ashrrev_i32_e32 v153, 31, v152
	v_lshlrev_b64 v[128:129], 11, v[152:153]
	v_ashrrev_i32_e32 v157, 31, v156
	v_lshl_add_u64 v[128:129], s[42:43], 0, v[128:129]
	v_lshlrev_b64 v[130:131], 1, v[156:157]
	v_or_b32_e32 v158, 16, v152
	v_lshl_add_u64 v[128:129], v[128:129], 0, v[130:131]
	v_ashrrev_i32_e32 v159, 31, v158
	global_load_dwordx4 v[168:171], v[128:129], off
	global_load_dwordx4 v[172:175], v[128:129], off offset:64
	v_lshlrev_b64 v[128:129], 11, v[158:159]
	v_lshl_add_u64 v[128:129], s[42:43], 0, v[128:129]
	v_lshl_add_u64 v[128:129], v[128:129], 0, v[130:131]
	global_load_dwordx4 v[132:135], v[128:129], off
	s_nop 0
	global_load_dwordx4 v[128:131], v[128:129], off offset:64
	v_cndmask_b32_e64 v155, 0, 1, s[12:13]
	v_or_b32_e32 v154, v156, v163
	v_cmp_ne_u32_e64 s[8:9], 1, v155
	v_ashrrev_i32_e32 v155, 31, v154
	s_andn2_b64 vcc, exec, s[12:13]
	v_lshlrev_b64 v[154:155], 1, v[154:155]
	s_waitcnt vmcnt(0)
	v_lshlrev_b32_e32 v176, 16, v168
	v_and_b32_e32 v177, 0xffff0000, v168
	v_lshlrev_b32_e32 v168, 16, v169
	v_and_b32_e32 v169, 0xffff0000, v169
	v_lshlrev_b32_e32 v178, 16, v170
	v_and_b32_e32 v179, 0xffff0000, v170
	v_lshlrev_b32_e32 v170, 16, v171
	v_and_b32_e32 v171, 0xffff0000, v171
	v_lshlrev_b32_e32 v180, 16, v172
	v_and_b32_e32 v181, 0xffff0000, v172
	v_lshlrev_b32_e32 v172, 16, v173
	v_and_b32_e32 v173, 0xffff0000, v173
	v_lshlrev_b32_e32 v182, 16, v174
	v_and_b32_e32 v183, 0xffff0000, v174
	v_lshlrev_b32_e32 v174, 16, v175
	v_and_b32_e32 v175, 0xffff0000, v175
	v_pk_add_f32 v[126:127], v[126:127], v[168:169]
	v_pk_add_f32 v[124:125], v[124:125], v[176:177]
	v_pk_add_f32 v[122:123], v[122:123], v[170:171]
	v_pk_add_f32 v[120:121], v[120:121], v[178:179]
	v_pk_add_f32 v[118:119], v[118:119], v[172:173]
	v_pk_add_f32 v[116:117], v[116:117], v[180:181]
	v_pk_add_f32 v[114:115], v[114:115], v[174:175]
	v_pk_add_f32 v[112:113], v[112:113], v[182:183]
	v_add_u32_e32 v169, 8, v152
	s_cbranch_vccnz .LBB0_1000
	v_cvt_pk_bf16_f32 v168, v124, v125
	v_cvt_pk_bf16_f32 v174, v116, v117
	v_cvt_pk_bf16_f32 v170, v126, v127
	v_cvt_pk_bf16_f32 v171, v120, v121
	v_cvt_pk_bf16_f32 v175, v118, v119
	v_cvt_pk_bf16_f32 v176, v112, v113
	v_cndmask_b32_e64 v173, v168, v174, s[4:5]
	v_mov_b32_e32 v178, 0
	v_cvt_pk_bf16_f32 v172, v122, v123
	v_cvt_pk_bf16_f32 v177, v114, v115
	v_mov_b32_dpp v178, v173 row_ror:8 row_mask:0xf bank_mask:0xf
	v_cndmask_b32_e64 v173, v170, v175, s[4:5]
	v_mov_b32_e32 v179, 0
	v_cndmask_b32_e64 v180, v171, v176, s[4:5]
	v_mov_b32_e32 v181, 0
	v_mov_b32_dpp v179, v173 row_ror:8 row_mask:0xf bank_mask:0xf
	v_cndmask_b32_e64 v173, v172, v177, s[4:5]
	v_mov_b32_dpp v181, v180 row_ror:8 row_mask:0xf bank_mask:0xf
	v_mov_b32_e32 v180, 0
	v_cndmask_b32_e64 v174, v174, v178, s[4:5]
	v_cndmask_b32_e64 v175, v175, v179, s[4:5]
	v_mov_b32_dpp v180, v173 row_ror:8 row_mask:0xf bank_mask:0xf
	v_cndmask_b32_e64 v173, v180, v172, s[4:5]
	v_cndmask_b32_e64 v172, v181, v171, s[4:5]
	v_cndmask_b32_e64 v171, v179, v170, s[4:5]
	v_cndmask_b32_e64 v170, v178, v168, s[4:5]
	v_add_u32_e32 v168, -8, v152
	v_cndmask_b32_e64 v178, v168, v152, s[4:5]
	v_ashrrev_i32_e32 v179, 31, v178
	v_lshlrev_b64 v[178:179], 11, v[178:179]
	v_lshl_add_u64 v[178:179], s[68:69], 0, v[178:179]
	v_lshl_add_u64 v[178:179], v[178:179], 0, v[154:155]
	global_store_dwordx4 v[178:179], v[170:173], off
	v_cndmask_b32_e64 v177, v177, v180, s[4:5]
	v_cndmask_b32_e64 v176, v176, v181, s[4:5]
	v_cndmask_b32_e64 v170, v152, v169, s[4:5]
	v_ashrrev_i32_e32 v171, 31, v170
	v_lshlrev_b64 v[170:171], 11, v[170:171]
	v_lshl_add_u64 v[170:171], s[68:69], 0, v[170:171]
	v_lshl_add_u64 v[170:171], v[170:171], 0, v[154:155]
	global_store_dwordx4 v[170:171], v[174:177], off

.LBB0_1092:
	s_ashr_i32 s37, s36, 31
	v_cmp_lt_i64_e32 vcc, s[0:1], v[142:143]
	s_lshl_b64 s[0:1], s[36:37], 19
	s_add_u32 s38, s68, s0
	s_addc_u32 s39, s69, s1
	s_and_b64 s[0:1], vcc, exec
	s_cselect_b32 s37, s39, s45
	s_cselect_b32 s60, s38, s44
	s_ashr_i32 s13, s12, 31
	s_lshl_b64 s[0:1], s[12:13], 19
	s_add_u32 s40, s70, s0
	s_addc_u32 s41, s71, s1
	s_and_b64 s[0:1], vcc, exec
	s_cselect_b32 s13, s41, s43
	s_cselect_b32 s61, s40, s42
	s_add_u32 s0, s44, 0x40080
	s_addc_u32 s1, s45, 0
	s_add_u32 s62, s42, 0x100
	s_addc_u32 s63, s43, 0
	s_mov_b32 s64, -2
	ds_read_b128 v[146:149], v167
	ds_read_b128 v[150:153], v167 offset:1024
	ds_read_b128 v[178:181], v167 offset:2048
	ds_read_b128 v[182:185], v167 offset:3072
	s_add_u32 s28, s0, 0xfffc0080
	s_addc_u32 s29, s1, -1
	s_cmp_eq_u32 s64, 12
	s_cselect_b32 s45, s37, s29
	s_cselect_b32 s44, s60, s28
	s_cselect_b32 s43, s13, s63
	s_cselect_b32 s42, s61, s62
	v_lshl_add_u64 v[156:157], s[0:1], 0, v[138:139]
	s_add_i32 m0, s47, 0xc000
	ds_read_b128 v[186:189], v171
	ds_read_b128 v[196:199], v171 offset:1024
	ds_read_b128 v[200:203], v171 offset:2048
	ds_read_b128 v[204:207], v171 offset:3072
	ds_read_b128 v[208:211], v171 offset:4096
	ds_read_b128 v[212:215], v171 offset:5120
	ds_read_b128 v[216:219], v171 offset:6144
	ds_read_b128 v[220:223], v171 offset:7168
	global_load_lds_dwordx4 v[156:157], off
	v_lshl_add_u64 v[156:157], s[0:1], 0, v[140:141]
	s_add_i32 m0, s47, 0xe000
	s_nop 0
	global_load_lds_dwordx4 v[156:157], off
	s_waitcnt lgkmcnt(8)
	s_barrier
	s_waitcnt lgkmcnt(0)
	v_mfma_f32_16x16x32_bf16 v[124:127], v[146:149], v[186:189], 0
	v_mfma_f32_16x16x32_bf16 v[120:123], v[178:181], v[186:189], 0
	v_mfma_f32_16x16x32_bf16 v[108:111], v[146:149], v[200:203], 0
	v_mfma_f32_16x16x32_bf16 v[104:107], v[178:181], v[200:203], 0
	v_mfma_f32_16x16x32_bf16 v[92:95], v[146:149], v[208:211], 0
	v_mfma_f32_16x16x32_bf16 v[88:91], v[178:181], v[208:211], 0
	v_mfma_f32_16x16x32_bf16 v[76:79], v[146:149], v[216:219], 0
	v_mfma_f32_16x16x32_bf16 v[72:75], v[178:181], v[216:219], 0
	v_mfma_f32_16x16x32_bf16 v[124:127], v[150:153], v[196:199], v[124:127]
	v_mfma_f32_16x16x32_bf16 v[120:123], v[182:185], v[196:199], v[120:123]
	v_mfma_f32_16x16x32_bf16 v[108:111], v[150:153], v[204:207], v[108:111]
	v_mfma_f32_16x16x32_bf16 v[104:107], v[182:185], v[204:207], v[104:107]
	v_mfma_f32_16x16x32_bf16 v[92:95], v[150:153], v[212:215], v[92:95]
	v_mfma_f32_16x16x32_bf16 v[88:91], v[182:185], v[212:215], v[88:91]
	v_mfma_f32_16x16x32_bf16 v[76:79], v[150:153], v[220:223], v[76:79]
	v_mfma_f32_16x16x32_bf16 v[72:75], v[182:185], v[220:223], v[72:75]
	s_barrier
	s_add_i32 s28, s56, s11
	v_lshl_add_u64 v[156:157], s[42:43], 0, v[132:133]
	s_mov_b32 m0, s28
	ds_read_b128 v[224:227], v175
	ds_read_b128 v[228:231], v175 offset:1024
	ds_read_b128 v[232:235], v175 offset:2048
	ds_read_b128 v[236:239], v175 offset:3072
	global_load_lds_dwordx4 v[156:157], off
	v_lshl_add_u64 v[160:161], s[42:43], 0, v[128:129]
	s_add_i32 m0, s28, 0x2000
	s_nop 0
	global_load_lds_dwordx4 v[160:161], off
	s_barrier
	s_waitcnt lgkmcnt(0)
	v_mfma_f32_16x16x32_bf16 v[116:119], v[224:227], v[186:189], 0
	v_mfma_f32_16x16x32_bf16 v[112:115], v[232:235], v[186:189], 0
	v_mfma_f32_16x16x32_bf16 v[100:103], v[224:227], v[200:203], 0
	v_mfma_f32_16x16x32_bf16 v[96:99], v[232:235], v[200:203], 0
	v_mfma_f32_16x16x32_bf16 v[84:87], v[224:227], v[208:211], 0
	v_mfma_f32_16x16x32_bf16 v[80:83], v[232:235], v[208:211], 0
	v_mfma_f32_16x16x32_bf16 v[68:71], v[224:227], v[216:219], 0
	v_mfma_f32_16x16x32_bf16 v[64:67], v[232:235], v[216:219], 0
	v_mfma_f32_16x16x32_bf16 v[116:119], v[228:231], v[196:199], v[116:119]
	v_mfma_f32_16x16x32_bf16 v[112:115], v[236:239], v[196:199], v[112:115]
	v_mfma_f32_16x16x32_bf16 v[100:103], v[228:231], v[204:207], v[100:103]
	v_mfma_f32_16x16x32_bf16 v[96:99], v[236:239], v[204:207], v[96:99]
	v_mfma_f32_16x16x32_bf16 v[84:87], v[228:231], v[212:215], v[84:87]
	v_mfma_f32_16x16x32_bf16 v[80:83], v[236:239], v[212:215], v[80:83]
	v_mfma_f32_16x16x32_bf16 v[68:71], v[228:231], v[220:223], v[68:71]
	v_mfma_f32_16x16x32_bf16 v[64:67], v[236:239], v[220:223], v[64:67]
	s_barrier
	s_mov_b32 m0, s47
	v_lshl_add_u64 v[164:165], s[44:45], 0, v[134:135]
	ds_read_b128 v[186:189], v171 offset:16384
	ds_read_b128 v[196:199], v171 offset:17408
	ds_read_b128 v[200:203], v171 offset:18432
	ds_read_b128 v[204:207], v171 offset:19456
	ds_read_b128 v[208:211], v171 offset:20480
	ds_read_b128 v[212:215], v171 offset:21504
	ds_read_b128 v[216:219], v171 offset:22528
	ds_read_b128 v[220:223], v171 offset:23552
	global_load_lds_dwordx4 v[164:165], off
	v_lshl_add_u64 v[168:169], s[44:45], 0, v[130:131]
	s_mov_b32 m0, s48
	s_nop 0
	global_load_lds_dwordx4 v[168:169], off
	s_barrier
	s_waitcnt lgkmcnt(0)
	v_mfma_f32_16x16x32_bf16 v[60:63], v[146:149], v[186:189], 0
	v_mfma_f32_16x16x32_bf16 v[56:59], v[178:181], v[186:189], 0
	v_mfma_f32_16x16x32_bf16 v[44:47], v[146:149], v[200:203], 0
	v_mfma_f32_16x16x32_bf16 v[40:43], v[178:181], v[200:203], 0
	v_mfma_f32_16x16x32_bf16 v[28:31], v[146:149], v[208:211], 0
	v_mfma_f32_16x16x32_bf16 v[24:27], v[178:181], v[208:211], 0
	v_mfma_f32_16x16x32_bf16 v[12:15], v[146:149], v[216:219], 0
	v_mfma_f32_16x16x32_bf16 v[8:11], v[178:181], v[216:219], 0
	v_mfma_f32_16x16x32_bf16 v[60:63], v[150:153], v[196:199], v[60:63]
	v_mfma_f32_16x16x32_bf16 v[56:59], v[182:185], v[196:199], v[56:59]
	v_mfma_f32_16x16x32_bf16 v[44:47], v[150:153], v[204:207], v[44:47]
	v_mfma_f32_16x16x32_bf16 v[40:43], v[182:185], v[204:207], v[40:43]
	v_mfma_f32_16x16x32_bf16 v[28:31], v[150:153], v[212:215], v[28:31]
	v_mfma_f32_16x16x32_bf16 v[24:27], v[182:185], v[212:215], v[24:27]
	v_mfma_f32_16x16x32_bf16 v[12:15], v[150:153], v[220:223], v[12:15]
	v_mfma_f32_16x16x32_bf16 v[8:11], v[182:185], v[220:223], v[8:11]
	s_barrier
	s_add_u32 s66, s42, 0x40000
	s_addc_u32 s67, s43, 0
	s_add_i32 s28, s57, s11
	v_lshl_add_u64 v[146:147], s[66:67], 0, v[132:133]
	s_mov_b32 m0, s28
	s_nop 0
	global_load_lds_dwordx4 v[146:147], off
	v_lshl_add_u64 v[146:147], s[66:67], 0, v[128:129]
	s_add_i32 m0, s28, 0x2000
	s_nop 0
	global_load_lds_dwordx4 v[146:147], off
	s_waitcnt vmcnt(6)
	s_barrier
	v_mfma_f32_16x16x32_bf16 v[52:55], v[224:227], v[186:189], 0
	v_mfma_f32_16x16x32_bf16 v[48:51], v[232:235], v[186:189], 0
	v_mfma_f32_16x16x32_bf16 v[36:39], v[224:227], v[200:203], 0
	v_mfma_f32_16x16x32_bf16 v[32:35], v[232:235], v[200:203], 0
	v_mfma_f32_16x16x32_bf16 v[20:23], v[224:227], v[208:211], 0
	v_mfma_f32_16x16x32_bf16 v[16:19], v[232:235], v[208:211], 0
	v_mfma_f32_16x16x32_bf16 v[4:7], v[224:227], v[216:219], 0
	v_mfma_f32_16x16x32_bf16 v[0:3], v[232:235], v[216:219], 0
	v_mfma_f32_16x16x32_bf16 v[52:55], v[228:231], v[196:199], v[52:55]
	v_mfma_f32_16x16x32_bf16 v[48:51], v[236:239], v[196:199], v[48:51]
	v_mfma_f32_16x16x32_bf16 v[36:39], v[228:231], v[204:207], v[36:39]
	v_mfma_f32_16x16x32_bf16 v[32:35], v[236:239], v[204:207], v[32:35]
	v_mfma_f32_16x16x32_bf16 v[20:23], v[228:231], v[212:215], v[20:23]
	v_mfma_f32_16x16x32_bf16 v[16:19], v[236:239], v[212:215], v[16:19]
	v_mfma_f32_16x16x32_bf16 v[4:7], v[228:231], v[220:223], v[4:7]
	v_mfma_f32_16x16x32_bf16 v[0:3], v[236:239], v[220:223], v[0:3]
	s_barrier
	s_add_i32 s28, 0, 0x18000
	v_add_u32_e32 v154, s28, v159
	ds_read_b128 v[146:149], v154
	ds_read_b128 v[150:153], v154 offset:1024
	ds_read_b128 v[178:181], v154 offset:2048
	ds_read_b128 v[182:185], v154 offset:3072
	s_add_u32 s44, s44, 0x40000
	s_addc_u32 s45, s45, 0
	s_mov_b32 m0, s49
	v_lshl_add_u64 v[172:173], s[44:45], 0, v[134:135]
	ds_read_b128 v[186:189], v171 offset:32768
	ds_read_b128 v[196:199], v171 offset:33792
	ds_read_b128 v[200:203], v171 offset:34816
	ds_read_b128 v[204:207], v171 offset:35840
	ds_read_b128 v[208:211], v171 offset:36864
	ds_read_b128 v[212:215], v171 offset:37888
	ds_read_b128 v[216:219], v171 offset:38912
	ds_read_b128 v[220:223], v171 offset:39936
	global_load_lds_dwordx4 v[172:173], off
	v_lshl_add_u64 v[172:173], s[44:45], 0, v[130:131]
	s_mov_b32 m0, s50
	s_nop 0
	global_load_lds_dwordx4 v[172:173], off
	s_waitcnt lgkmcnt(8)
	s_barrier
	s_waitcnt lgkmcnt(0)
	v_mfma_f32_16x16x32_bf16 v[124:127], v[146:149], v[186:189], v[124:127]
	v_mfma_f32_16x16x32_bf16 v[120:123], v[178:181], v[186:189], v[120:123]
	v_mfma_f32_16x16x32_bf16 v[108:111], v[146:149], v[200:203], v[108:111]
	v_mfma_f32_16x16x32_bf16 v[104:107], v[178:181], v[200:203], v[104:107]
	v_mfma_f32_16x16x32_bf16 v[92:95], v[146:149], v[208:211], v[92:95]
	v_mfma_f32_16x16x32_bf16 v[88:91], v[178:181], v[208:211], v[88:91]
	v_mfma_f32_16x16x32_bf16 v[76:79], v[146:149], v[216:219], v[76:79]
	v_mfma_f32_16x16x32_bf16 v[72:75], v[178:181], v[216:219], v[72:75]
	v_mfma_f32_16x16x32_bf16 v[124:127], v[150:153], v[196:199], v[124:127]
	v_mfma_f32_16x16x32_bf16 v[120:123], v[182:185], v[196:199], v[120:123]
	v_mfma_f32_16x16x32_bf16 v[108:111], v[150:153], v[204:207], v[108:111]
	v_mfma_f32_16x16x32_bf16 v[104:107], v[182:185], v[204:207], v[104:107]
	v_mfma_f32_16x16x32_bf16 v[92:95], v[150:153], v[212:215], v[92:95]
	v_mfma_f32_16x16x32_bf16 v[88:91], v[182:185], v[212:215], v[88:91]
	v_mfma_f32_16x16x32_bf16 v[76:79], v[150:153], v[220:223], v[76:79]
	v_mfma_f32_16x16x32_bf16 v[72:75], v[182:185], v[220:223], v[72:75]
	s_barrier
	s_add_i32 s29, 0, 0x1c000
	s_add_i32 s28, s28, s11
	v_add_u32_e32 v154, s29, v159
	v_lshl_add_u64 v[156:157], v[156:157], 0, s[6:7]
	s_mov_b32 m0, s28
	ds_read_b128 v[224:227], v154
	ds_read_b128 v[228:231], v154 offset:1024
	ds_read_b128 v[232:235], v154 offset:2048
	ds_read_b128 v[236:239], v154 offset:3072
	global_load_lds_dwordx4 v[156:157], off
	v_lshl_add_u64 v[156:157], v[160:161], 0, s[6:7]
	s_add_i32 m0, s28, 0x2000
	s_nop 0
	global_load_lds_dwordx4 v[156:157], off
	s_barrier
	s_waitcnt lgkmcnt(0)
	v_mfma_f32_16x16x32_bf16 v[116:119], v[224:227], v[186:189], v[116:119]
	v_mfma_f32_16x16x32_bf16 v[112:115], v[232:235], v[186:189], v[112:115]
	v_mfma_f32_16x16x32_bf16 v[100:103], v[224:227], v[200:203], v[100:103]
	v_mfma_f32_16x16x32_bf16 v[96:99], v[232:235], v[200:203], v[96:99]
	v_mfma_f32_16x16x32_bf16 v[84:87], v[224:227], v[208:211], v[84:87]
	v_mfma_f32_16x16x32_bf16 v[80:83], v[232:235], v[208:211], v[80:83]
	v_mfma_f32_16x16x32_bf16 v[68:71], v[224:227], v[216:219], v[68:71]
	v_mfma_f32_16x16x32_bf16 v[64:67], v[232:235], v[216:219], v[64:67]
	v_mfma_f32_16x16x32_bf16 v[116:119], v[228:231], v[196:199], v[116:119]
	v_mfma_f32_16x16x32_bf16 v[112:115], v[236:239], v[196:199], v[112:115]
	v_mfma_f32_16x16x32_bf16 v[100:103], v[228:231], v[204:207], v[100:103]
	v_mfma_f32_16x16x32_bf16 v[96:99], v[236:239], v[204:207], v[96:99]
	v_mfma_f32_16x16x32_bf16 v[84:87], v[228:231], v[212:215], v[84:87]
	v_mfma_f32_16x16x32_bf16 v[80:83], v[236:239], v[212:215], v[80:83]
	v_mfma_f32_16x16x32_bf16 v[68:71], v[228:231], v[220:223], v[68:71]
	v_mfma_f32_16x16x32_bf16 v[64:67], v[236:239], v[220:223], v[64:67]
	s_barrier
	s_mov_b32 m0, s53
	v_lshl_add_u64 v[156:157], v[164:165], 0, s[6:7]
	ds_read_b128 v[186:189], v171 offset:49152
	ds_read_b128 v[196:199], v171 offset:50176
	ds_read_b128 v[200:203], v171 offset:51200
	ds_read_b128 v[204:207], v171 offset:52224
	ds_read_b128 v[208:211], v171 offset:53248
	ds_read_b128 v[212:215], v171 offset:54272
	ds_read_b128 v[216:219], v171 offset:55296
	ds_read_b128 v[220:223], v171 offset:56320
	global_load_lds_dwordx4 v[156:157], off
	v_lshl_add_u64 v[156:157], v[168:169], 0, s[6:7]
	s_mov_b32 m0, s54
	s_nop 0
	global_load_lds_dwordx4 v[156:157], off
	s_barrier
	s_waitcnt lgkmcnt(0)
	v_mfma_f32_16x16x32_bf16 v[60:63], v[146:149], v[186:189], v[60:63]
	v_mfma_f32_16x16x32_bf16 v[56:59], v[178:181], v[186:189], v[56:59]
	v_mfma_f32_16x16x32_bf16 v[44:47], v[146:149], v[200:203], v[44:47]
	v_mfma_f32_16x16x32_bf16 v[40:43], v[178:181], v[200:203], v[40:43]
	v_mfma_f32_16x16x32_bf16 v[28:31], v[146:149], v[208:211], v[28:31]
	v_mfma_f32_16x16x32_bf16 v[24:27], v[178:181], v[208:211], v[24:27]
	v_mfma_f32_16x16x32_bf16 v[12:15], v[146:149], v[216:219], v[12:15]
	v_mfma_f32_16x16x32_bf16 v[8:11], v[178:181], v[216:219], v[8:11]
	v_mfma_f32_16x16x32_bf16 v[60:63], v[150:153], v[196:199], v[60:63]
	v_mfma_f32_16x16x32_bf16 v[56:59], v[182:185], v[196:199], v[56:59]
	v_mfma_f32_16x16x32_bf16 v[44:47], v[150:153], v[204:207], v[44:47]
	v_mfma_f32_16x16x32_bf16 v[40:43], v[182:185], v[204:207], v[40:43]
	v_mfma_f32_16x16x32_bf16 v[28:31], v[150:153], v[212:215], v[28:31]
	v_mfma_f32_16x16x32_bf16 v[24:27], v[182:185], v[212:215], v[24:27]
	v_mfma_f32_16x16x32_bf16 v[12:15], v[150:153], v[220:223], v[12:15]
	v_mfma_f32_16x16x32_bf16 v[8:11], v[182:185], v[220:223], v[8:11]
	s_barrier
	s_add_u32 s42, s42, 0x40080
	s_addc_u32 s43, s43, 0
	s_add_i32 s28, s29, s11
	v_lshl_add_u64 v[146:147], s[42:43], 0, v[132:133]
	s_mov_b32 m0, s28
	s_nop 0
	global_load_lds_dwordx4 v[146:147], off
	v_lshl_add_u64 v[146:147], s[42:43], 0, v[128:129]
	s_add_i32 m0, s28, 0x2000
	s_nop 0
	global_load_lds_dwordx4 v[146:147], off
	s_add_i32 s64, s64, 2
	s_add_u32 s0, s0, 0x100
	s_addc_u32 s1, s1, 0
	s_add_u32 s62, s62, 0x100
	s_addc_u32 s63, s63, 0
	s_cmp_gt_u32 s64, 13
	s_waitcnt vmcnt(6)
	s_barrier
	v_mfma_f32_16x16x32_bf16 v[52:55], v[224:227], v[186:189], v[52:55]
	v_mfma_f32_16x16x32_bf16 v[48:51], v[232:235], v[186:189], v[48:51]
	v_mfma_f32_16x16x32_bf16 v[36:39], v[224:227], v[200:203], v[36:39]
	v_mfma_f32_16x16x32_bf16 v[32:35], v[232:235], v[200:203], v[32:35]
	v_mfma_f32_16x16x32_bf16 v[20:23], v[224:227], v[208:211], v[20:23]
	v_mfma_f32_16x16x32_bf16 v[16:19], v[232:235], v[208:211], v[16:19]
	v_mfma_f32_16x16x32_bf16 v[4:7], v[224:227], v[216:219], v[4:7]
	v_mfma_f32_16x16x32_bf16 v[0:3], v[232:235], v[216:219], v[0:3]
	v_mfma_f32_16x16x32_bf16 v[52:55], v[228:231], v[196:199], v[52:55]
	v_mfma_f32_16x16x32_bf16 v[48:51], v[236:239], v[196:199], v[48:51]
	v_mfma_f32_16x16x32_bf16 v[36:39], v[228:231], v[204:207], v[36:39]
	v_mfma_f32_16x16x32_bf16 v[32:35], v[236:239], v[204:207], v[32:35]
	v_mfma_f32_16x16x32_bf16 v[20:23], v[228:231], v[212:215], v[20:23]
	v_mfma_f32_16x16x32_bf16 v[16:19], v[236:239], v[212:215], v[16:19]
	v_mfma_f32_16x16x32_bf16 v[4:7], v[228:231], v[220:223], v[4:7]
	v_mfma_f32_16x16x32_bf16 v[0:3], v[236:239], v[220:223], v[0:3]
	s_barrier
	s_cbranch_scc0 .LBB0_1093
.LBB0_1093:
	ds_read_b128 v[146:149], v167
	ds_read_b128 v[150:153], v167 offset:1024
	ds_read_b128 v[178:181], v167 offset:2048
	ds_read_b128 v[182:185], v167 offset:3072
	s_add_u32 s28, s0, 0xfffc0080
	s_addc_u32 s29, s1, -1
	s_cmp_eq_u32 s64, 12
	s_cselect_b32 s45, s37, s29
	s_cselect_b32 s44, s60, s28
	s_cselect_b32 s43, s13, s63
	s_cselect_b32 s42, s61, s62
	v_lshl_add_u64 v[156:157], s[0:1], 0, v[138:139]
	s_add_i32 m0, s47, 0xc000
	ds_read_b128 v[186:189], v171
	ds_read_b128 v[196:199], v171 offset:1024
	ds_read_b128 v[200:203], v171 offset:2048
	ds_read_b128 v[204:207], v171 offset:3072
	ds_read_b128 v[208:211], v171 offset:4096
	ds_read_b128 v[212:215], v171 offset:5120
	ds_read_b128 v[216:219], v171 offset:6144
	ds_read_b128 v[220:223], v171 offset:7168
	global_load_lds_dwordx4 v[156:157], off
	v_lshl_add_u64 v[156:157], s[0:1], 0, v[140:141]
	s_add_i32 m0, s47, 0xe000
	s_nop 0
	global_load_lds_dwordx4 v[156:157], off
	s_waitcnt lgkmcnt(8)
	s_barrier
	s_waitcnt lgkmcnt(0)
	v_mfma_f32_16x16x32_bf16 v[124:127], v[146:149], v[186:189], v[124:127]
	v_mfma_f32_16x16x32_bf16 v[120:123], v[178:181], v[186:189], v[120:123]
	v_mfma_f32_16x16x32_bf16 v[108:111], v[146:149], v[200:203], v[108:111]
	v_mfma_f32_16x16x32_bf16 v[104:107], v[178:181], v[200:203], v[104:107]
	v_mfma_f32_16x16x32_bf16 v[92:95], v[146:149], v[208:211], v[92:95]
	v_mfma_f32_16x16x32_bf16 v[88:91], v[178:181], v[208:211], v[88:91]
	v_mfma_f32_16x16x32_bf16 v[76:79], v[146:149], v[216:219], v[76:79]
	v_mfma_f32_16x16x32_bf16 v[72:75], v[178:181], v[216:219], v[72:75]
	v_mfma_f32_16x16x32_bf16 v[124:127], v[150:153], v[196:199], v[124:127]
	v_mfma_f32_16x16x32_bf16 v[120:123], v[182:185], v[196:199], v[120:123]
	v_mfma_f32_16x16x32_bf16 v[108:111], v[150:153], v[204:207], v[108:111]
	v_mfma_f32_16x16x32_bf16 v[104:107], v[182:185], v[204:207], v[104:107]
	v_mfma_f32_16x16x32_bf16 v[92:95], v[150:153], v[212:215], v[92:95]
	v_mfma_f32_16x16x32_bf16 v[88:91], v[182:185], v[212:215], v[88:91]
	v_mfma_f32_16x16x32_bf16 v[76:79], v[150:153], v[220:223], v[76:79]
	v_mfma_f32_16x16x32_bf16 v[72:75], v[182:185], v[220:223], v[72:75]
	s_barrier
	s_add_i32 s28, s56, s11
	v_lshl_add_u64 v[156:157], s[42:43], 0, v[132:133]
	s_mov_b32 m0, s28
	ds_read_b128 v[224:227], v175
	ds_read_b128 v[228:231], v175 offset:1024
	ds_read_b128 v[232:235], v175 offset:2048
	ds_read_b128 v[236:239], v175 offset:3072
	global_load_lds_dwordx4 v[156:157], off
	v_lshl_add_u64 v[160:161], s[42:43], 0, v[128:129]
	s_add_i32 m0, s28, 0x2000
	s_nop 0
	global_load_lds_dwordx4 v[160:161], off
	s_barrier
	s_waitcnt lgkmcnt(0)
	v_mfma_f32_16x16x32_bf16 v[116:119], v[224:227], v[186:189], v[116:119]
	v_mfma_f32_16x16x32_bf16 v[112:115], v[232:235], v[186:189], v[112:115]
	v_mfma_f32_16x16x32_bf16 v[100:103], v[224:227], v[200:203], v[100:103]
	v_mfma_f32_16x16x32_bf16 v[96:99], v[232:235], v[200:203], v[96:99]
	v_mfma_f32_16x16x32_bf16 v[84:87], v[224:227], v[208:211], v[84:87]
	v_mfma_f32_16x16x32_bf16 v[80:83], v[232:235], v[208:211], v[80:83]
	v_mfma_f32_16x16x32_bf16 v[68:71], v[224:227], v[216:219], v[68:71]
	v_mfma_f32_16x16x32_bf16 v[64:67], v[232:235], v[216:219], v[64:67]
	v_mfma_f32_16x16x32_bf16 v[116:119], v[228:231], v[196:199], v[116:119]
	v_mfma_f32_16x16x32_bf16 v[112:115], v[236:239], v[196:199], v[112:115]
	v_mfma_f32_16x16x32_bf16 v[100:103], v[228:231], v[204:207], v[100:103]
	v_mfma_f32_16x16x32_bf16 v[96:99], v[236:239], v[204:207], v[96:99]
	v_mfma_f32_16x16x32_bf16 v[84:87], v[228:231], v[212:215], v[84:87]
	v_mfma_f32_16x16x32_bf16 v[80:83], v[236:239], v[212:215], v[80:83]
	v_mfma_f32_16x16x32_bf16 v[68:71], v[228:231], v[220:223], v[68:71]
	v_mfma_f32_16x16x32_bf16 v[64:67], v[236:239], v[220:223], v[64:67]
	s_barrier
	s_mov_b32 m0, s47
	v_lshl_add_u64 v[164:165], s[44:45], 0, v[134:135]
	ds_read_b128 v[186:189], v171 offset:16384
	ds_read_b128 v[196:199], v171 offset:17408
	ds_read_b128 v[200:203], v171 offset:18432
	ds_read_b128 v[204:207], v171 offset:19456
	ds_read_b128 v[208:211], v171 offset:20480
	ds_read_b128 v[212:215], v171 offset:21504
	ds_read_b128 v[216:219], v171 offset:22528
	ds_read_b128 v[220:223], v171 offset:23552
	global_load_lds_dwordx4 v[164:165], off
	v_lshl_add_u64 v[168:169], s[44:45], 0, v[130:131]
	s_mov_b32 m0, s48
	s_nop 0
	global_load_lds_dwordx4 v[168:169], off
	s_barrier
	s_waitcnt lgkmcnt(0)
	v_mfma_f32_16x16x32_bf16 v[60:63], v[146:149], v[186:189], v[60:63]
	v_mfma_f32_16x16x32_bf16 v[56:59], v[178:181], v[186:189], v[56:59]
	v_mfma_f32_16x16x32_bf16 v[44:47], v[146:149], v[200:203], v[44:47]
	v_mfma_f32_16x16x32_bf16 v[40:43], v[178:181], v[200:203], v[40:43]
	v_mfma_f32_16x16x32_bf16 v[28:31], v[146:149], v[208:211], v[28:31]
	v_mfma_f32_16x16x32_bf16 v[24:27], v[178:181], v[208:211], v[24:27]
	v_mfma_f32_16x16x32_bf16 v[12:15], v[146:149], v[216:219], v[12:15]
	v_mfma_f32_16x16x32_bf16 v[8:11], v[178:181], v[216:219], v[8:11]
	v_mfma_f32_16x16x32_bf16 v[60:63], v[150:153], v[196:199], v[60:63]
	v_mfma_f32_16x16x32_bf16 v[56:59], v[182:185], v[196:199], v[56:59]
	v_mfma_f32_16x16x32_bf16 v[44:47], v[150:153], v[204:207], v[44:47]
	v_mfma_f32_16x16x32_bf16 v[40:43], v[182:185], v[204:207], v[40:43]
	v_mfma_f32_16x16x32_bf16 v[28:31], v[150:153], v[212:215], v[28:31]
	v_mfma_f32_16x16x32_bf16 v[24:27], v[182:185], v[212:215], v[24:27]
	v_mfma_f32_16x16x32_bf16 v[12:15], v[150:153], v[220:223], v[12:15]
	v_mfma_f32_16x16x32_bf16 v[8:11], v[182:185], v[220:223], v[8:11]
	s_barrier
	s_add_u32 s66, s42, 0x40000
	s_addc_u32 s67, s43, 0
	s_add_i32 s28, s57, s11
	v_lshl_add_u64 v[146:147], s[66:67], 0, v[132:133]
	s_mov_b32 m0, s28
	s_nop 0
	global_load_lds_dwordx4 v[146:147], off
	v_lshl_add_u64 v[146:147], s[66:67], 0, v[128:129]
	s_add_i32 m0, s28, 0x2000
	s_nop 0
	global_load_lds_dwordx4 v[146:147], off
	s_waitcnt vmcnt(6)
	s_barrier
	v_mfma_f32_16x16x32_bf16 v[52:55], v[224:227], v[186:189], v[52:55]
	v_mfma_f32_16x16x32_bf16 v[48:51], v[232:235], v[186:189], v[48:51]
	v_mfma_f32_16x16x32_bf16 v[36:39], v[224:227], v[200:203], v[36:39]
	v_mfma_f32_16x16x32_bf16 v[32:35], v[232:235], v[200:203], v[32:35]
	v_mfma_f32_16x16x32_bf16 v[20:23], v[224:227], v[208:211], v[20:23]
	v_mfma_f32_16x16x32_bf16 v[16:19], v[232:235], v[208:211], v[16:19]
	v_mfma_f32_16x16x32_bf16 v[4:7], v[224:227], v[216:219], v[4:7]
	v_mfma_f32_16x16x32_bf16 v[0:3], v[232:235], v[216:219], v[0:3]
	v_mfma_f32_16x16x32_bf16 v[52:55], v[228:231], v[196:199], v[52:55]
	v_mfma_f32_16x16x32_bf16 v[48:51], v[236:239], v[196:199], v[48:51]
	v_mfma_f32_16x16x32_bf16 v[36:39], v[228:231], v[204:207], v[36:39]
	v_mfma_f32_16x16x32_bf16 v[32:35], v[236:239], v[204:207], v[32:35]
	v_mfma_f32_16x16x32_bf16 v[20:23], v[228:231], v[212:215], v[20:23]
	v_mfma_f32_16x16x32_bf16 v[16:19], v[236:239], v[212:215], v[16:19]
	v_mfma_f32_16x16x32_bf16 v[4:7], v[228:231], v[220:223], v[4:7]
	v_mfma_f32_16x16x32_bf16 v[0:3], v[236:239], v[220:223], v[0:3]
	s_barrier
	s_add_i32 s28, 0, 0x18000
	v_add_u32_e32 v154, s28, v159
	ds_read_b128 v[146:149], v154
	ds_read_b128 v[150:153], v154 offset:1024
	ds_read_b128 v[178:181], v154 offset:2048
	ds_read_b128 v[182:185], v154 offset:3072
	s_add_u32 s44, s44, 0x40000
	s_addc_u32 s45, s45, 0
	s_mov_b32 m0, s49
	v_lshl_add_u64 v[172:173], s[44:45], 0, v[134:135]
	ds_read_b128 v[186:189], v171 offset:32768
	ds_read_b128 v[196:199], v171 offset:33792
	ds_read_b128 v[200:203], v171 offset:34816
	ds_read_b128 v[204:207], v171 offset:35840
	ds_read_b128 v[208:211], v171 offset:36864
	ds_read_b128 v[212:215], v171 offset:37888
	ds_read_b128 v[216:219], v171 offset:38912
	ds_read_b128 v[220:223], v171 offset:39936
	global_load_lds_dwordx4 v[172:173], off
	v_lshl_add_u64 v[172:173], s[44:45], 0, v[130:131]
	s_mov_b32 m0, s50
	s_nop 0
	global_load_lds_dwordx4 v[172:173], off
	s_waitcnt lgkmcnt(8)
	s_barrier
	s_waitcnt lgkmcnt(0)
	v_mfma_f32_16x16x32_bf16 v[124:127], v[146:149], v[186:189], v[124:127]
	v_mfma_f32_16x16x32_bf16 v[120:123], v[178:181], v[186:189], v[120:123]
	v_mfma_f32_16x16x32_bf16 v[108:111], v[146:149], v[200:203], v[108:111]
	v_mfma_f32_16x16x32_bf16 v[104:107], v[178:181], v[200:203], v[104:107]
	v_mfma_f32_16x16x32_bf16 v[92:95], v[146:149], v[208:211], v[92:95]
	v_mfma_f32_16x16x32_bf16 v[88:91], v[178:181], v[208:211], v[88:91]
	v_mfma_f32_16x16x32_bf16 v[76:79], v[146:149], v[216:219], v[76:79]
	v_mfma_f32_16x16x32_bf16 v[72:75], v[178:181], v[216:219], v[72:75]
	v_mfma_f32_16x16x32_bf16 v[124:127], v[150:153], v[196:199], v[124:127]
	v_mfma_f32_16x16x32_bf16 v[120:123], v[182:185], v[196:199], v[120:123]
	v_mfma_f32_16x16x32_bf16 v[108:111], v[150:153], v[204:207], v[108:111]
	v_mfma_f32_16x16x32_bf16 v[104:107], v[182:185], v[204:207], v[104:107]
	v_mfma_f32_16x16x32_bf16 v[92:95], v[150:153], v[212:215], v[92:95]
	v_mfma_f32_16x16x32_bf16 v[88:91], v[182:185], v[212:215], v[88:91]
	v_mfma_f32_16x16x32_bf16 v[76:79], v[150:153], v[220:223], v[76:79]
	v_mfma_f32_16x16x32_bf16 v[72:75], v[182:185], v[220:223], v[72:75]
	s_barrier
	s_add_i32 s29, 0, 0x1c000
	s_add_i32 s28, s28, s11
	v_add_u32_e32 v154, s29, v159
	v_lshl_add_u64 v[156:157], v[156:157], 0, s[6:7]
	s_mov_b32 m0, s28
	ds_read_b128 v[224:227], v154
	ds_read_b128 v[228:231], v154 offset:1024
	ds_read_b128 v[232:235], v154 offset:2048
	ds_read_b128 v[236:239], v154 offset:3072
	global_load_lds_dwordx4 v[156:157], off
	v_lshl_add_u64 v[156:157], v[160:161], 0, s[6:7]
	s_add_i32 m0, s28, 0x2000
	s_nop 0
	global_load_lds_dwordx4 v[156:157], off
	s_barrier
	s_waitcnt lgkmcnt(0)
	v_mfma_f32_16x16x32_bf16 v[116:119], v[224:227], v[186:189], v[116:119]
	v_mfma_f32_16x16x32_bf16 v[112:115], v[232:235], v[186:189], v[112:115]
	v_mfma_f32_16x16x32_bf16 v[100:103], v[224:227], v[200:203], v[100:103]
	v_mfma_f32_16x16x32_bf16 v[96:99], v[232:235], v[200:203], v[96:99]
	v_mfma_f32_16x16x32_bf16 v[84:87], v[224:227], v[208:211], v[84:87]
	v_mfma_f32_16x16x32_bf16 v[80:83], v[232:235], v[208:211], v[80:83]
	v_mfma_f32_16x16x32_bf16 v[68:71], v[224:227], v[216:219], v[68:71]
	v_mfma_f32_16x16x32_bf16 v[64:67], v[232:235], v[216:219], v[64:67]
	v_mfma_f32_16x16x32_bf16 v[116:119], v[228:231], v[196:199], v[116:119]
	v_mfma_f32_16x16x32_bf16 v[112:115], v[236:239], v[196:199], v[112:115]
	v_mfma_f32_16x16x32_bf16 v[100:103], v[228:231], v[204:207], v[100:103]
	v_mfma_f32_16x16x32_bf16 v[96:99], v[236:239], v[204:207], v[96:99]
	v_mfma_f32_16x16x32_bf16 v[84:87], v[228:231], v[212:215], v[84:87]
	v_mfma_f32_16x16x32_bf16 v[80:83], v[236:239], v[212:215], v[80:83]
	v_mfma_f32_16x16x32_bf16 v[68:71], v[228:231], v[220:223], v[68:71]
	v_mfma_f32_16x16x32_bf16 v[64:67], v[236:239], v[220:223], v[64:67]
	s_barrier
	s_mov_b32 m0, s53
	v_lshl_add_u64 v[156:157], v[164:165], 0, s[6:7]
	ds_read_b128 v[186:189], v171 offset:49152
	ds_read_b128 v[196:199], v171 offset:50176
	ds_read_b128 v[200:203], v171 offset:51200
	ds_read_b128 v[204:207], v171 offset:52224
	ds_read_b128 v[208:211], v171 offset:53248
	ds_read_b128 v[212:215], v171 offset:54272
	ds_read_b128 v[216:219], v171 offset:55296
	ds_read_b128 v[220:223], v171 offset:56320
	global_load_lds_dwordx4 v[156:157], off
	v_lshl_add_u64 v[156:157], v[168:169], 0, s[6:7]
	s_mov_b32 m0, s54
	s_nop 0
	global_load_lds_dwordx4 v[156:157], off
	s_barrier
	s_waitcnt lgkmcnt(0)
	v_mfma_f32_16x16x32_bf16 v[60:63], v[146:149], v[186:189], v[60:63]
	v_mfma_f32_16x16x32_bf16 v[56:59], v[178:181], v[186:189], v[56:59]
	v_mfma_f32_16x16x32_bf16 v[44:47], v[146:149], v[200:203], v[44:47]
	v_mfma_f32_16x16x32_bf16 v[40:43], v[178:181], v[200:203], v[40:43]
	v_mfma_f32_16x16x32_bf16 v[28:31], v[146:149], v[208:211], v[28:31]
	v_mfma_f32_16x16x32_bf16 v[24:27], v[178:181], v[208:211], v[24:27]
	v_mfma_f32_16x16x32_bf16 v[12:15], v[146:149], v[216:219], v[12:15]
	v_mfma_f32_16x16x32_bf16 v[8:11], v[178:181], v[216:219], v[8:11]
	v_mfma_f32_16x16x32_bf16 v[60:63], v[150:153], v[196:199], v[60:63]
	v_mfma_f32_16x16x32_bf16 v[56:59], v[182:185], v[196:199], v[56:59]
	v_mfma_f32_16x16x32_bf16 v[44:47], v[150:153], v[204:207], v[44:47]
	v_mfma_f32_16x16x32_bf16 v[40:43], v[182:185], v[204:207], v[40:43]
	v_mfma_f32_16x16x32_bf16 v[28:31], v[150:153], v[212:215], v[28:31]
	v_mfma_f32_16x16x32_bf16 v[24:27], v[182:185], v[212:215], v[24:27]
	v_mfma_f32_16x16x32_bf16 v[12:15], v[150:153], v[220:223], v[12:15]
	v_mfma_f32_16x16x32_bf16 v[8:11], v[182:185], v[220:223], v[8:11]
	s_barrier
	s_add_u32 s42, s42, 0x40080
	s_addc_u32 s43, s43, 0
	s_add_i32 s28, s29, s11
	v_lshl_add_u64 v[146:147], s[42:43], 0, v[132:133]
	s_mov_b32 m0, s28
	s_nop 0
	global_load_lds_dwordx4 v[146:147], off
	v_lshl_add_u64 v[146:147], s[42:43], 0, v[128:129]
	s_add_i32 m0, s28, 0x2000
	s_nop 0
	global_load_lds_dwordx4 v[146:147], off
	s_add_i32 s64, s64, 2
	s_add_u32 s0, s0, 0x100
	s_addc_u32 s1, s1, 0
	s_add_u32 s62, s62, 0x100
	s_addc_u32 s63, s63, 0
	s_cmp_gt_u32 s64, 13
	s_waitcnt vmcnt(6)
	s_barrier
	v_mfma_f32_16x16x32_bf16 v[52:55], v[224:227], v[186:189], v[52:55]
	v_mfma_f32_16x16x32_bf16 v[48:51], v[232:235], v[186:189], v[48:51]
	v_mfma_f32_16x16x32_bf16 v[36:39], v[224:227], v[200:203], v[36:39]
	v_mfma_f32_16x16x32_bf16 v[32:35], v[232:235], v[200:203], v[32:35]
	v_mfma_f32_16x16x32_bf16 v[20:23], v[224:227], v[208:211], v[20:23]
	v_mfma_f32_16x16x32_bf16 v[16:19], v[232:235], v[208:211], v[16:19]
	v_mfma_f32_16x16x32_bf16 v[4:7], v[224:227], v[216:219], v[4:7]
	v_mfma_f32_16x16x32_bf16 v[0:3], v[232:235], v[216:219], v[0:3]
	v_mfma_f32_16x16x32_bf16 v[52:55], v[228:231], v[196:199], v[52:55]
	v_mfma_f32_16x16x32_bf16 v[48:51], v[236:239], v[196:199], v[48:51]
	v_mfma_f32_16x16x32_bf16 v[36:39], v[228:231], v[204:207], v[36:39]
	v_mfma_f32_16x16x32_bf16 v[32:35], v[236:239], v[204:207], v[32:35]
	v_mfma_f32_16x16x32_bf16 v[20:23], v[228:231], v[212:215], v[20:23]
	v_mfma_f32_16x16x32_bf16 v[16:19], v[236:239], v[212:215], v[16:19]
	v_mfma_f32_16x16x32_bf16 v[4:7], v[228:231], v[220:223], v[4:7]
	v_mfma_f32_16x16x32_bf16 v[0:3], v[236:239], v[220:223], v[0:3]
	s_barrier
	s_cbranch_scc0 .LBB0_1093
	v_lshl_add_u32 v168, s4, 8, v155
	v_or_b32_e32 v164, 16, v168
	v_or_b32_e32 v160, 32, v168
	v_or_b32_e32 v156, 48, v168
	v_add_u32_e32 v152, 0x80, v168
	v_add_u32_e32 v150, 0x90, v168
	v_add_u32_e32 v148, 0xa0, v168
	v_add_u32_e32 v146, 0xb0, v168
	v_lshl_or_b32 v172, s5, 7, v163
	v_mov_b32_e32 v178, v240
	v_mov_b32_e32 v179, v240
	v_mov_b32_e32 v154, v241
	s_and_b32 s0, s36, 0x7f
	v_lshl_add_u32 v228, s0, 8, v155
	v_mov_b32_e32 v229, 0
	v_lshlrev_b32_e32 v228, 6, v228
	v_lshl_add_u64 v[230:231], v[136:137], 0, v[228:229]
	v_mov_b32_e32 v228, 0x2000
	v_lshl_add_u64 v[232:233], v[230:231], 0, v[228:229]
	global_load_dwordx4 v[216:219], v[230:231], off
	global_load_dwordx4 v[220:223], v[230:231], off offset:1024
	global_load_dwordx4 v[224:227], v[230:231], off offset:2048
	global_load_dwordx4 v[196:199], v[230:231], off offset:3072
	global_load_dwordx4 v[200:203], v[232:233], off
	global_load_dwordx4 v[204:207], v[232:233], off offset:1024
	global_load_dwordx4 v[208:211], v[232:233], off offset:2048
	global_load_dwordx4 v[212:215], v[232:233], off offset:3072
	v_pk_mul_f32 v[124:125], v[124:125], v[178:179] op_sel_hi:[1,0]
	v_pk_mul_f32 v[126:127], v[126:127], v[178:179] op_sel_hi:[1,0]
	v_mul_f32_e32 v147, 0xbfb8aa3b, v124
	v_exp_f32_e32 v147, v147
	v_mul_f32_e32 v149, 0xbfb8aa3b, v125
	v_exp_f32_e32 v149, v149
	v_mul_f32_e32 v151, 0xbfb8aa3b, v127
	v_add_f32_e32 v147, 1.0, v147
	v_rcp_f32_e32 v180, v147
	v_add_f32_e32 v147, 1.0, v149
	v_mul_f32_e32 v149, 0xbfb8aa3b, v126
	v_exp_f32_e32 v149, v149
	v_exp_f32_e32 v151, v151
	v_rcp_f32_e32 v181, v147
	v_pk_mul_f32 v[116:117], v[116:117], v[178:179] op_sel_hi:[1,0]
	v_add_f32_e32 v147, 1.0, v149
	v_rcp_f32_e32 v182, v147
	v_add_f32_e32 v147, 1.0, v151
	v_rcp_f32_e32 v183, v147
	v_pk_mul_f32 v[124:125], v[124:125], v[180:181]
	v_pk_mul_f32 v[120:121], v[120:121], v[178:179] op_sel_hi:[1,0]
	v_pk_mul_f32 v[116:117], v[116:117], v[124:125]
	v_pk_mul_f32 v[124:125], v[126:127], v[182:183]
	v_mul_f32_e32 v126, 0xbfb8aa3b, v120
	v_exp_f32_e32 v126, v126
	v_pk_mul_f32 v[118:119], v[118:119], v[178:179] op_sel_hi:[1,0]
	v_pk_mul_f32 v[122:123], v[122:123], v[178:179] op_sel_hi:[1,0]
	v_pk_mul_f32 v[118:119], v[118:119], v[124:125]
	v_mul_f32_e32 v124, 0xbfb8aa3b, v121
	v_exp_f32_e32 v125, v124
	v_add_f32_e32 v124, 1.0, v126
	v_mul_f32_e32 v126, 0xbfb8aa3b, v122
	v_mul_f32_e32 v127, 0xbfb8aa3b, v123
	v_exp_f32_e32 v126, v126
	v_exp_f32_e32 v127, v127
	v_add_f32_e32 v125, 1.0, v125
	v_rcp_f32_e32 v124, v124
	v_rcp_f32_e32 v125, v125
	v_add_f32_e32 v126, 1.0, v126
	v_add_f32_e32 v127, 1.0, v127
	v_rcp_f32_e32 v126, v126
	v_rcp_f32_e32 v127, v127
	v_pk_mul_f32 v[112:113], v[112:113], v[178:179] op_sel_hi:[1,0]
	v_pk_mul_f32 v[120:121], v[120:121], v[124:125]
	v_pk_mul_f32 v[114:115], v[114:115], v[178:179] op_sel_hi:[1,0]
	v_pk_mul_f32 v[112:113], v[112:113], v[120:121]
	v_pk_mul_f32 v[120:121], v[122:123], v[126:127]
	v_ashrrev_i32_e32 v173, 31, v172
	v_pk_mul_f32 v[114:115], v[114:115], v[120:121]
	v_cvt_pk_bf16_f32 v116, v116, v117
	v_cvt_pk_bf16_f32 v117, v118, v119
	v_cvt_pk_bf16_f32 v118, v112, v113
	v_mov_b64_e32 v[112:113], s[20:21]
	v_cvt_pk_bf16_f32 v119, v114, v115
	v_mad_i64_i32 v[120:121], s[0:1], v168, s59, v[112:113]
	v_lshlrev_b64 v[114:115], 1, v[172:173]
	v_lshl_add_u64 v[120:121], v[120:121], 0, v[114:115]
	v_pk_mul_f32 v[108:109], v[108:109], v[176:177] op_sel_hi:[1,0]
	global_store_dwordx4 v[120:121], v[116:119], off
	v_mul_f32_e32 v122, 0xbfb8aa3b, v108
	v_pk_mul_f32 v[110:111], v[110:111], v[176:177] op_sel_hi:[1,0]
	v_mul_f32_e32 v116, 0xbfb8aa3b, v109
	v_exp_f32_e32 v122, v122
	v_exp_f32_e32 v117, v116
	v_mul_f32_e32 v118, 0xbfb8aa3b, v110
	v_mul_f32_e32 v119, 0xbfb8aa3b, v111
	v_exp_f32_e32 v118, v118
	v_exp_f32_e32 v119, v119
	v_add_f32_e32 v116, 1.0, v122
	v_add_f32_e32 v117, 1.0, v117
	v_rcp_f32_e32 v116, v116
	v_rcp_f32_e32 v117, v117
	v_add_f32_e32 v118, 1.0, v118
	v_add_f32_e32 v119, 1.0, v119
	v_rcp_f32_e32 v118, v118
	v_rcp_f32_e32 v119, v119
	v_pk_mul_f32 v[100:101], v[100:101], v[176:177] op_sel_hi:[1,0]
	v_pk_mul_f32 v[108:109], v[108:109], v[116:117]
	v_pk_mul_f32 v[104:105], v[104:105], v[176:177] op_sel_hi:[1,0]
	v_pk_mul_f32 v[100:101], v[100:101], v[108:109]
	v_pk_mul_f32 v[108:109], v[110:111], v[118:119]
	v_mul_f32_e32 v110, 0xbfb8aa3b, v104
	v_exp_f32_e32 v110, v110
	v_pk_mul_f32 v[102:103], v[102:103], v[176:177] op_sel_hi:[1,0]
	v_pk_mul_f32 v[106:107], v[106:107], v[176:177] op_sel_hi:[1,0]
	v_pk_mul_f32 v[102:103], v[102:103], v[108:109]
	v_mul_f32_e32 v108, 0xbfb8aa3b, v105
	v_exp_f32_e32 v109, v108
	v_add_f32_e32 v108, 1.0, v110
	v_mul_f32_e32 v110, 0xbfb8aa3b, v106
	v_mul_f32_e32 v111, 0xbfb8aa3b, v107
	v_exp_f32_e32 v110, v110
	v_exp_f32_e32 v111, v111
	v_add_f32_e32 v109, 1.0, v109
	v_rcp_f32_e32 v108, v108
	v_rcp_f32_e32 v109, v109
	v_add_f32_e32 v110, 1.0, v110
	v_add_f32_e32 v111, 1.0, v111
	v_rcp_f32_e32 v110, v110
	v_rcp_f32_e32 v111, v111
	v_pk_mul_f32 v[96:97], v[96:97], v[176:177] op_sel_hi:[1,0]
	v_pk_mul_f32 v[104:105], v[104:105], v[108:109]
	v_pk_mul_f32 v[92:93], v[92:93], v[174:175] op_sel_hi:[1,0]
	v_pk_mul_f32 v[104:105], v[96:97], v[104:105]
	v_pk_mul_f32 v[96:97], v[98:99], v[176:177] op_sel_hi:[1,0]
	v_pk_mul_f32 v[98:99], v[106:107], v[110:111]
	v_pk_mul_f32 v[94:95], v[94:95], v[174:175] op_sel_hi:[1,0]
	v_pk_mul_f32 v[106:107], v[96:97], v[98:99]
	v_cvt_pk_bf16_f32 v96, v100, v101
	v_mad_i64_i32 v[100:101], s[0:1], v164, s59, v[112:113]
	v_cvt_pk_bf16_f32 v97, v102, v103
	v_cvt_pk_bf16_f32 v98, v104, v105
	v_cvt_pk_bf16_f32 v99, v106, v107
	v_lshl_add_u64 v[100:101], v[100:101], 0, v[114:115]
	v_mul_f32_e32 v102, 0xbfb8aa3b, v92
	global_store_dwordx4 v[100:101], v[96:99], off
	v_exp_f32_e32 v102, v102
	v_pk_mul_f32 v[84:85], v[84:85], v[174:175] op_sel_hi:[1,0]
	v_mul_f32_e32 v96, 0xbfb8aa3b, v93
	v_exp_f32_e32 v97, v96
	v_mul_f32_e32 v98, 0xbfb8aa3b, v94
	v_mul_f32_e32 v99, 0xbfb8aa3b, v95
	v_exp_f32_e32 v98, v98
	v_exp_f32_e32 v99, v99
	v_add_f32_e32 v96, 1.0, v102
	v_add_f32_e32 v97, 1.0, v97
	v_rcp_f32_e32 v96, v96
	v_rcp_f32_e32 v97, v97
	v_add_f32_e32 v98, 1.0, v98
	v_add_f32_e32 v99, 1.0, v99
	v_rcp_f32_e32 v98, v98
	v_rcp_f32_e32 v99, v99
	v_pk_mul_f32 v[92:93], v[92:93], v[96:97]
	v_pk_mul_f32 v[88:89], v[88:89], v[174:175] op_sel_hi:[1,0]
	v_pk_mul_f32 v[84:85], v[84:85], v[92:93]
	v_pk_mul_f32 v[92:93], v[94:95], v[98:99]
	v_mul_f32_e32 v94, 0xbfb8aa3b, v88
	v_exp_f32_e32 v94, v94
	v_pk_mul_f32 v[86:87], v[86:87], v[174:175] op_sel_hi:[1,0]
	v_pk_mul_f32 v[90:91], v[90:91], v[174:175] op_sel_hi:[1,0]
	v_pk_mul_f32 v[86:87], v[86:87], v[92:93]
	v_mul_f32_e32 v92, 0xbfb8aa3b, v89
	v_exp_f32_e32 v93, v92
	v_add_f32_e32 v92, 1.0, v94
	v_mul_f32_e32 v94, 0xbfb8aa3b, v90
	v_mul_f32_e32 v95, 0xbfb8aa3b, v91
	v_exp_f32_e32 v94, v94
	v_exp_f32_e32 v95, v95
	v_add_f32_e32 v93, 1.0, v93
	v_rcp_f32_e32 v92, v92
	v_rcp_f32_e32 v93, v93
	v_add_f32_e32 v94, 1.0, v94
	v_add_f32_e32 v95, 1.0, v95
	v_rcp_f32_e32 v94, v94
	v_rcp_f32_e32 v95, v95
	v_pk_mul_f32 v[80:81], v[80:81], v[174:175] op_sel_hi:[1,0]
	v_pk_mul_f32 v[88:89], v[88:89], v[92:93]
	v_pk_mul_f32 v[76:77], v[76:77], v[170:171] op_sel_hi:[1,0]
	v_pk_mul_f32 v[88:89], v[80:81], v[88:89]
	v_pk_mul_f32 v[80:81], v[82:83], v[174:175] op_sel_hi:[1,0]
	v_pk_mul_f32 v[82:83], v[90:91], v[94:95]
	v_pk_mul_f32 v[78:79], v[78:79], v[170:171] op_sel_hi:[1,0]
	v_pk_mul_f32 v[90:91], v[80:81], v[82:83]
	v_cvt_pk_bf16_f32 v80, v84, v85
	v_mad_i64_i32 v[84:85], s[0:1], v160, s59, v[112:113]
	v_cvt_pk_bf16_f32 v81, v86, v87
	v_cvt_pk_bf16_f32 v82, v88, v89
	v_cvt_pk_bf16_f32 v83, v90, v91
	v_lshl_add_u64 v[84:85], v[84:85], 0, v[114:115]
	v_mul_f32_e32 v86, 0xbfb8aa3b, v76
	global_store_dwordx4 v[84:85], v[80:83], off
	v_exp_f32_e32 v86, v86
	v_pk_mul_f32 v[68:69], v[68:69], v[170:171] op_sel_hi:[1,0]
	v_mul_f32_e32 v80, 0xbfb8aa3b, v77
	v_exp_f32_e32 v81, v80
	v_mul_f32_e32 v82, 0xbfb8aa3b, v78
	v_mul_f32_e32 v83, 0xbfb8aa3b, v79
	v_exp_f32_e32 v82, v82
	v_exp_f32_e32 v83, v83
	v_add_f32_e32 v80, 1.0, v86
	v_add_f32_e32 v81, 1.0, v81
	v_rcp_f32_e32 v80, v80
	v_rcp_f32_e32 v81, v81
	v_add_f32_e32 v82, 1.0, v82
	v_add_f32_e32 v83, 1.0, v83
	v_rcp_f32_e32 v82, v82
	v_rcp_f32_e32 v83, v83
	v_pk_mul_f32 v[76:77], v[76:77], v[80:81]
	v_pk_mul_f32 v[72:73], v[72:73], v[170:171] op_sel_hi:[1,0]
	v_pk_mul_f32 v[68:69], v[68:69], v[76:77]
	v_pk_mul_f32 v[76:77], v[78:79], v[82:83]
	v_mul_f32_e32 v78, 0xbfb8aa3b, v72
	v_exp_f32_e32 v78, v78
	v_pk_mul_f32 v[70:71], v[70:71], v[170:171] op_sel_hi:[1,0]
	v_pk_mul_f32 v[74:75], v[74:75], v[170:171] op_sel_hi:[1,0]
	v_pk_mul_f32 v[70:71], v[70:71], v[76:77]
	v_mul_f32_e32 v76, 0xbfb8aa3b, v73
	v_exp_f32_e32 v77, v76
	v_add_f32_e32 v76, 1.0, v78
	v_mul_f32_e32 v78, 0xbfb8aa3b, v74
	v_mul_f32_e32 v79, 0xbfb8aa3b, v75
	v_exp_f32_e32 v78, v78
	v_exp_f32_e32 v79, v79
	v_add_f32_e32 v77, 1.0, v77
	v_rcp_f32_e32 v76, v76
	v_rcp_f32_e32 v77, v77
	v_add_f32_e32 v78, 1.0, v78
	v_add_f32_e32 v79, 1.0, v79
	v_rcp_f32_e32 v78, v78
	v_rcp_f32_e32 v79, v79
	v_pk_mul_f32 v[64:65], v[64:65], v[170:171] op_sel_hi:[1,0]
	v_pk_mul_f32 v[72:73], v[72:73], v[76:77]
	v_pk_mul_f32 v[60:61], v[60:61], v[166:167] op_sel_hi:[1,0]
	v_pk_mul_f32 v[72:73], v[64:65], v[72:73]
	v_pk_mul_f32 v[64:65], v[66:67], v[170:171] op_sel_hi:[1,0]
	v_pk_mul_f32 v[66:67], v[74:75], v[78:79]
	v_pk_mul_f32 v[62:63], v[62:63], v[166:167] op_sel_hi:[1,0]
	v_pk_mul_f32 v[74:75], v[64:65], v[66:67]
	v_cvt_pk_bf16_f32 v64, v68, v69
	v_mad_i64_i32 v[68:69], s[0:1], v156, s59, v[112:113]
	v_cvt_pk_bf16_f32 v65, v70, v71
	v_cvt_pk_bf16_f32 v66, v72, v73
	v_cvt_pk_bf16_f32 v67, v74, v75
	v_lshl_add_u64 v[68:69], v[68:69], 0, v[114:115]
	v_mul_f32_e32 v70, 0xbfb8aa3b, v60
	global_store_dwordx4 v[68:69], v[64:67], off
	v_exp_f32_e32 v70, v70
	v_pk_mul_f32 v[52:53], v[52:53], v[166:167] op_sel_hi:[1,0]
	v_mul_f32_e32 v64, 0xbfb8aa3b, v61
	v_exp_f32_e32 v65, v64
	v_mul_f32_e32 v66, 0xbfb8aa3b, v62
	v_mul_f32_e32 v67, 0xbfb8aa3b, v63
	v_exp_f32_e32 v66, v66
	v_exp_f32_e32 v67, v67
	v_add_f32_e32 v64, 1.0, v70
	v_add_f32_e32 v65, 1.0, v65
	v_rcp_f32_e32 v64, v64
	v_rcp_f32_e32 v65, v65
	v_add_f32_e32 v66, 1.0, v66
	v_add_f32_e32 v67, 1.0, v67
	v_rcp_f32_e32 v66, v66
	v_rcp_f32_e32 v67, v67
	v_pk_mul_f32 v[60:61], v[60:61], v[64:65]
	v_pk_mul_f32 v[56:57], v[56:57], v[166:167] op_sel_hi:[1,0]
	v_pk_mul_f32 v[52:53], v[52:53], v[60:61]
	v_pk_mul_f32 v[60:61], v[62:63], v[66:67]
	v_mul_f32_e32 v62, 0xbfb8aa3b, v56
	v_exp_f32_e32 v62, v62
	v_pk_mul_f32 v[54:55], v[54:55], v[166:167] op_sel_hi:[1,0]
	v_pk_mul_f32 v[58:59], v[58:59], v[166:167] op_sel_hi:[1,0]
	v_pk_mul_f32 v[54:55], v[54:55], v[60:61]
	v_mul_f32_e32 v60, 0xbfb8aa3b, v57
	v_exp_f32_e32 v61, v60
	v_add_f32_e32 v60, 1.0, v62
	v_mul_f32_e32 v62, 0xbfb8aa3b, v58
	v_mul_f32_e32 v63, 0xbfb8aa3b, v59
	v_exp_f32_e32 v62, v62
	v_exp_f32_e32 v63, v63
	v_add_f32_e32 v61, 1.0, v61
	v_rcp_f32_e32 v60, v60
	v_rcp_f32_e32 v61, v61
	v_add_f32_e32 v62, 1.0, v62
	v_add_f32_e32 v63, 1.0, v63
	v_rcp_f32_e32 v62, v62
	v_rcp_f32_e32 v63, v63
	v_pk_mul_f32 v[48:49], v[48:49], v[166:167] op_sel_hi:[1,0]
	v_pk_mul_f32 v[56:57], v[56:57], v[60:61]
	v_pk_mul_f32 v[44:45], v[44:45], v[162:163] op_sel_hi:[1,0]
	v_pk_mul_f32 v[56:57], v[48:49], v[56:57]
	v_pk_mul_f32 v[48:49], v[50:51], v[166:167] op_sel_hi:[1,0]
	v_pk_mul_f32 v[50:51], v[58:59], v[62:63]
	v_pk_mul_f32 v[46:47], v[46:47], v[162:163] op_sel_hi:[1,0]
	v_pk_mul_f32 v[58:59], v[48:49], v[50:51]
	v_cvt_pk_bf16_f32 v48, v52, v53
	v_mad_i64_i32 v[52:53], s[0:1], v152, s59, v[112:113]
	v_cvt_pk_bf16_f32 v49, v54, v55
	v_cvt_pk_bf16_f32 v50, v56, v57
	v_cvt_pk_bf16_f32 v51, v58, v59
	v_lshl_add_u64 v[52:53], v[52:53], 0, v[114:115]
	v_mul_f32_e32 v54, 0xbfb8aa3b, v44
	global_store_dwordx4 v[52:53], v[48:51], off
	v_exp_f32_e32 v54, v54
	v_pk_mul_f32 v[36:37], v[36:37], v[162:163] op_sel_hi:[1,0]
	v_mul_f32_e32 v48, 0xbfb8aa3b, v45
	v_exp_f32_e32 v49, v48
	v_mul_f32_e32 v50, 0xbfb8aa3b, v46
	v_mul_f32_e32 v51, 0xbfb8aa3b, v47
	v_exp_f32_e32 v50, v50
	v_exp_f32_e32 v51, v51
	v_add_f32_e32 v48, 1.0, v54
	v_add_f32_e32 v49, 1.0, v49
	v_rcp_f32_e32 v48, v48
	v_rcp_f32_e32 v49, v49
	v_add_f32_e32 v50, 1.0, v50
	v_add_f32_e32 v51, 1.0, v51
	v_rcp_f32_e32 v50, v50
	v_rcp_f32_e32 v51, v51
	v_pk_mul_f32 v[44:45], v[44:45], v[48:49]
	v_pk_mul_f32 v[40:41], v[40:41], v[162:163] op_sel_hi:[1,0]
	v_pk_mul_f32 v[36:37], v[36:37], v[44:45]
	v_pk_mul_f32 v[44:45], v[46:47], v[50:51]
	v_mul_f32_e32 v46, 0xbfb8aa3b, v40
	v_exp_f32_e32 v46, v46
	v_pk_mul_f32 v[38:39], v[38:39], v[162:163] op_sel_hi:[1,0]
	v_pk_mul_f32 v[42:43], v[42:43], v[162:163] op_sel_hi:[1,0]
	v_pk_mul_f32 v[38:39], v[38:39], v[44:45]
	v_mul_f32_e32 v44, 0xbfb8aa3b, v41
	v_exp_f32_e32 v45, v44
	v_add_f32_e32 v44, 1.0, v46
	v_mul_f32_e32 v46, 0xbfb8aa3b, v42
	v_mul_f32_e32 v47, 0xbfb8aa3b, v43
	v_exp_f32_e32 v46, v46
	v_exp_f32_e32 v47, v47
	v_add_f32_e32 v45, 1.0, v45
	v_rcp_f32_e32 v44, v44
	v_rcp_f32_e32 v45, v45
	v_add_f32_e32 v46, 1.0, v46
	v_add_f32_e32 v47, 1.0, v47
	v_rcp_f32_e32 v46, v46
	v_rcp_f32_e32 v47, v47
	v_pk_mul_f32 v[32:33], v[32:33], v[162:163] op_sel_hi:[1,0]
	v_pk_mul_f32 v[40:41], v[40:41], v[44:45]
	v_pk_mul_f32 v[28:29], v[28:29], v[158:159] op_sel_hi:[1,0]
	v_pk_mul_f32 v[40:41], v[32:33], v[40:41]
	v_pk_mul_f32 v[32:33], v[34:35], v[162:163] op_sel_hi:[1,0]
	v_pk_mul_f32 v[34:35], v[42:43], v[46:47]
	v_pk_mul_f32 v[30:31], v[30:31], v[158:159] op_sel_hi:[1,0]
	v_pk_mul_f32 v[42:43], v[32:33], v[34:35]
	v_cvt_pk_bf16_f32 v32, v36, v37
	v_mad_i64_i32 v[36:37], s[0:1], v150, s59, v[112:113]
	v_cvt_pk_bf16_f32 v33, v38, v39
	v_cvt_pk_bf16_f32 v34, v40, v41
	v_cvt_pk_bf16_f32 v35, v42, v43
	v_lshl_add_u64 v[36:37], v[36:37], 0, v[114:115]
	v_mul_f32_e32 v38, 0xbfb8aa3b, v28
	global_store_dwordx4 v[36:37], v[32:35], off
	v_exp_f32_e32 v38, v38
	v_pk_mul_f32 v[20:21], v[20:21], v[158:159] op_sel_hi:[1,0]
	v_mul_f32_e32 v32, 0xbfb8aa3b, v29
	v_exp_f32_e32 v33, v32
	v_mul_f32_e32 v34, 0xbfb8aa3b, v30
	v_mul_f32_e32 v35, 0xbfb8aa3b, v31
	v_exp_f32_e32 v34, v34
	v_exp_f32_e32 v35, v35
	v_add_f32_e32 v32, 1.0, v38
	v_add_f32_e32 v33, 1.0, v33
	v_rcp_f32_e32 v32, v32
	v_rcp_f32_e32 v33, v33
	v_add_f32_e32 v34, 1.0, v34
	v_add_f32_e32 v35, 1.0, v35
	v_rcp_f32_e32 v34, v34
	v_rcp_f32_e32 v35, v35
	v_pk_mul_f32 v[28:29], v[28:29], v[32:33]
	v_pk_mul_f32 v[24:25], v[24:25], v[158:159] op_sel_hi:[1,0]
	v_pk_mul_f32 v[20:21], v[20:21], v[28:29]
	v_pk_mul_f32 v[28:29], v[30:31], v[34:35]
	v_mul_f32_e32 v30, 0xbfb8aa3b, v24
	v_exp_f32_e32 v30, v30
	v_pk_mul_f32 v[22:23], v[22:23], v[158:159] op_sel_hi:[1,0]
	v_pk_mul_f32 v[26:27], v[26:27], v[158:159] op_sel_hi:[1,0]
	v_pk_mul_f32 v[22:23], v[22:23], v[28:29]
	v_mul_f32_e32 v28, 0xbfb8aa3b, v25
	v_exp_f32_e32 v29, v28
	v_add_f32_e32 v28, 1.0, v30
	v_mul_f32_e32 v30, 0xbfb8aa3b, v26
	v_mul_f32_e32 v31, 0xbfb8aa3b, v27
	v_exp_f32_e32 v30, v30
	v_exp_f32_e32 v31, v31
	v_add_f32_e32 v29, 1.0, v29
	v_rcp_f32_e32 v28, v28
	v_rcp_f32_e32 v29, v29
	v_add_f32_e32 v30, 1.0, v30
	v_add_f32_e32 v31, 1.0, v31
	v_rcp_f32_e32 v30, v30
	v_rcp_f32_e32 v31, v31
	v_pk_mul_f32 v[16:17], v[16:17], v[158:159] op_sel_hi:[1,0]
	v_pk_mul_f32 v[24:25], v[24:25], v[28:29]
	v_pk_mul_f32 v[12:13], v[12:13], v[154:155] op_sel_hi:[1,0]
	v_pk_mul_f32 v[24:25], v[16:17], v[24:25]
	v_pk_mul_f32 v[16:17], v[18:19], v[158:159] op_sel_hi:[1,0]
	v_pk_mul_f32 v[18:19], v[26:27], v[30:31]
	v_pk_mul_f32 v[14:15], v[14:15], v[154:155] op_sel_hi:[1,0]
	v_pk_mul_f32 v[26:27], v[16:17], v[18:19]
	v_cvt_pk_bf16_f32 v16, v20, v21
	v_mad_i64_i32 v[20:21], s[0:1], v148, s59, v[112:113]
	v_cvt_pk_bf16_f32 v17, v22, v23
	v_cvt_pk_bf16_f32 v18, v24, v25
	v_cvt_pk_bf16_f32 v19, v26, v27
	v_lshl_add_u64 v[20:21], v[20:21], 0, v[114:115]
	v_mul_f32_e32 v22, 0xbfb8aa3b, v12
	global_store_dwordx4 v[20:21], v[16:19], off
	v_exp_f32_e32 v22, v22
	v_pk_mul_f32 v[4:5], v[4:5], v[154:155] op_sel_hi:[1,0]
	v_mul_f32_e32 v16, 0xbfb8aa3b, v13
	v_exp_f32_e32 v17, v16
	v_mul_f32_e32 v18, 0xbfb8aa3b, v14
	v_mul_f32_e32 v19, 0xbfb8aa3b, v15
	v_exp_f32_e32 v18, v18
	v_exp_f32_e32 v19, v19
	v_add_f32_e32 v16, 1.0, v22
	v_add_f32_e32 v17, 1.0, v17
	v_rcp_f32_e32 v16, v16
	v_rcp_f32_e32 v17, v17
	v_add_f32_e32 v18, 1.0, v18
	v_add_f32_e32 v19, 1.0, v19
	v_rcp_f32_e32 v18, v18
	v_rcp_f32_e32 v19, v19
	v_pk_mul_f32 v[12:13], v[12:13], v[16:17]
	v_pk_mul_f32 v[8:9], v[8:9], v[154:155] op_sel_hi:[1,0]
	v_pk_mul_f32 v[4:5], v[4:5], v[12:13]
	v_pk_mul_f32 v[12:13], v[14:15], v[18:19]
	v_mul_f32_e32 v14, 0xbfb8aa3b, v8
	v_exp_f32_e32 v14, v14
	v_pk_mul_f32 v[6:7], v[6:7], v[154:155] op_sel_hi:[1,0]
	v_pk_mul_f32 v[10:11], v[10:11], v[154:155] op_sel_hi:[1,0]
	v_pk_mul_f32 v[6:7], v[6:7], v[12:13]
	v_mul_f32_e32 v12, 0xbfb8aa3b, v9
	v_exp_f32_e32 v13, v12
	v_add_f32_e32 v12, 1.0, v14
	v_mul_f32_e32 v14, 0xbfb8aa3b, v10
	v_mul_f32_e32 v15, 0xbfb8aa3b, v11
	v_exp_f32_e32 v14, v14
	v_exp_f32_e32 v15, v15
	v_add_f32_e32 v13, 1.0, v13
	v_rcp_f32_e32 v12, v12
	v_rcp_f32_e32 v13, v13
	v_add_f32_e32 v14, 1.0, v14
	v_add_f32_e32 v15, 1.0, v15
	v_rcp_f32_e32 v14, v14
	v_rcp_f32_e32 v15, v15
	v_pk_mul_f32 v[0:1], v[0:1], v[154:155] op_sel_hi:[1,0]
	v_pk_mul_f32 v[8:9], v[8:9], v[12:13]
	s_and_b64 vcc, exec, s[2:3]
	v_pk_mul_f32 v[8:9], v[0:1], v[8:9]
	v_pk_mul_f32 v[0:1], v[2:3], v[154:155] op_sel_hi:[1,0]
	v_pk_mul_f32 v[2:3], v[10:11], v[14:15]
	s_mov_b32 s5, s12
	v_pk_mul_f32 v[10:11], v[0:1], v[2:3]
	v_cvt_pk_bf16_f32 v0, v4, v5
	v_mad_i64_i32 v[4:5], s[0:1], v146, s59, v[112:113]
	v_cvt_pk_bf16_f32 v1, v6, v7
	v_cvt_pk_bf16_f32 v2, v8, v9
	v_cvt_pk_bf16_f32 v3, v10, v11
	v_lshl_add_u64 v[4:5], v[4:5], 0, v[114:115]
	s_mov_b32 s4, s36
	s_mov_b64 s[42:43], s[40:41]
	s_mov_b64 s[44:45], s[38:39]
	global_store_dwordx4 v[4:5], v[0:3], off
	s_waitcnt vmcnt(8)
	v_xor_b32_e32 v184, 16, v177
	v_xor_b32_e32 v185, 32, v177
	v_lshlrev_b32_e32 v184, 2, v184
	v_lshlrev_b32_e32 v185, 2, v185
	v_mov_b32_e32 v190, s10
	v_pk_add_f32 v[216:217], v[216:217], v[218:219]
	v_pk_add_f32 v[220:221], v[220:221], v[222:223]
	v_pk_add_f32 v[224:225], v[224:225], v[226:227]
	v_pk_add_f32 v[196:197], v[196:197], v[198:199]
	v_pk_add_f32 v[200:201], v[200:201], v[202:203]
	v_pk_add_f32 v[204:205], v[204:205], v[206:207]
	v_pk_add_f32 v[208:209], v[208:209], v[210:211]
	v_pk_add_f32 v[212:213], v[212:213], v[214:215]
	v_add_f32_e32 v216, v216, v217
	v_add_f32_e32 v220, v220, v221
	v_add_f32_e32 v224, v224, v225
	v_add_f32_e32 v196, v196, v197
	v_add_f32_e32 v200, v200, v201
	v_add_f32_e32 v204, v204, v205
	v_add_f32_e32 v208, v208, v209
	v_add_f32_e32 v212, v212, v213
	ds_bpermute_b32 v218, v184, v216
	ds_bpermute_b32 v219, v184, v220
	ds_bpermute_b32 v222, v184, v224
	ds_bpermute_b32 v223, v184, v196
	ds_bpermute_b32 v226, v184, v200
	ds_bpermute_b32 v227, v184, v204
	ds_bpermute_b32 v198, v184, v208
	ds_bpermute_b32 v199, v184, v212
	s_waitcnt lgkmcnt(0)
	v_add_f32_e32 v216, v216, v218
	v_add_f32_e32 v220, v220, v219
	v_add_f32_e32 v224, v224, v222
	v_add_f32_e32 v196, v196, v223
	v_add_f32_e32 v200, v200, v226
	v_add_f32_e32 v204, v204, v227
	v_add_f32_e32 v208, v208, v198
	v_add_f32_e32 v212, v212, v199
	ds_bpermute_b32 v218, v185, v216
	ds_bpermute_b32 v219, v185, v220
	ds_bpermute_b32 v222, v185, v224
	ds_bpermute_b32 v223, v185, v196
	ds_bpermute_b32 v226, v185, v200
	ds_bpermute_b32 v227, v185, v204
	ds_bpermute_b32 v198, v185, v208
	ds_bpermute_b32 v199, v185, v212
	s_waitcnt lgkmcnt(0)
	v_add_f32_e32 v216, v216, v218
	v_add_f32_e32 v220, v220, v219
	v_add_f32_e32 v224, v224, v222
	v_add_f32_e32 v196, v196, v223
	v_add_f32_e32 v200, v200, v226
	v_add_f32_e32 v204, v204, v227
	v_add_f32_e32 v208, v208, v198
	v_add_f32_e32 v212, v212, v199
	v_fma_f32 v216, v216, s8, v190
	v_fma_f32 v220, v220, s8, v190
	v_fma_f32 v224, v224, s8, v190
	v_fma_f32 v196, v196, s8, v190
	v_fma_f32 v200, v200, s8, v190
	v_fma_f32 v204, v204, s8, v190
	v_fma_f32 v208, v208, s8, v190
	v_fma_f32 v212, v212, s8, v190
	v_rsq_f32_e32 v240, v216
	v_rsq_f32_e32 v176, v220
	v_rsq_f32_e32 v174, v224
	v_rsq_f32_e32 v170, v196
	v_rsq_f32_e32 v166, v200
	v_rsq_f32_e32 v162, v204
	v_rsq_f32_e32 v158, v208
	v_rsq_f32_e32 v241, v212
	s_and_b64 vcc, exec, s[2:3]
	s_mov_b32 s5, s12
	s_mov_b32 s4, s36
	s_cbranch_vccz .LBB0_1090
	s_waitcnt vmcnt(0)
	s_cmpk_gt_u32 s9, 0xff
	s_cbranch_scc1 .LBB0_1097
	s_barrier

.LBB0_1169:
	ds_read_b128 v[128:131], v167
	ds_read_b128 v[132:135], v167 offset:1024
	ds_read_b128 v[136:139], v167 offset:2048
	ds_read_b128 v[156:159], v167 offset:3072
	s_add_u32 s6, s40, 0x100
	s_addc_u32 s7, s41, 0
	s_cmp_eq_u32 s65, 40
	s_cselect_b32 s45, s1, s7
	s_cselect_b32 s44, s0, s6
	s_cselect_b32 s43, s39, s64
	s_cselect_b32 s42, s38, s63
	v_lshl_add_u64 v[202:203], s[40:41], 0, v[148:149]
	s_add_i32 m0, s47, 0xc000
	ds_read_b128 v[160:163], v168
	ds_read_b128 v[172:175], v168 offset:1024
	ds_read_b128 v[176:179], v168 offset:2048
	ds_read_b128 v[180:183], v168 offset:3072
	ds_read_b128 v[184:187], v168 offset:4096
	ds_read_b128 v[188:191], v168 offset:5120
	ds_read_b128 v[194:197], v168 offset:6144
	ds_read_b128 v[198:201], v168 offset:7168
	global_load_lds_dwordx4 v[202:203], off
	v_lshl_add_u64 v[202:203], s[40:41], 0, v[150:151]
	s_add_i32 m0, s47, 0xe000
	s_nop 0
	global_load_lds_dwordx4 v[202:203], off
	s_waitcnt lgkmcnt(8)
	s_barrier
	s_waitcnt lgkmcnt(0)
	v_mfma_f32_16x16x32_bf16 v[124:127], v[128:131], v[160:163], v[124:127]
	v_mfma_f32_16x16x32_bf16 v[120:123], v[136:139], v[160:163], v[120:123]
	v_mfma_f32_16x16x32_bf16 v[108:111], v[128:131], v[176:179], v[108:111]
	v_mfma_f32_16x16x32_bf16 v[104:107], v[136:139], v[176:179], v[104:107]
	v_mfma_f32_16x16x32_bf16 v[92:95], v[128:131], v[184:187], v[92:95]
	v_mfma_f32_16x16x32_bf16 v[88:91], v[136:139], v[184:187], v[88:91]
	v_mfma_f32_16x16x32_bf16 v[76:79], v[128:131], v[194:197], v[76:79]
	v_mfma_f32_16x16x32_bf16 v[72:75], v[136:139], v[194:197], v[72:75]
	v_mfma_f32_16x16x32_bf16 v[124:127], v[132:135], v[172:175], v[124:127]
	v_mfma_f32_16x16x32_bf16 v[120:123], v[156:159], v[172:175], v[120:123]
	v_mfma_f32_16x16x32_bf16 v[108:111], v[132:135], v[180:183], v[108:111]
	v_mfma_f32_16x16x32_bf16 v[104:107], v[156:159], v[180:183], v[104:107]
	v_mfma_f32_16x16x32_bf16 v[92:95], v[132:135], v[188:191], v[92:95]
	v_mfma_f32_16x16x32_bf16 v[88:91], v[156:159], v[188:191], v[88:91]
	v_mfma_f32_16x16x32_bf16 v[76:79], v[132:135], v[198:201], v[76:79]
	v_mfma_f32_16x16x32_bf16 v[72:75], v[156:159], v[198:201], v[72:75]
	s_barrier
	s_add_i32 s28, s57, s46
	v_lshl_add_u64 v[218:219], s[42:43], 0, v[142:143]
	s_mov_b32 m0, s28
	ds_read_b128 v[202:205], v169
	ds_read_b128 v[206:209], v169 offset:1024
	ds_read_b128 v[210:213], v169 offset:2048
	ds_read_b128 v[214:217], v169 offset:3072
	global_load_lds_dwordx4 v[218:219], off
	v_lshl_add_u64 v[220:221], s[42:43], 0, v[146:147]
	s_add_i32 m0, s28, 0x2000
	s_nop 0
	global_load_lds_dwordx4 v[220:221], off
	s_barrier
	s_waitcnt lgkmcnt(0)
	v_mfma_f32_16x16x32_bf16 v[116:119], v[202:205], v[160:163], v[116:119]
	v_mfma_f32_16x16x32_bf16 v[112:115], v[210:213], v[160:163], v[112:115]
	v_mfma_f32_16x16x32_bf16 v[100:103], v[202:205], v[176:179], v[100:103]
	v_mfma_f32_16x16x32_bf16 v[96:99], v[210:213], v[176:179], v[96:99]
	v_mfma_f32_16x16x32_bf16 v[84:87], v[202:205], v[184:187], v[84:87]
	v_mfma_f32_16x16x32_bf16 v[80:83], v[210:213], v[184:187], v[80:83]
	v_mfma_f32_16x16x32_bf16 v[68:71], v[202:205], v[194:197], v[68:71]
	v_mfma_f32_16x16x32_bf16 v[64:67], v[210:213], v[194:197], v[64:67]
	v_mfma_f32_16x16x32_bf16 v[116:119], v[206:209], v[172:175], v[116:119]
	v_mfma_f32_16x16x32_bf16 v[112:115], v[214:217], v[172:175], v[112:115]
	v_mfma_f32_16x16x32_bf16 v[100:103], v[206:209], v[180:183], v[100:103]
	v_mfma_f32_16x16x32_bf16 v[96:99], v[214:217], v[180:183], v[96:99]
	v_mfma_f32_16x16x32_bf16 v[84:87], v[206:209], v[188:191], v[84:87]
	v_mfma_f32_16x16x32_bf16 v[80:83], v[214:217], v[188:191], v[80:83]
	v_mfma_f32_16x16x32_bf16 v[68:71], v[206:209], v[198:201], v[68:71]
	v_mfma_f32_16x16x32_bf16 v[64:67], v[214:217], v[198:201], v[64:67]
	s_barrier
	s_mov_b32 m0, s47
	v_lshl_add_u64 v[222:223], s[44:45], 0, v[140:141]
	ds_read_b128 v[160:163], v168 offset:16384
	ds_read_b128 v[172:175], v168 offset:17408
	ds_read_b128 v[176:179], v168 offset:18432
	ds_read_b128 v[180:183], v168 offset:19456
	ds_read_b128 v[184:187], v168 offset:20480
	ds_read_b128 v[188:191], v168 offset:21504
	ds_read_b128 v[194:197], v168 offset:22528
	ds_read_b128 v[198:201], v168 offset:23552
	global_load_lds_dwordx4 v[222:223], off
	v_lshl_add_u64 v[224:225], s[44:45], 0, v[144:145]
	s_mov_b32 m0, s48
	s_nop 0
	global_load_lds_dwordx4 v[224:225], off
	s_barrier
	s_waitcnt lgkmcnt(0)
	v_mfma_f32_16x16x32_bf16 v[60:63], v[128:131], v[160:163], v[60:63]
	v_mfma_f32_16x16x32_bf16 v[56:59], v[136:139], v[160:163], v[56:59]
	v_mfma_f32_16x16x32_bf16 v[44:47], v[128:131], v[176:179], v[44:47]
	v_mfma_f32_16x16x32_bf16 v[40:43], v[136:139], v[176:179], v[40:43]
	v_mfma_f32_16x16x32_bf16 v[28:31], v[128:131], v[184:187], v[28:31]
	v_mfma_f32_16x16x32_bf16 v[24:27], v[136:139], v[184:187], v[24:27]
	v_mfma_f32_16x16x32_bf16 v[12:15], v[128:131], v[194:197], v[12:15]
	v_mfma_f32_16x16x32_bf16 v[8:11], v[136:139], v[194:197], v[8:11]
	v_mfma_f32_16x16x32_bf16 v[60:63], v[132:135], v[172:175], v[60:63]
	v_mfma_f32_16x16x32_bf16 v[56:59], v[156:159], v[172:175], v[56:59]
	v_mfma_f32_16x16x32_bf16 v[44:47], v[132:135], v[180:183], v[44:47]
	v_mfma_f32_16x16x32_bf16 v[40:43], v[156:159], v[180:183], v[40:43]
	v_mfma_f32_16x16x32_bf16 v[28:31], v[132:135], v[188:191], v[28:31]
	v_mfma_f32_16x16x32_bf16 v[24:27], v[156:159], v[188:191], v[24:27]
	v_mfma_f32_16x16x32_bf16 v[12:15], v[132:135], v[198:201], v[12:15]
	v_mfma_f32_16x16x32_bf16 v[8:11], v[156:159], v[198:201], v[8:11]
	s_barrier
	s_add_u32 s40, s42, 0x2c000
	s_addc_u32 s41, s43, 0
	s_add_i32 s28, s58, s46
	v_lshl_add_u64 v[128:129], s[40:41], 0, v[142:143]
	s_mov_b32 m0, s28
	s_nop 0
	global_load_lds_dwordx4 v[128:129], off
	v_lshl_add_u64 v[128:129], s[40:41], 0, v[146:147]
	s_add_i32 m0, s28, 0x2000
	s_nop 0
	global_load_lds_dwordx4 v[128:129], off
	s_waitcnt vmcnt(6)
	s_barrier
	v_mfma_f32_16x16x32_bf16 v[52:55], v[202:205], v[160:163], v[52:55]
	v_mfma_f32_16x16x32_bf16 v[48:51], v[210:213], v[160:163], v[48:51]
	v_mfma_f32_16x16x32_bf16 v[36:39], v[202:205], v[176:179], v[36:39]
	v_mfma_f32_16x16x32_bf16 v[32:35], v[210:213], v[176:179], v[32:35]
	v_mfma_f32_16x16x32_bf16 v[20:23], v[202:205], v[184:187], v[20:23]
	v_mfma_f32_16x16x32_bf16 v[16:19], v[210:213], v[184:187], v[16:19]
	v_mfma_f32_16x16x32_bf16 v[4:7], v[202:205], v[194:197], v[4:7]
	v_mfma_f32_16x16x32_bf16 v[0:3], v[210:213], v[194:197], v[0:3]
	v_mfma_f32_16x16x32_bf16 v[52:55], v[206:209], v[172:175], v[52:55]
	v_mfma_f32_16x16x32_bf16 v[48:51], v[214:217], v[172:175], v[48:51]
	v_mfma_f32_16x16x32_bf16 v[36:39], v[206:209], v[180:183], v[36:39]
	v_mfma_f32_16x16x32_bf16 v[32:35], v[214:217], v[180:183], v[32:35]
	v_mfma_f32_16x16x32_bf16 v[20:23], v[206:209], v[188:191], v[20:23]
	v_mfma_f32_16x16x32_bf16 v[16:19], v[214:217], v[188:191], v[16:19]
	v_mfma_f32_16x16x32_bf16 v[4:7], v[206:209], v[198:201], v[4:7]
	v_mfma_f32_16x16x32_bf16 v[0:3], v[214:217], v[198:201], v[0:3]
	s_barrier
	s_add_i32 s28, 0, 0x18000
	v_add_u32_e32 v156, s28, v165
	ds_read_b128 v[128:131], v156
	ds_read_b128 v[132:135], v156 offset:1024
	ds_read_b128 v[136:139], v156 offset:2048
	ds_read_b128 v[156:159], v156 offset:3072
	s_add_u32 s40, s44, 0xb0000
	s_addc_u32 s41, s45, 0
	s_mov_b32 m0, s49
	v_lshl_add_u64 v[202:203], s[40:41], 0, v[140:141]
	ds_read_b128 v[160:163], v168 offset:32768
	ds_read_b128 v[172:175], v168 offset:33792
	ds_read_b128 v[176:179], v168 offset:34816
	ds_read_b128 v[180:183], v168 offset:35840
	ds_read_b128 v[184:187], v168 offset:36864
	ds_read_b128 v[188:191], v168 offset:37888
	ds_read_b128 v[194:197], v168 offset:38912
	ds_read_b128 v[198:201], v168 offset:39936
	global_load_lds_dwordx4 v[202:203], off
	v_lshl_add_u64 v[202:203], s[40:41], 0, v[144:145]
	s_mov_b32 m0, s50
	s_nop 0
	global_load_lds_dwordx4 v[202:203], off
	s_waitcnt lgkmcnt(8)
	s_barrier
	s_waitcnt lgkmcnt(0)
	v_mfma_f32_16x16x32_bf16 v[124:127], v[128:131], v[160:163], v[124:127]
	v_mfma_f32_16x16x32_bf16 v[120:123], v[136:139], v[160:163], v[120:123]
	v_mfma_f32_16x16x32_bf16 v[108:111], v[128:131], v[176:179], v[108:111]
	v_mfma_f32_16x16x32_bf16 v[104:107], v[136:139], v[176:179], v[104:107]
	v_mfma_f32_16x16x32_bf16 v[92:95], v[128:131], v[184:187], v[92:95]
	v_mfma_f32_16x16x32_bf16 v[88:91], v[136:139], v[184:187], v[88:91]
	v_mfma_f32_16x16x32_bf16 v[76:79], v[128:131], v[194:197], v[76:79]
	v_mfma_f32_16x16x32_bf16 v[72:75], v[136:139], v[194:197], v[72:75]
	v_mfma_f32_16x16x32_bf16 v[124:127], v[132:135], v[172:175], v[124:127]
	v_mfma_f32_16x16x32_bf16 v[120:123], v[156:159], v[172:175], v[120:123]
	v_mfma_f32_16x16x32_bf16 v[108:111], v[132:135], v[180:183], v[108:111]
	v_mfma_f32_16x16x32_bf16 v[104:107], v[156:159], v[180:183], v[104:107]
	v_mfma_f32_16x16x32_bf16 v[92:95], v[132:135], v[188:191], v[92:95]
	v_mfma_f32_16x16x32_bf16 v[88:91], v[156:159], v[188:191], v[88:91]
	v_mfma_f32_16x16x32_bf16 v[76:79], v[132:135], v[198:201], v[76:79]
	v_mfma_f32_16x16x32_bf16 v[72:75], v[156:159], v[198:201], v[72:75]
	s_barrier
	s_add_i32 s29, 0, 0x1c000
	s_add_i32 s28, s28, s46
	v_add_u32_e32 v171, s29, v165
	v_lshl_add_u64 v[218:219], v[218:219], 0, s[36:37]
	s_mov_b32 m0, s28
	ds_read_b128 v[202:205], v171
	ds_read_b128 v[206:209], v171 offset:1024
	ds_read_b128 v[210:213], v171 offset:2048
	ds_read_b128 v[214:217], v171 offset:3072
	global_load_lds_dwordx4 v[218:219], off
	v_lshl_add_u64 v[218:219], v[220:221], 0, s[36:37]
	s_add_i32 m0, s28, 0x2000
	s_nop 0
	global_load_lds_dwordx4 v[218:219], off
	s_barrier
	s_waitcnt lgkmcnt(0)
	v_mfma_f32_16x16x32_bf16 v[116:119], v[202:205], v[160:163], v[116:119]
	v_mfma_f32_16x16x32_bf16 v[112:115], v[210:213], v[160:163], v[112:115]
	v_mfma_f32_16x16x32_bf16 v[100:103], v[202:205], v[176:179], v[100:103]
	v_mfma_f32_16x16x32_bf16 v[96:99], v[210:213], v[176:179], v[96:99]
	v_mfma_f32_16x16x32_bf16 v[84:87], v[202:205], v[184:187], v[84:87]
	v_mfma_f32_16x16x32_bf16 v[80:83], v[210:213], v[184:187], v[80:83]
	v_mfma_f32_16x16x32_bf16 v[68:71], v[202:205], v[194:197], v[68:71]
	v_mfma_f32_16x16x32_bf16 v[64:67], v[210:213], v[194:197], v[64:67]
	v_mfma_f32_16x16x32_bf16 v[116:119], v[206:209], v[172:175], v[116:119]
	v_mfma_f32_16x16x32_bf16 v[112:115], v[214:217], v[172:175], v[112:115]
	v_mfma_f32_16x16x32_bf16 v[100:103], v[206:209], v[180:183], v[100:103]
	v_mfma_f32_16x16x32_bf16 v[96:99], v[214:217], v[180:183], v[96:99]
	v_mfma_f32_16x16x32_bf16 v[84:87], v[206:209], v[188:191], v[84:87]
	v_mfma_f32_16x16x32_bf16 v[80:83], v[214:217], v[188:191], v[80:83]
	v_mfma_f32_16x16x32_bf16 v[68:71], v[206:209], v[198:201], v[68:71]
	v_mfma_f32_16x16x32_bf16 v[64:67], v[214:217], v[198:201], v[64:67]
	s_barrier
	s_mov_b32 m0, s54
	v_lshl_add_u64 v[218:219], v[222:223], 0, s[36:37]
	ds_read_b128 v[160:163], v168 offset:49152
	ds_read_b128 v[172:175], v168 offset:50176
	ds_read_b128 v[176:179], v168 offset:51200
	ds_read_b128 v[180:183], v168 offset:52224
	ds_read_b128 v[184:187], v168 offset:53248
	ds_read_b128 v[188:191], v168 offset:54272
	ds_read_b128 v[194:197], v168 offset:55296
	ds_read_b128 v[198:201], v168 offset:56320
	global_load_lds_dwordx4 v[218:219], off
	v_lshl_add_u64 v[218:219], v[224:225], 0, s[36:37]
	s_mov_b32 m0, s55
	s_nop 0
	global_load_lds_dwordx4 v[218:219], off
	s_barrier
	s_waitcnt lgkmcnt(0)
	v_mfma_f32_16x16x32_bf16 v[60:63], v[128:131], v[160:163], v[60:63]
	v_mfma_f32_16x16x32_bf16 v[56:59], v[136:139], v[160:163], v[56:59]
	v_mfma_f32_16x16x32_bf16 v[44:47], v[128:131], v[176:179], v[44:47]
	v_mfma_f32_16x16x32_bf16 v[40:43], v[136:139], v[176:179], v[40:43]
	v_mfma_f32_16x16x32_bf16 v[28:31], v[128:131], v[184:187], v[28:31]
	v_mfma_f32_16x16x32_bf16 v[24:27], v[136:139], v[184:187], v[24:27]
	v_mfma_f32_16x16x32_bf16 v[12:15], v[128:131], v[194:197], v[12:15]
	v_mfma_f32_16x16x32_bf16 v[8:11], v[136:139], v[194:197], v[8:11]
	v_mfma_f32_16x16x32_bf16 v[60:63], v[132:135], v[172:175], v[60:63]
	v_mfma_f32_16x16x32_bf16 v[56:59], v[156:159], v[172:175], v[56:59]
	v_mfma_f32_16x16x32_bf16 v[44:47], v[132:135], v[180:183], v[44:47]
	v_mfma_f32_16x16x32_bf16 v[40:43], v[156:159], v[180:183], v[40:43]
	v_mfma_f32_16x16x32_bf16 v[28:31], v[132:135], v[188:191], v[28:31]
	v_mfma_f32_16x16x32_bf16 v[24:27], v[156:159], v[188:191], v[24:27]
	v_mfma_f32_16x16x32_bf16 v[12:15], v[132:135], v[198:201], v[12:15]
	v_mfma_f32_16x16x32_bf16 v[8:11], v[156:159], v[198:201], v[8:11]
	s_barrier
	s_add_u32 s40, s42, 0x2c080
	s_addc_u32 s41, s43, 0
	s_add_i32 s28, s29, s46
	v_lshl_add_u64 v[128:129], s[40:41], 0, v[142:143]
	s_mov_b32 m0, s28
	s_nop 0
	global_load_lds_dwordx4 v[128:129], off
	v_lshl_add_u64 v[128:129], s[40:41], 0, v[146:147]
	s_add_i32 m0, s28, 0x2000
	s_nop 0
	global_load_lds_dwordx4 v[128:129], off
	s_add_i32 s65, s65, 2
	s_add_u32 s63, s63, 0x100
	s_addc_u32 s64, s64, 0
	s_cmp_gt_u32 s65, 41
	s_mov_b64 s[40:41], s[6:7]
	s_waitcnt vmcnt(6)
	s_barrier
	v_mfma_f32_16x16x32_bf16 v[52:55], v[202:205], v[160:163], v[52:55]
	v_mfma_f32_16x16x32_bf16 v[48:51], v[210:213], v[160:163], v[48:51]
	v_mfma_f32_16x16x32_bf16 v[36:39], v[202:205], v[176:179], v[36:39]
	v_mfma_f32_16x16x32_bf16 v[32:35], v[210:213], v[176:179], v[32:35]
	v_mfma_f32_16x16x32_bf16 v[20:23], v[202:205], v[184:187], v[20:23]
	v_mfma_f32_16x16x32_bf16 v[16:19], v[210:213], v[184:187], v[16:19]
	v_mfma_f32_16x16x32_bf16 v[4:7], v[202:205], v[194:197], v[4:7]
	v_mfma_f32_16x16x32_bf16 v[0:3], v[210:213], v[194:197], v[0:3]
	v_mfma_f32_16x16x32_bf16 v[52:55], v[206:209], v[172:175], v[52:55]
	v_mfma_f32_16x16x32_bf16 v[48:51], v[214:217], v[172:175], v[48:51]
	v_mfma_f32_16x16x32_bf16 v[36:39], v[206:209], v[180:183], v[36:39]
	v_mfma_f32_16x16x32_bf16 v[32:35], v[214:217], v[180:183], v[32:35]
	v_mfma_f32_16x16x32_bf16 v[20:23], v[206:209], v[188:191], v[20:23]
	v_mfma_f32_16x16x32_bf16 v[16:19], v[214:217], v[188:191], v[16:19]
	v_mfma_f32_16x16x32_bf16 v[4:7], v[206:209], v[198:201], v[4:7]
	v_mfma_f32_16x16x32_bf16 v[0:3], v[214:217], v[198:201], v[0:3]
	s_barrier
	s_cbranch_scc0 .LBB0_1169
	v_lshl_add_u32 v171, s62, 8, v164
	v_lshl_or_b32 v188, s10, 8, v166
	s_mov_b32 s63, 0xffff0000
	v_lshlrev_b32_e32 v128, 11, v171
	v_lshl_add_u32 v128, v188, 1, v128
	v_lshlrev_b32_e32 v129, 12, v171
	v_lshl_add_u32 v129, v188, 2, v129
	v_lshlrev_b32_e32 v132, 2, v188
	s_mov_b64 s[70:71], s[68:69]
	global_load_dwordx4 v[194:197], v128, s[70:71]
	global_load_dwordx4 v[198:201], v128, s[70:71] offset:64
	s_add_u32 s70, s70, 0x8000
	s_addc_u32 s71, s71, 0
	global_load_dwordx4 v[202:205], v128, s[70:71]
	global_load_dwordx4 v[206:209], v128, s[70:71] offset:64
	s_add_u32 s70, s70, 0x8000
	s_addc_u32 s71, s71, 0
	global_load_dwordx4 v[210:213], v128, s[70:71]
	global_load_dwordx4 v[214:217], v128, s[70:71] offset:64
	s_add_u32 s70, s70, 0x8000
	s_addc_u32 s71, s71, 0
	global_load_dwordx4 v[218:221], v128, s[70:71]
	global_load_dwordx4 v[222:225], v128, s[70:71] offset:64
	s_add_u32 s70, s70, 0x28000
	s_addc_u32 s71, s71, 0
	global_load_dwordx4 v[226:229], v128, s[70:71]
	global_load_dwordx4 v[230:233], v128, s[70:71] offset:64
	s_add_u32 s70, s70, 0x8000
	s_addc_u32 s71, s71, 0
	global_load_dwordx4 v[234:237], v128, s[70:71]
	global_load_dwordx4 v[238:241], v128, s[70:71] offset:64
	s_add_u32 s70, s70, 0x8000
	s_addc_u32 s71, s71, 0
	global_load_dwordx4 v[172:175], v128, s[70:71]
	global_load_dwordx4 v[176:179], v128, s[70:71] offset:64
	s_add_u32 s70, s70, 0x8000
	s_addc_u32 s71, s71, 0
	global_load_dwordx4 v[180:183], v128, s[70:71]
	global_load_dwordx4 v[184:187], v128, s[70:71] offset:64
	s_bfe_u32 s42, s17, 0x20006
	s_lshl_b32 s43, s10, 4
	s_lshl_b32 s42, s42, 2
	s_add_i32 s43, s43, s42
	v_lshl_add_u32 v130, v171, 6, s43
	v_and_b32_e32 v131, 48, v170
	v_lshl_add_u32 v131, v171, 6, v131
	v_xor_b32_e32 v134, 16, v170
	v_xor_b32_e32 v135, 32, v170
	v_lshlrev_b32_e32 v134, 2, v134
	v_lshlrev_b32_e32 v135, 2, v135
	v_cmp_gt_u32_e64 s[64:65], 16, v170
	s_add_u32 s74, s8, 0x2000
	s_addc_u32 s75, s9, 0
	s_lshl_b32 s42, s62, 7
	s_add_u32 s78, s26, 0x3c08000
	s_addc_u32 s79, s27, 0
	s_add_u32 s78, s78, s42
	s_addc_u32 s79, s79, 0
	s_waitcnt vmcnt(14)
	v_lshlrev_b32_e32 v136, 16, v194
	v_and_b32_e32 v137, s63, v194
	v_pk_add_f32 v[124:125], v[124:125], v[136:137]
	v_lshlrev_b32_e32 v138, 16, v195
	v_and_b32_e32 v139, s63, v195
	v_pk_add_f32 v[126:127], v[126:127], v[138:139]
	v_lshlrev_b32_e32 v190, 16, v196
	v_and_b32_e32 v191, s63, v196
	v_pk_add_f32 v[120:121], v[120:121], v[190:191]
	v_lshlrev_b32_e32 v136, 16, v197
	v_and_b32_e32 v137, s63, v197
	v_pk_add_f32 v[122:123], v[122:123], v[136:137]
	v_lshlrev_b32_e32 v138, 16, v198
	v_and_b32_e32 v139, s63, v198
	v_pk_add_f32 v[116:117], v[116:117], v[138:139]
	v_lshlrev_b32_e32 v190, 16, v199
	v_and_b32_e32 v191, s63, v199
	v_pk_add_f32 v[118:119], v[118:119], v[190:191]
	v_lshlrev_b32_e32 v136, 16, v200
	v_and_b32_e32 v137, s63, v200
	v_pk_add_f32 v[112:113], v[112:113], v[136:137]
	v_lshlrev_b32_e32 v138, 16, v201
	v_and_b32_e32 v139, s63, v201
	v_pk_add_f32 v[114:115], v[114:115], v[138:139]
	v_mul_f32_e32 v156, v120, v120
	v_mul_f32_e32 v189, v112, v112
	v_fmac_f32_e32 v156, v121, v121
	v_fmac_f32_e32 v189, v113, v113
	v_fmac_f32_e32 v156, v122, v122
	v_fmac_f32_e32 v189, v114, v114
	v_fmac_f32_e32 v156, v123, v123
	v_fmac_f32_e32 v189, v115, v115
	v_fmac_f32_e32 v156, v124, v124
	v_fmac_f32_e32 v189, v116, v116
	v_fmac_f32_e32 v156, v125, v125
	v_fmac_f32_e32 v189, v117, v117
	v_fmac_f32_e32 v156, v126, v126
	v_fmac_f32_e32 v189, v118, v118
	v_fmac_f32_e32 v156, v127, v127
	v_fmac_f32_e32 v189, v119, v119
	v_add_f32_e32 v156, v156, v189
	s_waitcnt vmcnt(12)
	v_lshlrev_b32_e32 v190, 16, v202
	v_and_b32_e32 v191, s63, v202
	v_pk_add_f32 v[108:109], v[108:109], v[190:191]
	v_lshlrev_b32_e32 v136, 16, v203
	v_and_b32_e32 v137, s63, v203
	v_pk_add_f32 v[110:111], v[110:111], v[136:137]
	v_lshlrev_b32_e32 v138, 16, v204
	v_and_b32_e32 v139, s63, v204
	v_pk_add_f32 v[104:105], v[104:105], v[138:139]
	v_lshlrev_b32_e32 v190, 16, v205
	v_and_b32_e32 v191, s63, v205
	v_pk_add_f32 v[106:107], v[106:107], v[190:191]
	v_lshlrev_b32_e32 v136, 16, v206
	v_and_b32_e32 v137, s63, v206
	v_pk_add_f32 v[100:101], v[100:101], v[136:137]
	v_lshlrev_b32_e32 v138, 16, v207
	v_and_b32_e32 v139, s63, v207
	v_pk_add_f32 v[102:103], v[102:103], v[138:139]
	v_lshlrev_b32_e32 v190, 16, v208
	v_and_b32_e32 v191, s63, v208
	v_pk_add_f32 v[96:97], v[96:97], v[190:191]
	v_lshlrev_b32_e32 v136, 16, v209
	v_and_b32_e32 v137, s63, v209
	v_pk_add_f32 v[98:99], v[98:99], v[136:137]
	v_mul_f32_e32 v157, v104, v104
	v_mul_f32_e32 v189, v96, v96
	v_fmac_f32_e32 v157, v105, v105
	v_fmac_f32_e32 v189, v97, v97
	v_fmac_f32_e32 v157, v106, v106
	v_fmac_f32_e32 v189, v98, v98
	v_fmac_f32_e32 v157, v107, v107
	v_fmac_f32_e32 v189, v99, v99
	v_fmac_f32_e32 v157, v108, v108
	v_fmac_f32_e32 v189, v100, v100
	v_fmac_f32_e32 v157, v109, v109
	v_fmac_f32_e32 v189, v101, v101
	v_fmac_f32_e32 v157, v110, v110
	v_fmac_f32_e32 v189, v102, v102
	v_fmac_f32_e32 v157, v111, v111
	v_fmac_f32_e32 v189, v103, v103
	v_add_f32_e32 v157, v157, v189
	s_waitcnt vmcnt(10)
	v_lshlrev_b32_e32 v138, 16, v210
	v_and_b32_e32 v139, s63, v210
	v_pk_add_f32 v[92:93], v[92:93], v[138:139]
	v_lshlrev_b32_e32 v190, 16, v211
	v_and_b32_e32 v191, s63, v211
	v_pk_add_f32 v[94:95], v[94:95], v[190:191]
	v_lshlrev_b32_e32 v136, 16, v212
	v_and_b32_e32 v137, s63, v212
	v_pk_add_f32 v[88:89], v[88:89], v[136:137]
	v_lshlrev_b32_e32 v138, 16, v213
	v_and_b32_e32 v139, s63, v213
	v_pk_add_f32 v[90:91], v[90:91], v[138:139]
	v_lshlrev_b32_e32 v190, 16, v214
	v_and_b32_e32 v191, s63, v214
	v_pk_add_f32 v[84:85], v[84:85], v[190:191]
	v_lshlrev_b32_e32 v136, 16, v215
	v_and_b32_e32 v137, s63, v215
	v_pk_add_f32 v[86:87], v[86:87], v[136:137]
	v_lshlrev_b32_e32 v138, 16, v216
	v_and_b32_e32 v139, s63, v216
	v_pk_add_f32 v[80:81], v[80:81], v[138:139]
	v_lshlrev_b32_e32 v190, 16, v217
	v_and_b32_e32 v191, s63, v217
	v_pk_add_f32 v[82:83], v[82:83], v[190:191]
	v_mul_f32_e32 v158, v88, v88
	v_mul_f32_e32 v189, v80, v80
	v_fmac_f32_e32 v158, v89, v89
	v_fmac_f32_e32 v189, v81, v81
	v_fmac_f32_e32 v158, v90, v90
	v_fmac_f32_e32 v189, v82, v82
	v_fmac_f32_e32 v158, v91, v91
	v_fmac_f32_e32 v189, v83, v83
	v_fmac_f32_e32 v158, v92, v92
	v_fmac_f32_e32 v189, v84, v84
	v_fmac_f32_e32 v158, v93, v93
	v_fmac_f32_e32 v189, v85, v85
	v_fmac_f32_e32 v158, v94, v94
	v_fmac_f32_e32 v189, v86, v86
	v_fmac_f32_e32 v158, v95, v95
	v_fmac_f32_e32 v189, v87, v87
	v_add_f32_e32 v158, v158, v189
	s_waitcnt vmcnt(8)
	v_lshlrev_b32_e32 v136, 16, v218
	v_and_b32_e32 v137, s63, v218
	v_pk_add_f32 v[76:77], v[76:77], v[136:137]
	v_lshlrev_b32_e32 v138, 16, v219
	v_and_b32_e32 v139, s63, v219
	v_pk_add_f32 v[78:79], v[78:79], v[138:139]
	v_lshlrev_b32_e32 v190, 16, v220
	v_and_b32_e32 v191, s63, v220
	v_pk_add_f32 v[72:73], v[72:73], v[190:191]
	v_lshlrev_b32_e32 v136, 16, v221
	v_and_b32_e32 v137, s63, v221
	v_pk_add_f32 v[74:75], v[74:75], v[136:137]
	v_lshlrev_b32_e32 v138, 16, v222
	v_and_b32_e32 v139, s63, v222
	v_pk_add_f32 v[68:69], v[68:69], v[138:139]
	v_lshlrev_b32_e32 v190, 16, v223
	v_and_b32_e32 v191, s63, v223
	v_pk_add_f32 v[70:71], v[70:71], v[190:191]
	v_lshlrev_b32_e32 v136, 16, v224
	v_and_b32_e32 v137, s63, v224
	v_pk_add_f32 v[64:65], v[64:65], v[136:137]
	v_lshlrev_b32_e32 v138, 16, v225
	v_and_b32_e32 v139, s63, v225
	v_pk_add_f32 v[66:67], v[66:67], v[138:139]
	v_mul_f32_e32 v159, v72, v72
	v_mul_f32_e32 v189, v64, v64
	v_fmac_f32_e32 v159, v73, v73
	v_fmac_f32_e32 v189, v65, v65
	v_fmac_f32_e32 v159, v74, v74
	v_fmac_f32_e32 v189, v66, v66
	v_fmac_f32_e32 v159, v75, v75
	v_fmac_f32_e32 v189, v67, v67
	v_fmac_f32_e32 v159, v76, v76
	v_fmac_f32_e32 v189, v68, v68
	v_fmac_f32_e32 v159, v77, v77
	v_fmac_f32_e32 v189, v69, v69
	v_fmac_f32_e32 v159, v78, v78
	v_fmac_f32_e32 v189, v70, v70
	v_fmac_f32_e32 v159, v79, v79
	v_fmac_f32_e32 v189, v71, v71
	v_add_f32_e32 v159, v159, v189
	s_waitcnt vmcnt(6)
	v_lshlrev_b32_e32 v190, 16, v226
	v_and_b32_e32 v191, s63, v226
	v_pk_add_f32 v[60:61], v[60:61], v[190:191]
	v_lshlrev_b32_e32 v136, 16, v227
	v_and_b32_e32 v137, s63, v227
	v_pk_add_f32 v[62:63], v[62:63], v[136:137]
	v_lshlrev_b32_e32 v138, 16, v228
	v_and_b32_e32 v139, s63, v228
	v_pk_add_f32 v[56:57], v[56:57], v[138:139]
	v_lshlrev_b32_e32 v190, 16, v229
	v_and_b32_e32 v191, s63, v229
	v_pk_add_f32 v[58:59], v[58:59], v[190:191]
	v_lshlrev_b32_e32 v136, 16, v230
	v_and_b32_e32 v137, s63, v230
	v_pk_add_f32 v[52:53], v[52:53], v[136:137]
	v_lshlrev_b32_e32 v138, 16, v231
	v_and_b32_e32 v139, s63, v231
	v_pk_add_f32 v[54:55], v[54:55], v[138:139]
	v_lshlrev_b32_e32 v190, 16, v232
	v_and_b32_e32 v191, s63, v232
	v_pk_add_f32 v[48:49], v[48:49], v[190:191]
	v_lshlrev_b32_e32 v136, 16, v233
	v_and_b32_e32 v137, s63, v233
	v_pk_add_f32 v[50:51], v[50:51], v[136:137]
	v_mul_f32_e32 v160, v56, v56
	v_mul_f32_e32 v189, v48, v48
	v_fmac_f32_e32 v160, v57, v57
	v_fmac_f32_e32 v189, v49, v49
	v_fmac_f32_e32 v160, v58, v58
	v_fmac_f32_e32 v189, v50, v50
	v_fmac_f32_e32 v160, v59, v59
	v_fmac_f32_e32 v189, v51, v51
	v_fmac_f32_e32 v160, v60, v60
	v_fmac_f32_e32 v189, v52, v52
	v_fmac_f32_e32 v160, v61, v61
	v_fmac_f32_e32 v189, v53, v53
	v_fmac_f32_e32 v160, v62, v62
	v_fmac_f32_e32 v189, v54, v54
	v_fmac_f32_e32 v160, v63, v63
	v_fmac_f32_e32 v189, v55, v55
	v_add_f32_e32 v160, v160, v189
	s_waitcnt vmcnt(4)
	v_lshlrev_b32_e32 v138, 16, v234
	v_and_b32_e32 v139, s63, v234
	v_pk_add_f32 v[44:45], v[44:45], v[138:139]
	v_lshlrev_b32_e32 v190, 16, v235
	v_and_b32_e32 v191, s63, v235
	v_pk_add_f32 v[46:47], v[46:47], v[190:191]
	v_lshlrev_b32_e32 v136, 16, v236
	v_and_b32_e32 v137, s63, v236
	v_pk_add_f32 v[40:41], v[40:41], v[136:137]
	v_lshlrev_b32_e32 v138, 16, v237
	v_and_b32_e32 v139, s63, v237
	v_pk_add_f32 v[42:43], v[42:43], v[138:139]
	v_lshlrev_b32_e32 v190, 16, v238
	v_and_b32_e32 v191, s63, v238
	v_pk_add_f32 v[36:37], v[36:37], v[190:191]
	v_lshlrev_b32_e32 v136, 16, v239
	v_and_b32_e32 v137, s63, v239
	v_pk_add_f32 v[38:39], v[38:39], v[136:137]
	v_lshlrev_b32_e32 v138, 16, v240
	v_and_b32_e32 v139, s63, v240
	v_pk_add_f32 v[32:33], v[32:33], v[138:139]
	v_lshlrev_b32_e32 v190, 16, v241
	v_and_b32_e32 v191, s63, v241
	v_pk_add_f32 v[34:35], v[34:35], v[190:191]
	v_mul_f32_e32 v161, v40, v40
	v_mul_f32_e32 v189, v32, v32
	v_fmac_f32_e32 v161, v41, v41
	v_fmac_f32_e32 v189, v33, v33
	v_fmac_f32_e32 v161, v42, v42
	v_fmac_f32_e32 v189, v34, v34
	v_fmac_f32_e32 v161, v43, v43
	v_fmac_f32_e32 v189, v35, v35
	v_fmac_f32_e32 v161, v44, v44
	v_fmac_f32_e32 v189, v36, v36
	v_fmac_f32_e32 v161, v45, v45
	v_fmac_f32_e32 v189, v37, v37
	v_fmac_f32_e32 v161, v46, v46
	v_fmac_f32_e32 v189, v38, v38
	v_fmac_f32_e32 v161, v47, v47
	v_fmac_f32_e32 v189, v39, v39
	v_add_f32_e32 v161, v161, v189
	s_waitcnt vmcnt(2)
	v_lshlrev_b32_e32 v136, 16, v172
	v_and_b32_e32 v137, s63, v172
	v_pk_add_f32 v[28:29], v[28:29], v[136:137]
	v_lshlrev_b32_e32 v138, 16, v173
	v_and_b32_e32 v139, s63, v173
	v_pk_add_f32 v[30:31], v[30:31], v[138:139]
	v_lshlrev_b32_e32 v190, 16, v174
	v_and_b32_e32 v191, s63, v174
	v_pk_add_f32 v[24:25], v[24:25], v[190:191]
	v_lshlrev_b32_e32 v136, 16, v175
	v_and_b32_e32 v137, s63, v175
	v_pk_add_f32 v[26:27], v[26:27], v[136:137]
	v_lshlrev_b32_e32 v138, 16, v176
	v_and_b32_e32 v139, s63, v176
	v_pk_add_f32 v[20:21], v[20:21], v[138:139]
	v_lshlrev_b32_e32 v190, 16, v177
	v_and_b32_e32 v191, s63, v177
	v_pk_add_f32 v[22:23], v[22:23], v[190:191]
	v_lshlrev_b32_e32 v136, 16, v178
	v_and_b32_e32 v137, s63, v178
	v_pk_add_f32 v[16:17], v[16:17], v[136:137]
	v_lshlrev_b32_e32 v138, 16, v179
	v_and_b32_e32 v139, s63, v179
	v_pk_add_f32 v[18:19], v[18:19], v[138:139]
	v_mul_f32_e32 v162, v24, v24
	v_mul_f32_e32 v189, v16, v16
	v_fmac_f32_e32 v162, v25, v25
	v_fmac_f32_e32 v189, v17, v17
	v_fmac_f32_e32 v162, v26, v26
	v_fmac_f32_e32 v189, v18, v18
	v_fmac_f32_e32 v162, v27, v27
	v_fmac_f32_e32 v189, v19, v19
	v_fmac_f32_e32 v162, v28, v28
	v_fmac_f32_e32 v189, v20, v20
	v_fmac_f32_e32 v162, v29, v29
	v_fmac_f32_e32 v189, v21, v21
	v_fmac_f32_e32 v162, v30, v30
	v_fmac_f32_e32 v189, v22, v22
	v_fmac_f32_e32 v162, v31, v31
	v_fmac_f32_e32 v189, v23, v23
	v_add_f32_e32 v162, v162, v189
	s_waitcnt vmcnt(0)
	v_lshlrev_b32_e32 v190, 16, v180
	v_and_b32_e32 v191, s63, v180
	v_pk_add_f32 v[12:13], v[12:13], v[190:191]
	v_lshlrev_b32_e32 v136, 16, v181
	v_and_b32_e32 v137, s63, v181
	v_pk_add_f32 v[14:15], v[14:15], v[136:137]
	v_lshlrev_b32_e32 v138, 16, v182
	v_and_b32_e32 v139, s63, v182
	v_pk_add_f32 v[8:9], v[8:9], v[138:139]
	v_lshlrev_b32_e32 v190, 16, v183
	v_and_b32_e32 v191, s63, v183
	v_pk_add_f32 v[10:11], v[10:11], v[190:191]
	v_lshlrev_b32_e32 v136, 16, v184
	v_and_b32_e32 v137, s63, v184
	v_pk_add_f32 v[4:5], v[4:5], v[136:137]
	v_lshlrev_b32_e32 v138, 16, v185
	v_and_b32_e32 v139, s63, v185
	v_pk_add_f32 v[6:7], v[6:7], v[138:139]
	v_lshlrev_b32_e32 v190, 16, v186
	v_and_b32_e32 v191, s63, v186
	v_pk_add_f32 v[0:1], v[0:1], v[190:191]
	v_lshlrev_b32_e32 v136, 16, v187
	v_and_b32_e32 v137, s63, v187
	v_pk_add_f32 v[2:3], v[2:3], v[136:137]
	v_mul_f32_e32 v163, v8, v8
	v_mul_f32_e32 v189, v0, v0
	v_fmac_f32_e32 v163, v9, v9
	v_fmac_f32_e32 v189, v1, v1
	v_fmac_f32_e32 v163, v10, v10
	v_fmac_f32_e32 v189, v2, v2
	v_fmac_f32_e32 v163, v11, v11
	v_fmac_f32_e32 v189, v3, v3
	v_fmac_f32_e32 v163, v12, v12
	v_fmac_f32_e32 v189, v4, v4
	v_fmac_f32_e32 v163, v13, v13
	v_fmac_f32_e32 v189, v5, v5
	v_fmac_f32_e32 v163, v14, v14
	v_fmac_f32_e32 v189, v6, v6
	v_fmac_f32_e32 v163, v15, v15
	v_fmac_f32_e32 v189, v7, v7
	v_add_f32_e32 v163, v163, v189
	ds_bpermute_b32 v136, v134, v156
	ds_bpermute_b32 v137, v134, v157
	ds_bpermute_b32 v138, v134, v158
	ds_bpermute_b32 v139, v134, v159
	ds_bpermute_b32 v188, v134, v160
	ds_bpermute_b32 v189, v134, v161
	ds_bpermute_b32 v190, v134, v162
	ds_bpermute_b32 v191, v134, v163
	s_waitcnt lgkmcnt(0)
	v_add_f32_e32 v156, v156, v136
	v_add_f32_e32 v157, v157, v137
	v_add_f32_e32 v158, v158, v138
	v_add_f32_e32 v159, v159, v139
	v_add_f32_e32 v160, v160, v188
	v_add_f32_e32 v161, v161, v189
	v_add_f32_e32 v162, v162, v190
	v_add_f32_e32 v163, v163, v191
	ds_bpermute_b32 v136, v135, v156
	ds_bpermute_b32 v137, v135, v157
	ds_bpermute_b32 v138, v135, v158
	ds_bpermute_b32 v139, v135, v159
	ds_bpermute_b32 v188, v135, v160
	ds_bpermute_b32 v189, v135, v161
	ds_bpermute_b32 v190, v135, v162
	ds_bpermute_b32 v191, v135, v163
	s_waitcnt lgkmcnt(0)
	v_add_f32_e32 v156, v156, v136
	v_add_f32_e32 v157, v157, v137
	v_add_f32_e32 v158, v158, v138
	v_add_f32_e32 v159, v159, v139
	v_add_f32_e32 v160, v160, v188
	v_add_f32_e32 v161, v161, v189
	v_add_f32_e32 v162, v162, v190
	v_add_f32_e32 v163, v163, v191
	s_and_saveexec_b64 s[66:67], s[64:65]
	global_store_dword v130, v156, s[8:9] sc1
	global_store_dword v130, v157, s[8:9] offset:1024 sc1
	global_store_dword v130, v158, s[8:9] offset:2048 sc1
	global_store_dword v130, v159, s[8:9] offset:3072 sc1
	global_store_dword v130, v160, s[74:75] sc1
	global_store_dword v130, v161, s[74:75] offset:1024 sc1
	global_store_dword v130, v162, s[74:75] offset:2048 sc1
	global_store_dword v130, v163, s[74:75] offset:3072 sc1
	s_or_b64 exec, exec, s[66:67]
	global_load_dwordx4 v[210:213], v132, s[22:23]
	global_load_dwordx4 v[214:217], v132, s[22:23] offset:16
	global_load_dwordx4 v[218:221], v132, s[22:23] offset:128
	global_load_dwordx4 v[222:225], v132, s[22:23] offset:144
	s_waitcnt vmcnt(0)
	s_barrier
	s_barrier
	s_cmpk_gt_u32 s17, 0xff
	s_cbranch_scc1 .Lf11_w1_a
	s_and_saveexec_b64 s[40:41], s[14:15]
	s_cbranch_execz .Lf11_t0_done
	v_mov_b32_e32 v133, 0
	v_mov_b32_e32 v189, 1
	global_atomic_add v133, v189, s[78:79]
	s_mov_b32 s80, 0
